# adds: trans-use hazard fix in G2 ring, MGB ring loads without nt, bf16 K-loops LDS-DMA issue spread with in-place address post-increment, G4 row-scale load no longer waited before the x/pp loads
# speedup vs baseline: 1.0261x; 1.0101x over previous
; #define WAIT_V0() asm volatile("s_waitcnt vmcnt(0)" ::: "memory")
; DI void gemm_core(const int tid, const u16* __restrict__ Wb, int ldw, const u16* __restrict__ Xb, int ldx, int K, f32x4 (&acc)[8][4], const bool pre = false) {
;     ...
;   auto stage = [&](int buf, int kt) {
; #pragma unroll
;     for (int i = 0; i < 4; ++i) {
;       __builtin_amdgcn_global_load_lds((const unsigned*)(Wb + offw[i] + kt * 64), (unsigned*)(shm + buf * STAGE_B + wid * 1024 + i * 8192), 16, 0, 0);
;       __builtin_amdgcn_global_load_lds((const unsigned*)(Xb + offx[i] + kt * 64), (unsigned*)(shm + buf * STAGE_B + TILE_B + wid * 1024 + i * 8192), 16, 0, 0);
;     }
;   };
;   const int nt = K >> 6;
;   if (!pre) stage(0, 0);
;   WAIT_V0(); __syncthreads();
;   for (int t = 0; t < nt; ++t) {
;     const int cur = t & 1;
;     if (t + 1 < nt) stage(cur ^ 1, t + 1);
; #pragma unroll
;     for (int ks = 0; ks < 2; ++ks) {
;       bf16x8 At[8], Bf[4];
;       const char* pb = shm + cur * STAGE_B + TILE_B + lds_byte(wc * 64 + fr, fq * 8) + ks * 1024;
;       const char* pa = shm + cur * STAGE_B + lds_byte(wr * 128 + fr, fq * 8) + ks * 1024;
; #pragma unroll
;       for (int n = 0; n < 4; ++n) Bf[n] = *(const bf16x8*)(pb + n * 2048);
; #pragma unroll
;       for (int m = 0; m < 8; ++m) At[m] = *(const bf16x8*)(pa + m * 2048);
; #pragma unroll
;       for (int m = 0; m < 8; ++m)
; #pragma unroll
;         for (int n = 0; n < 4; ++n)
;           acc[m][n] = __builtin_amdgcn_mfma_f32_16x16x32_bf16(At[m], Bf[n], acc[m][n], 0, 0, 0);
;       __builtin_amdgcn_sched_group_barrier(0x100, 5, 0);
; #pragma unroll
;       for (int m = 0; m < 8; ++m) {
;         __builtin_amdgcn_sched_group_barrier(0x008, 1, 0);
;         if (m < 7) __builtin_amdgcn_sched_group_barrier(0x100, 1, 0);
;         __builtin_amdgcn_sched_group_barrier(0x008, 3, 0);
;       }
;       __builtin_amdgcn_sched_barrier(0);
;     }
;     WAIT_V0(); __syncthreads();
.LBB0_43:
	s_and_b32 s23, s22, 0x10000
	s_xor_b32 s24, s23, 0x10000
	s_add_i32 s24, s7, s24
	s_add_i32 vcc_lo, s21, s23
	s_nop 1
	v_add_u32_e32 v149, vcc_lo, v148
	ds_read_b128 v[150:153], v149
	s_or_b32 s23, s15, s23
	v_add_u32_e32 v174, s23, v148
	ds_read_b128 v[154:157], v174 offset:32768
	ds_read_b128 v[158:161], v174 offset:34816
	ds_read_b128 v[162:165], v174 offset:36864
	ds_read_b128 v[166:169], v174 offset:38912
	s_mov_b32 m0, s24
	s_nop 0
	global_load_lds_dwordx4 v[144:145], off
	v_lshl_add_u64 v[144:145], v[144:145], 0, s[64:65]
	s_waitcnt lgkmcnt(0)
	v_mfma_f32_16x16x32_bf16 v[126:129], v[150:153], v[154:157], v[126:129]
	ds_read_b128 v[170:173], v149 offset:2048
	v_mfma_f32_16x16x32_bf16 v[122:125], v[150:153], v[158:161], v[122:125]
	v_mfma_f32_16x16x32_bf16 v[118:121], v[150:153], v[162:165], v[118:121]
	v_mfma_f32_16x16x32_bf16 v[114:117], v[150:153], v[166:169], v[114:117]
	s_waitcnt lgkmcnt(0)
	v_mfma_f32_16x16x32_bf16 v[110:113], v[170:173], v[154:157], v[110:113]
	ds_read_b128 v[150:153], v149 offset:4096
	s_add_i32 m0, s24, 0x8000
	s_nop 0
	global_load_lds_dwordx4 v[142:143], off
	v_lshl_add_u64 v[142:143], v[142:143], 0, s[64:65]
	v_mfma_f32_16x16x32_bf16 v[106:109], v[170:173], v[158:161], v[106:109]
	v_mfma_f32_16x16x32_bf16 v[102:105], v[170:173], v[162:165], v[102:105]
	v_mfma_f32_16x16x32_bf16 v[98:101], v[170:173], v[166:169], v[98:101]
	s_waitcnt lgkmcnt(0)
	v_mfma_f32_16x16x32_bf16 v[94:97], v[150:153], v[154:157], v[94:97]
	ds_read_b128 v[170:173], v149 offset:6144
	s_add_i32 m0, s24, 0x2000
	s_nop 0
	global_load_lds_dwordx4 v[140:141], off
	v_lshl_add_u64 v[140:141], v[140:141], 0, s[64:65]
	v_mfma_f32_16x16x32_bf16 v[90:93], v[150:153], v[158:161], v[90:93]
	v_mfma_f32_16x16x32_bf16 v[86:89], v[150:153], v[162:165], v[86:89]
	v_mfma_f32_16x16x32_bf16 v[82:85], v[150:153], v[166:169], v[82:85]
	s_waitcnt lgkmcnt(0)
	v_mfma_f32_16x16x32_bf16 v[70:73], v[170:173], v[154:157], v[70:73]
	ds_read_b128 v[150:153], v149 offset:8192
	s_add_i32 m0, s24, 0xa000
	s_nop 0
	global_load_lds_dwordx4 v[138:139], off
	v_lshl_add_u64 v[138:139], v[138:139], 0, s[64:65]
	v_mfma_f32_16x16x32_bf16 v[66:69], v[170:173], v[158:161], v[66:69]
	v_mfma_f32_16x16x32_bf16 v[62:65], v[170:173], v[162:165], v[62:65]
	v_mfma_f32_16x16x32_bf16 v[58:61], v[170:173], v[166:169], v[58:61]
	s_waitcnt lgkmcnt(0)
	v_mfma_f32_16x16x32_bf16 v[42:45], v[150:153], v[154:157], v[42:45]
	ds_read_b128 v[170:173], v149 offset:10240
	s_add_i32 m0, s24, 0x4000
	s_nop 0
	global_load_lds_dwordx4 v[136:137], off
	v_lshl_add_u64 v[136:137], v[136:137], 0, s[64:65]
	v_mfma_f32_16x16x32_bf16 v[6:9], v[150:153], v[158:161], v[6:9]
	v_mfma_f32_16x16x32_bf16 v[2:5], v[150:153], v[162:165], v[2:5]
	v_mfma_f32_16x16x32_bf16 v[54:57], v[150:153], v[166:169], v[54:57]
	s_waitcnt lgkmcnt(0)
	v_mfma_f32_16x16x32_bf16 v[50:53], v[170:173], v[154:157], v[50:53]
	ds_read_b128 v[150:153], v149 offset:12288
	s_add_i32 m0, s24, 0xc000
	s_nop 0
	global_load_lds_dwordx4 v[134:135], off
	v_lshl_add_u64 v[134:135], v[134:135], 0, s[64:65]
	v_mfma_f32_16x16x32_bf16 v[38:41], v[170:173], v[158:161], v[38:41]
	v_mfma_f32_16x16x32_bf16 v[46:49], v[170:173], v[162:165], v[46:49]
	v_mfma_f32_16x16x32_bf16 v[34:37], v[170:173], v[166:169], v[34:37]
	s_waitcnt lgkmcnt(0)
	v_mfma_f32_16x16x32_bf16 v[26:29], v[150:153], v[154:157], v[26:29]
	ds_read_b128 v[170:173], v149 offset:14336
	s_add_i32 m0, s24, 0x6000
	s_nop 0
	global_load_lds_dwordx4 v[132:133], off
	v_lshl_add_u64 v[132:133], v[132:133], 0, s[64:65]
	v_mfma_f32_16x16x32_bf16 v[30:33], v[150:153], v[158:161], v[30:33]
	v_mfma_f32_16x16x32_bf16 v[78:81], v[150:153], v[162:165], v[78:81]
	v_mfma_f32_16x16x32_bf16 v[22:25], v[150:153], v[166:169], v[22:25]
	s_waitcnt lgkmcnt(0)
	v_mfma_f32_16x16x32_bf16 v[14:17], v[170:173], v[154:157], v[14:17]
	s_add_i32 m0, s24, 0xe000
	s_nop 0
	global_load_lds_dwordx4 v[130:131], off
	v_lshl_add_u64 v[130:131], v[130:131], 0, s[64:65]
	v_mfma_f32_16x16x32_bf16 v[18:21], v[170:173], v[158:161], v[18:21]
	v_mfma_f32_16x16x32_bf16 v[74:77], v[170:173], v[162:165], v[74:77]
	v_mfma_f32_16x16x32_bf16 v[10:13], v[170:173], v[166:169], v[10:13]
	ds_read_b128 v[150:153], v149 offset:1024
	ds_read_b128 v[154:157], v174 offset:33792
	ds_read_b128 v[158:161], v174 offset:35840
	ds_read_b128 v[162:165], v174 offset:37888
	ds_read_b128 v[166:169], v174 offset:39936
	s_waitcnt lgkmcnt(0)
	v_mfma_f32_16x16x32_bf16 v[126:129], v[150:153], v[154:157], v[126:129]
	ds_read_b128 v[170:173], v149 offset:3072
	v_mfma_f32_16x16x32_bf16 v[122:125], v[150:153], v[158:161], v[122:125]
	v_mfma_f32_16x16x32_bf16 v[118:121], v[150:153], v[162:165], v[118:121]
	v_mfma_f32_16x16x32_bf16 v[114:117], v[150:153], v[166:169], v[114:117]
	s_waitcnt lgkmcnt(0)
	v_mfma_f32_16x16x32_bf16 v[110:113], v[170:173], v[154:157], v[110:113]
	ds_read_b128 v[150:153], v149 offset:5120
	v_mfma_f32_16x16x32_bf16 v[106:109], v[170:173], v[158:161], v[106:109]
	v_mfma_f32_16x16x32_bf16 v[102:105], v[170:173], v[162:165], v[102:105]
	v_mfma_f32_16x16x32_bf16 v[98:101], v[170:173], v[166:169], v[98:101]
	s_waitcnt lgkmcnt(0)
	v_mfma_f32_16x16x32_bf16 v[94:97], v[150:153], v[154:157], v[94:97]
	ds_read_b128 v[170:173], v149 offset:7168
	v_mfma_f32_16x16x32_bf16 v[90:93], v[150:153], v[158:161], v[90:93]
	v_mfma_f32_16x16x32_bf16 v[86:89], v[150:153], v[162:165], v[86:89]
	v_mfma_f32_16x16x32_bf16 v[82:85], v[150:153], v[166:169], v[82:85]
	s_waitcnt lgkmcnt(0)
	v_mfma_f32_16x16x32_bf16 v[70:73], v[170:173], v[154:157], v[70:73]
	ds_read_b128 v[150:153], v149 offset:9216
	v_mfma_f32_16x16x32_bf16 v[66:69], v[170:173], v[158:161], v[66:69]
	v_mfma_f32_16x16x32_bf16 v[62:65], v[170:173], v[162:165], v[62:65]
	v_mfma_f32_16x16x32_bf16 v[58:61], v[170:173], v[166:169], v[58:61]
	s_waitcnt lgkmcnt(0)
; #define WAIT_V0() asm volatile("s_waitcnt vmcnt(0)" ::: "memory")
; DI void gemm_core(const int tid, const u16* __restrict__ Wb, int ldw, const u16* __restrict__ Xb, int ldx, int K, f32x4 (&acc)[8][4], const bool pre = false) {
;     ...
;     for (int ks = 0; ks < 2; ++ks) {
;       bf16x8 At[8], Bf[4];
;       const char* pb = shm + cur * STAGE_B + TILE_B + lds_byte(wc * 64 + fr, fq * 8) + ks * 1024;
;       const char* pa = shm + cur * STAGE_B + lds_byte(wr * 128 + fr, fq * 8) + ks * 1024;
; #pragma unroll
;       for (int n = 0; n < 4; ++n) Bf[n] = *(const bf16x8*)(pb + n * 2048);
; #pragma unroll
;       for (int m = 0; m < 8; ++m) At[m] = *(const bf16x8*)(pa + m * 2048);
; #pragma unroll
;       for (int m = 0; m < 8; ++m)
; #pragma unroll
;         for (int n = 0; n < 4; ++n)
;           acc[m][n] = __builtin_amdgcn_mfma_f32_16x16x32_bf16(At[m], Bf[n], acc[m][n], 0, 0, 0);
;       __builtin_amdgcn_sched_group_barrier(0x100, 5, 0);
; #pragma unroll
;       for (int m = 0; m < 8; ++m) {
;         __builtin_amdgcn_sched_group_barrier(0x008, 1, 0);
;         if (m < 7) __builtin_amdgcn_sched_group_barrier(0x100, 1, 0);
;         __builtin_amdgcn_sched_group_barrier(0x008, 3, 0);
;       }
;       __builtin_amdgcn_sched_barrier(0);
;     }
;     WAIT_V0(); __syncthreads();
;   }
	v_mfma_f32_16x16x32_bf16 v[42:45], v[150:153], v[154:157], v[42:45]
	ds_read_b128 v[170:173], v149 offset:11264
	v_mfma_f32_16x16x32_bf16 v[6:9], v[150:153], v[158:161], v[6:9]
	v_mfma_f32_16x16x32_bf16 v[2:5], v[150:153], v[162:165], v[2:5]
	v_mfma_f32_16x16x32_bf16 v[54:57], v[150:153], v[166:169], v[54:57]
	s_waitcnt lgkmcnt(0)
	v_mfma_f32_16x16x32_bf16 v[50:53], v[170:173], v[154:157], v[50:53]
	ds_read_b128 v[150:153], v149 offset:13312
	v_mfma_f32_16x16x32_bf16 v[38:41], v[170:173], v[158:161], v[38:41]
	v_mfma_f32_16x16x32_bf16 v[46:49], v[170:173], v[162:165], v[46:49]
	v_mfma_f32_16x16x32_bf16 v[34:37], v[170:173], v[166:169], v[34:37]
	s_waitcnt lgkmcnt(0)
	v_mfma_f32_16x16x32_bf16 v[26:29], v[150:153], v[154:157], v[26:29]
	ds_read_b128 v[170:173], v149 offset:15360
	v_mfma_f32_16x16x32_bf16 v[30:33], v[150:153], v[158:161], v[30:33]
	v_mfma_f32_16x16x32_bf16 v[78:81], v[150:153], v[162:165], v[78:81]
	v_mfma_f32_16x16x32_bf16 v[22:25], v[150:153], v[166:169], v[22:25]
	s_waitcnt lgkmcnt(0)
	v_mfma_f32_16x16x32_bf16 v[14:17], v[170:173], v[154:157], v[14:17]
	v_mfma_f32_16x16x32_bf16 v[18:21], v[170:173], v[158:161], v[18:21]
	v_mfma_f32_16x16x32_bf16 v[74:77], v[170:173], v[162:165], v[74:77]
	v_mfma_f32_16x16x32_bf16 v[10:13], v[170:173], v[166:169], v[10:13]
	s_add_i32 s22, s22, 0x10000
	s_waitcnt vmcnt(0)
	s_add_u32 s8, s8, 0x80
	s_addc_u32 s9, s9, 0
	s_cmpk_lg_i32 s8, 0x780
	s_waitcnt vmcnt(0)
	s_barrier
	s_cbranch_scc1 .LBB0_43
; #define WAIT_V0() asm volatile("s_waitcnt vmcnt(0)" ::: "memory")
; DI void gemm_core(const int tid, const u16* __restrict__ Wb, int ldw, const u16* __restrict__ Xb, int ldx, int K, f32x4 (&acc)[8][4], const bool pre = false) {
;     ...
; #pragma unroll
;     for (int ks = 0; ks < 2; ++ks) {
;       bf16x8 At[8], Bf[4];
;       const char* pb = shm + cur * STAGE_B + TILE_B + lds_byte(wc * 64 + fr, fq * 8) + ks * 1024;
;       const char* pa = shm + cur * STAGE_B + lds_byte(wr * 128 + fr, fq * 8) + ks * 1024;
; #pragma unroll
;       for (int n = 0; n < 4; ++n) Bf[n] = *(const bf16x8*)(pb + n * 2048);
; #pragma unroll
;       for (int m = 0; m < 8; ++m) At[m] = *(const bf16x8*)(pa + m * 2048);
; #pragma unroll
;       for (int m = 0; m < 8; ++m)
; #pragma unroll
;         for (int n = 0; n < 4; ++n)
;           acc[m][n] = __builtin_amdgcn_mfma_f32_16x16x32_bf16(At[m], Bf[n], acc[m][n], 0, 0, 0);
;       __builtin_amdgcn_sched_group_barrier(0x100, 5, 0);
; #pragma unroll
;       for (int m = 0; m < 8; ++m) {
;         __builtin_amdgcn_sched_group_barrier(0x008, 1, 0);
;         if (m < 7) __builtin_amdgcn_sched_group_barrier(0x100, 1, 0);
;         __builtin_amdgcn_sched_group_barrier(0x008, 3, 0);
;       }
;       __builtin_amdgcn_sched_barrier(0);
;     }
;     WAIT_V0(); __syncthreads();
; template <int CT>
; DI void phase_g4(int c, int l) {
;     ...
;     { int pm2, pn2;
;       pre = tile_map((it + 1) * G + vb, ntm, ntn, pm2, pn2);
;       if (pre) gemm_stage0(tid, WSU(WpgT) + ((size_t)l * 1024 + (pn2 << 8)) * 1024, 1024, WSU(x1b) + (size_t)(pm2 << 8) * 1024, 1024); }
	v_add_u32_e32 v130, s21, v148
	v_add_u32_e32 v198, 0x10000, v130
	ds_read_b128 v[150:153], v198 offset:12288
	v_add_u32_e32 v134, s15, v148
	v_add_u32_e32 v199, 0x18000, v134
	ds_read_b128 v[130:133], v198 offset:14336
	ds_read_b128 v[154:157], v198 offset:10240
	ds_read_b128 v[158:161], v198 offset:8192
	ds_read_b128 v[162:165], v198 offset:6144
	ds_read_b128 v[166:169], v199 offset:4096
	s_waitcnt lgkmcnt(0)
	v_mfma_f32_16x16x32_bf16 v[138:141], v[150:153], v[166:169], v[78:81]
	s_nop 2
	ds_read_b128 v[78:81], v199 offset:2048
	s_waitcnt lgkmcnt(0)
	v_mfma_f32_16x16x32_bf16 v[6:9], v[158:161], v[78:81], v[6:9]
	v_mfma_f32_16x16x32_bf16 v[134:137], v[130:133], v[166:169], v[74:77]
	v_mfma_f32_16x16x32_bf16 v[178:181], v[154:157], v[166:169], v[46:49]
	v_mfma_f32_16x16x32_bf16 v[170:173], v[130:133], v[78:81], v[18:21]
	s_nop 2
	ds_read_b128 v[18:21], v199 offset:6144
	s_waitcnt lgkmcnt(0)
	v_mfma_f32_16x16x32_bf16 v[174:177], v[150:153], v[18:21], v[22:25]
	s_nop 2
	ds_read_b128 v[22:25], v199
	s_waitcnt lgkmcnt(0)
	v_mfma_f32_16x16x32_bf16 v[42:45], v[158:161], v[22:25], v[42:45]
	ds_read_b128 v[74:77], v198 offset:4096
	v_mfma_f32_16x16x32_bf16 v[70:73], v[162:165], v[22:25], v[70:73]
	v_mfma_f32_16x16x32_bf16 v[142:145], v[130:133], v[18:21], v[10:13]
	v_mfma_f32_16x16x32_bf16 v[190:193], v[158:161], v[18:21], v[54:57]
	s_nop 1
	ds_read_b128 v[10:13], v198 offset:2048
	s_waitcnt lgkmcnt(0)
	v_mfma_f32_16x16x32_bf16 v[54:57], v[10:13], v[166:169], v[102:105]
	v_mfma_f32_16x16x32_bf16 v[102:105], v[74:77], v[78:81], v[90:93]
	v_mfma_f32_16x16x32_bf16 v[194:197], v[154:157], v[22:25], v[50:53]
	v_mfma_f32_16x16x32_bf16 v[50:53], v[74:77], v[18:21], v[82:85]
	v_mfma_f32_16x16x32_bf16 v[82:85], v[74:77], v[166:169], v[86:89]
	v_mfma_f32_16x16x32_bf16 v[74:77], v[74:77], v[22:25], v[94:97]
	v_mfma_f32_16x16x32_bf16 v[46:49], v[10:13], v[18:21], v[98:101]
	v_mfma_f32_16x16x32_bf16 v[86:89], v[10:13], v[78:81], v[106:109]
	v_mfma_f32_16x16x32_bf16 v[10:13], v[10:13], v[22:25], v[110:113]
	v_mfma_f32_16x16x32_bf16 v[182:185], v[150:153], v[78:81], v[30:33]
	v_mfma_f32_16x16x32_bf16 v[38:41], v[154:157], v[78:81], v[38:41]
	v_mfma_f32_16x16x32_bf16 v[66:69], v[162:165], v[78:81], v[66:69]
	v_mfma_f32_16x16x32_bf16 v[34:37], v[154:157], v[18:21], v[34:37]
	v_mfma_f32_16x16x32_bf16 v[98:101], v[162:165], v[166:169], v[62:65]
	v_mfma_f32_16x16x32_bf16 v[186:189], v[130:133], v[22:25], v[14:17]
	v_mfma_f32_16x16x32_bf16 v[148:151], v[150:153], v[22:25], v[26:29]
	s_nop 1
	ds_read_b128 v[14:17], v198
	s_waitcnt lgkmcnt(0)
	v_mfma_f32_16x16x32_bf16 v[26:29], v[14:17], v[18:21], v[114:117]
	v_mfma_f32_16x16x32_bf16 v[18:21], v[162:165], v[18:21], v[58:61]
	v_mfma_f32_16x16x32_bf16 v[30:33], v[14:17], v[166:169], v[118:121]
	v_mfma_f32_16x16x32_bf16 v[58:61], v[14:17], v[78:81], v[122:125]
	v_mfma_f32_16x16x32_bf16 v[14:17], v[14:17], v[22:25], v[126:129]
	v_mfma_f32_16x16x32_bf16 v[2:5], v[158:161], v[166:169], v[2:5]
	ds_read_b128 v[22:25], v198 offset:1024
	ds_read_b128 v[118:121], v199 offset:1024
	ds_read_b128 v[126:129], v199 offset:3072
	ds_read_b128 v[152:155], v199 offset:5120
	ds_read_b128 v[162:165], v199 offset:7168
	s_waitcnt lgkmcnt(3)
	v_mfma_f32_16x16x32_bf16 v[158:161], v[22:25], v[118:121], v[14:17]
	s_nop 2
	ds_read_b128 v[14:17], v198 offset:3072
	s_waitcnt lgkmcnt(3)
	v_mfma_f32_16x16x32_bf16 v[94:97], v[22:25], v[126:129], v[58:61]
	s_waitcnt lgkmcnt(2)
	v_mfma_f32_16x16x32_bf16 v[62:65], v[22:25], v[152:155], v[30:33]
	s_waitcnt lgkmcnt(1)
	v_mfma_f32_16x16x32_bf16 v[30:33], v[22:25], v[162:165], v[26:29]
	s_waitcnt lgkmcnt(0)
	v_mfma_f32_16x16x32_bf16 v[130:133], v[14:17], v[118:121], v[10:13]
	s_nop 2
	ds_read_b128 v[10:13], v198 offset:5120
	v_mfma_f32_16x16x32_bf16 v[90:93], v[14:17], v[126:129], v[86:89]
	v_mfma_f32_16x16x32_bf16 v[58:61], v[14:17], v[152:155], v[54:57]
	v_mfma_f32_16x16x32_bf16 v[26:29], v[14:17], v[162:165], v[46:49]
	s_waitcnt lgkmcnt(0)
	v_mfma_f32_16x16x32_bf16 v[122:125], v[10:13], v[118:121], v[74:77]
	ds_read_b128 v[14:17], v198 offset:7168
	v_mfma_f32_16x16x32_bf16 v[86:89], v[10:13], v[126:129], v[102:105]
	v_mfma_f32_16x16x32_bf16 v[54:57], v[10:13], v[152:155], v[82:85]
	v_mfma_f32_16x16x32_bf16 v[22:25], v[10:13], v[162:165], v[50:53]
	s_waitcnt lgkmcnt(0)
	v_mfma_f32_16x16x32_bf16 v[114:117], v[14:17], v[118:121], v[70:73]
	ds_read_b128 v[10:13], v198 offset:9216
	v_mfma_f32_16x16x32_bf16 v[82:85], v[14:17], v[126:129], v[66:69]
	v_mfma_f32_16x16x32_bf16 v[50:53], v[14:17], v[152:155], v[98:101]
	v_mfma_f32_16x16x32_bf16 v[18:21], v[14:17], v[162:165], v[18:21]
	s_waitcnt lgkmcnt(0)
	v_mfma_f32_16x16x32_bf16 v[110:113], v[10:13], v[118:121], v[42:45]
	ds_read_b128 v[66:69], v198 offset:11264
	v_mfma_f32_16x16x32_bf16 v[78:81], v[10:13], v[126:129], v[6:9]
	v_mfma_f32_16x16x32_bf16 v[46:49], v[10:13], v[152:155], v[2:5]
	v_mfma_f32_16x16x32_bf16 v[14:17], v[10:13], v[162:165], v[190:193]
	s_waitcnt lgkmcnt(0)
	v_mfma_f32_16x16x32_bf16 v[106:109], v[66:69], v[118:121], v[194:197]
	ds_read_b128 v[2:5], v198 offset:13312
	v_mfma_f32_16x16x32_bf16 v[74:77], v[66:69], v[126:129], v[38:41]
	v_mfma_f32_16x16x32_bf16 v[42:45], v[66:69], v[152:155], v[178:181]
	v_mfma_f32_16x16x32_bf16 v[10:13], v[66:69], v[162:165], v[34:37]
	s_waitcnt lgkmcnt(0)
	v_mfma_f32_16x16x32_bf16 v[102:105], v[2:5], v[118:121], v[148:151]
	s_nop 2
	ds_read_b128 v[148:151], v198 offset:15360
	v_mfma_f32_16x16x32_bf16 v[70:73], v[2:5], v[126:129], v[182:185]
	v_mfma_f32_16x16x32_bf16 v[38:41], v[2:5], v[152:155], v[138:141]
	v_mfma_f32_16x16x32_bf16 v[6:9], v[2:5], v[162:165], v[174:177]
	s_waitcnt lgkmcnt(0)
	v_mfma_f32_16x16x32_bf16 v[98:101], v[148:151], v[118:121], v[186:189]
	v_mfma_f32_16x16x32_bf16 v[66:69], v[148:151], v[126:129], v[170:173]
	v_mfma_f32_16x16x32_bf16 v[34:37], v[148:151], v[152:155], v[134:137]
	v_mfma_f32_16x16x32_bf16 v[2:5], v[148:151], v[162:165], v[142:145]
	s_add_i32 s29, s29, 1
	s_mul_i32 s7, s29, s3
	s_waitcnt vmcnt(0)
	s_add_i32 s7, s7, s26
	s_cmpk_lt_i32 s7, 0x200
	s_cselect_b64 s[22:23], -1, 0
	s_cmpk_gt_i32 s7, 0x1ff
	s_barrier
	s_cbranch_scc1 .LBB0_46
	s_ashr_i32 s8, s7, 31
	s_lshr_b32 s8, s8, 27
	s_add_i32 s8, s7, s8
	s_ashr_i32 s9, s8, 5
	s_and_b32 s8, s8, 0xffe0
	s_sub_i32 s7, s7, s8
	s_bfe_i32 s8, s7, 0x80000
	s_bfe_u32 s8, s8, 0x3000c
	s_add_i32 s8, s7, s8
	s_bfe_i32 s15, s8, 0x80000
	s_and_b32 s8, s8, 0xf8
	s_sub_i32 s7, s7, s8
	s_lshl_b32 s9, s9, 3
	s_sext_i32_i16 s15, s15
	s_sext_i32_i8 s7, s7
	s_add_i32 s42, s9, s7
	s_ashr_i32 s43, s15, 3

; DI uint4 ld_nt16(const void* q) { const ntu4 t = __builtin_nontemporal_load((const ntu4*)q); uint4 v; v.x = t[0]; v.y = t[1]; v.z = t[2]; v.w = t[3]; return v; }
; DI int opaque_tid() { int t = threadIdx.x; asm volatile("" : "+v"(t)); return t; }
; DI int uni(int v) { return __builtin_amdgcn_readfirstlane(v); }
; DI float bf2f(u16 v) { return __uint_as_float(((unsigned)v) << 16); }
; DI float sigmoidf_(float x) { return frcp(1.f + __expf(-x)); }
; template <int CT>
; DI void phase_g4(int c, int l) {
;     ...
;     { const int etid = opaque_tid(), wid = uni(etid >> 6), lane = etid & 63, wr = wid >> 2, wc = wid & 3, fr = lane & 15, fq = lane >> 4; (void)lane; (void)wr; (void)wc; (void)fr; (void)fq;
; #pragma unroll
;     for (int n = 0; n < 4; ++n) {
;       const int tl = tbase + wc * 64 + n * 16 + fr;
;       const size_t tg = (size_t)c * CT + tl;
;       const float rs = rsqrtf(WSF(ssq1)[(size_t)l * CT + tl] * (1.f / 1024.f) + EPS);
;       float ss = 0.f;
;       f32x4 xin8[8]; uint4 pp4[4];
; #pragma unroll
;       for (int m = 0; m < 8; ++m) xin8[m] = *(const f32x4*)(p.out + tg * 1024 + fbase + wr * 128 + m * 16 + fq * 4);
; #pragma unroll
;       for (int mp = 0; mp < 4; ++mp) pp4[mp] = ld_nt16(WSU(PPB) + frag_off(pm, pn, wid, n, mp, lane));
; #pragma unroll
;       for (int m = 0; m < 8; ++m) {
;         const int f = fbase + wr * 128 + m * 16 + fq * 4;
;         f32x4 xv = xin8[m];
;         uint2 pp; pp.x = (m & 1) ? pp4[m >> 1].z : pp4[m >> 1].x; pp.y = (m & 1) ? pp4[m >> 1].w : pp4[m >> 1].y;
;         xv[0] += sigmoidf_(rs * acc[m][n][0]) * bf2f(pp.x & 0xffff);
;         xv[1] += sigmoidf_(rs * acc[m][n][1]) * bf2f(pp.x >> 16);
;         xv[2] += sigmoidf_(rs * acc[m][n][2]) * bf2f(pp.y & 0xffff);
;         xv[3] += sigmoidf_(rs * acc[m][n][3]) * bf2f(pp.y >> 16);
;         *(f32x4*)(p.out + tg * 1024 + f) = xv;
;         if (l == 0) {
;           *(unsigned*)((u8*)WSU(xb) + (size_t)tl * 1024 + f) = pk4_fp8(xv[0], xv[1], xv[2], xv[3]);
;           ss += xv[0] * xv[0] + xv[1] * xv[1] + xv[2] * xv[2] + xv[3] * xv[3];
;         }
;       }
.LBB0_48:
	v_mov_b32_e32 v0, v210
	s_nop 0
	v_readfirstlane_b32 s8, v0
	s_and_b32 s7, s8, 0xc0
	v_and_or_b32 v118, v0, 15, s7
	v_or_b32_e32 v176, s6, v118
	v_ashrrev_i32_e32 v177, 31, v176
	v_lshl_add_u64 v[180:181], v[176:177], 2, s[10:11]
	global_load_dword v185, v[180:181], off
	s_ashr_i32 s44, s8, 6
	s_lshl_b64 s[6:7], s[4:5], 2
	s_add_u32 s5, s12, s6
	s_addc_u32 s15, s13, s7
	s_ashr_i32 s6, s8, 1
	s_and_b32 s6, s6, 0xffffff80
	s_ashr_i32 s7, s6, 31
	v_and_b32_e32 v184, 63, v0
	s_lshl_b64 s[8:9], s[6:7], 2
	v_lshrrev_b32_e32 v0, 2, v0
	s_add_u32 s8, s5, s8
	v_and_b32_e32 v118, 12, v0
	s_addc_u32 s9, s15, s9
	v_lshlrev_b32_e32 v0, 2, v118
	s_ashr_i32 s15, s14, 31
	s_ashr_i32 s21, s20, 31
	v_lshl_add_u64 v[178:179], s[8:9], 0, v[0:1]
	s_lshl_b64 s[8:9], s[14:15], 5
	s_lshl_b64 s[24:25], s[20:21], 3
	s_add_u32 s5, s24, s8
	s_addc_u32 s7, s25, s9
	s_ashr_i32 s9, s44, 31
	s_add_u32 s8, s5, s44
	s_addc_u32 s9, s7, s9
	s_lshl_b64 s[8:9], s[8:9], 14
	s_add_u32 s8, s36, s8
	s_addc_u32 s9, s37, s9
	s_add_i32 s4, s6, s4
	v_or_b32_e32 v174, s4, v118
	v_lshl_add_u64 v[118:119], s[54:55], 0, v[176:177]
	v_lshlrev_b64 v[182:183], 12, v[118:119]
	v_lshl_add_u64 v[118:119], v[178:179], 0, v[182:183]
	v_lshlrev_b32_e32 v0, 4, v184
	v_readlane_b32 s6, v255, 30
	v_lshl_add_u64 v[190:191], s[12:13], 0, v[182:183]
	v_lshlrev_b64 v[182:183], 10, v[176:177]
	v_readlane_b32 s7, v255, 31
	v_lshl_add_u64 v[182:183], s[16:17], 0, v[182:183]
	global_load_dwordx4 v[186:189], v[118:119], off
	global_load_dwordx4 v[166:169], v[118:119], off offset:64
	global_load_dwordx4 v[154:157], v[118:119], off offset:128
	global_load_dwordx4 v[150:153], v[118:119], off offset:192
	global_load_dwordx4 v[142:145], v[118:119], off offset:256
	global_load_dwordx4 v[138:141], v[118:119], off offset:320
	global_load_dwordx4 v[126:129], v[118:119], off offset:384
	s_nop 0
	global_load_dwordx4 v[118:121], v[118:119], off offset:448
	s_nop 0
	global_load_dwordx4 v[170:173], v0, s[8:9] nt
	global_load_dwordx4 v[162:165], v0, s[8:9] offset:1024 nt
	global_load_dwordx4 v[146:149], v0, s[8:9] offset:2048 nt
	global_load_dwordx4 v[134:137], v0, s[8:9] offset:3072 nt
	s_waitcnt vmcnt(12)
	v_fmamk_f32 v185, v185, 0x3a800000, v211
	v_cmp_gt_f32_e32 vcc, s88, v185
	v_mul_f32_e32 v175, 0x4b800000, v185
	s_nop 0
	v_cndmask_b32_e32 v185, v185, v175, vcc
	v_rsq_f32_e32 v175, v185
	s_nop 0
	v_mul_f32_e32 v185, 0x45800000, v175
	v_cndmask_b32_e32 v185, v175, v185, vcc
	v_mul_f32_e32 v158, v158, v185
	v_mul_f32_e32 v159, v159, v185
	v_mul_f32_e32 v158, 0xbfb8aa3b, v158
	v_mul_f32_e32 v159, 0xbfb8aa3b, v159
	v_mul_f32_e32 v160, v160, v185
	v_mul_f32_e32 v161, v161, v185
	v_exp_f32_e32 v158, v158
	v_exp_f32_e32 v159, v159
	v_mul_f32_e32 v160, 0xbfb8aa3b, v160
	v_mul_f32_e32 v161, 0xbfb8aa3b, v161
	v_exp_f32_e32 v160, v160
	v_exp_f32_e32 v161, v161
	v_add_f32_e32 v158, 1.0, v158
	v_add_f32_e32 v159, 1.0, v159
	v_rcp_f32_e32 v158, v158
	v_rcp_f32_e32 v159, v159
	v_add_f32_e32 v160, 1.0, v160
	v_add_f32_e32 v161, 1.0, v161
	v_rcp_f32_e32 v160, v160
	v_rcp_f32_e32 v161, v161
	v_ashrrev_i32_e32 v175, 31, v174
	s_andn2_b64 vcc, exec, s[6:7]
	v_lshl_add_u64 v[182:183], v[182:183], 0, v[174:175]
	s_waitcnt vmcnt(0)
	v_lshlrev_b32_e32 v192, 16, v170
	v_and_b32_e32 v193, 0xffff0000, v170
	v_pk_fma_f32 v[158:159], v[158:159], v[192:193], v[186:187]
	v_and_b32_e32 v187, 0xffff0000, v171
	v_lshlrev_b32_e32 v186, 16, v171
	v_pk_fma_f32 v[160:161], v[160:161], v[186:187], v[188:189]
	v_cndmask_b32_e64 v187, 0, 1, s[6:7]
	v_lshl_add_u64 v[170:171], v[174:175], 2, v[190:191]
	v_mov_b32_e32 v186, 0
	v_cmp_ne_u32_e64 s[4:5], 1, v187
	global_store_dwordx4 v[170:171], v[158:161], off
	s_cbranch_vccnz .LBB0_50
	v_mov_b32_e32 v188, v1
	v_cvt_pk_fp8_f32 v188, v158, v159
	v_pk_mul_f32 v[158:159], v[158:159], v[158:159]
	v_pk_mul_f32 v[186:187], v[160:161], v[160:161]
	v_add_f32_e32 v158, v158, v159
	v_cvt_pk_fp8_f32 v188, v160, v161 op_sel:[0,0,1]
	v_add_f32_e32 v158, v186, v158
	v_add_f32_e32 v186, v187, v158
	global_store_dword v[182:183], v188, off

; #define WAIT_V0() asm volatile("s_waitcnt vmcnt(0)" ::: "memory")
; DI void gemm_core(const int tid, const u16* __restrict__ Wb, int ldw, const u16* __restrict__ Xb, int ldx, int K, f32x4 (&acc)[8][4], const bool pre = false) {
;     ...
;   auto stage = [&](int buf, int kt) {
; #pragma unroll
;     for (int i = 0; i < 4; ++i) {
;       __builtin_amdgcn_global_load_lds((const unsigned*)(Wb + offw[i] + kt * 64), (unsigned*)(shm + buf * STAGE_B + wid * 1024 + i * 8192), 16, 0, 0);
;       __builtin_amdgcn_global_load_lds((const unsigned*)(Xb + offx[i] + kt * 64), (unsigned*)(shm + buf * STAGE_B + TILE_B + wid * 1024 + i * 8192), 16, 0, 0);
;     }
;   };
;   const int nt = K >> 6;
;   if (!pre) stage(0, 0);
;   WAIT_V0(); __syncthreads();
;   for (int t = 0; t < nt; ++t) {
;     const int cur = t & 1;
;     if (t + 1 < nt) stage(cur ^ 1, t + 1);
; #pragma unroll
;     for (int ks = 0; ks < 2; ++ks) {
;       bf16x8 At[8], Bf[4];
;       const char* pb = shm + cur * STAGE_B + TILE_B + lds_byte(wc * 64 + fr, fq * 8) + ks * 1024;
;       const char* pa = shm + cur * STAGE_B + lds_byte(wr * 128 + fr, fq * 8) + ks * 1024;
; #pragma unroll
;       for (int n = 0; n < 4; ++n) Bf[n] = *(const bf16x8*)(pb + n * 2048);
; #pragma unroll
;       for (int m = 0; m < 8; ++m) At[m] = *(const bf16x8*)(pa + m * 2048);
; #pragma unroll
;       for (int m = 0; m < 8; ++m)
; #pragma unroll
;         for (int n = 0; n < 4; ++n)
;           acc[m][n] = __builtin_amdgcn_mfma_f32_16x16x32_bf16(At[m], Bf[n], acc[m][n], 0, 0, 0);
;       __builtin_amdgcn_sched_group_barrier(0x100, 5, 0);
; #pragma unroll
;       for (int m = 0; m < 8; ++m) {
;         __builtin_amdgcn_sched_group_barrier(0x008, 1, 0);
;         if (m < 7) __builtin_amdgcn_sched_group_barrier(0x100, 1, 0);
;         __builtin_amdgcn_sched_group_barrier(0x008, 3, 0);
;       }
;       __builtin_amdgcn_sched_barrier(0);
;     }
;     WAIT_V0(); __syncthreads();
.LBB0_159:
	s_and_b32 s9, s8, 0x10000
	s_xor_b32 s27, s9, 0x10000
	s_add_i32 s27, s26, s27
	s_add_i32 vcc_lo, s25, s9
	s_nop 1
	v_add_u32_e32 v149, vcc_lo, v148
	ds_read_b128 v[150:153], v149
	s_or_b32 s9, s24, s9
	v_add_u32_e32 v174, s9, v148
	ds_read_b128 v[154:157], v174 offset:32768
	ds_read_b128 v[158:161], v174 offset:34816
	ds_read_b128 v[162:165], v174 offset:36864
	ds_read_b128 v[166:169], v174 offset:38912
	s_mov_b32 m0, s27
	s_nop 0
	global_load_lds_dwordx4 v[144:145], off
	v_lshl_add_u64 v[144:145], v[144:145], 0, s[64:65]
	s_waitcnt lgkmcnt(0)
	v_mfma_f32_16x16x32_bf16 v[126:129], v[150:153], v[154:157], v[126:129]
	ds_read_b128 v[170:173], v149 offset:2048
	v_mfma_f32_16x16x32_bf16 v[122:125], v[150:153], v[158:161], v[122:125]
	v_mfma_f32_16x16x32_bf16 v[118:121], v[150:153], v[162:165], v[118:121]
	v_mfma_f32_16x16x32_bf16 v[114:117], v[150:153], v[166:169], v[114:117]
	s_waitcnt lgkmcnt(0)
	v_mfma_f32_16x16x32_bf16 v[110:113], v[170:173], v[154:157], v[110:113]
	ds_read_b128 v[150:153], v149 offset:4096
	s_add_i32 m0, s27, 0x8000
	s_nop 0
	global_load_lds_dwordx4 v[142:143], off
	v_lshl_add_u64 v[142:143], v[142:143], 0, s[64:65]
	v_mfma_f32_16x16x32_bf16 v[106:109], v[170:173], v[158:161], v[106:109]
	v_mfma_f32_16x16x32_bf16 v[102:105], v[170:173], v[162:165], v[102:105]
	v_mfma_f32_16x16x32_bf16 v[98:101], v[170:173], v[166:169], v[98:101]
	s_waitcnt lgkmcnt(0)
	v_mfma_f32_16x16x32_bf16 v[94:97], v[150:153], v[154:157], v[94:97]
	ds_read_b128 v[170:173], v149 offset:6144
	s_add_i32 m0, s27, 0x2000
	s_nop 0
	global_load_lds_dwordx4 v[140:141], off
	v_lshl_add_u64 v[140:141], v[140:141], 0, s[64:65]
	v_mfma_f32_16x16x32_bf16 v[90:93], v[150:153], v[158:161], v[90:93]
	v_mfma_f32_16x16x32_bf16 v[86:89], v[150:153], v[162:165], v[86:89]
	v_mfma_f32_16x16x32_bf16 v[82:85], v[150:153], v[166:169], v[82:85]
	s_waitcnt lgkmcnt(0)
	v_mfma_f32_16x16x32_bf16 v[70:73], v[170:173], v[154:157], v[70:73]
	ds_read_b128 v[150:153], v149 offset:8192
	s_add_i32 m0, s27, 0xa000
	s_nop 0
	global_load_lds_dwordx4 v[138:139], off
	v_lshl_add_u64 v[138:139], v[138:139], 0, s[64:65]
	v_mfma_f32_16x16x32_bf16 v[66:69], v[170:173], v[158:161], v[66:69]
	v_mfma_f32_16x16x32_bf16 v[62:65], v[170:173], v[162:165], v[62:65]
	v_mfma_f32_16x16x32_bf16 v[58:61], v[170:173], v[166:169], v[58:61]
	s_waitcnt lgkmcnt(0)
	v_mfma_f32_16x16x32_bf16 v[42:45], v[150:153], v[154:157], v[42:45]
	ds_read_b128 v[170:173], v149 offset:10240
	s_add_i32 m0, s27, 0x4000
	s_nop 0
	global_load_lds_dwordx4 v[136:137], off
	v_lshl_add_u64 v[136:137], v[136:137], 0, s[64:65]
	v_mfma_f32_16x16x32_bf16 v[6:9], v[150:153], v[158:161], v[6:9]
	v_mfma_f32_16x16x32_bf16 v[2:5], v[150:153], v[162:165], v[2:5]
	v_mfma_f32_16x16x32_bf16 v[54:57], v[150:153], v[166:169], v[54:57]
	s_waitcnt lgkmcnt(0)
	v_mfma_f32_16x16x32_bf16 v[50:53], v[170:173], v[154:157], v[50:53]
	ds_read_b128 v[150:153], v149 offset:12288
	s_add_i32 m0, s27, 0xc000
	s_nop 0
	global_load_lds_dwordx4 v[134:135], off
	v_lshl_add_u64 v[134:135], v[134:135], 0, s[64:65]
	v_mfma_f32_16x16x32_bf16 v[38:41], v[170:173], v[158:161], v[38:41]
	v_mfma_f32_16x16x32_bf16 v[46:49], v[170:173], v[162:165], v[46:49]
	v_mfma_f32_16x16x32_bf16 v[34:37], v[170:173], v[166:169], v[34:37]
	s_waitcnt lgkmcnt(0)
	v_mfma_f32_16x16x32_bf16 v[26:29], v[150:153], v[154:157], v[26:29]
	ds_read_b128 v[170:173], v149 offset:14336
	s_add_i32 m0, s27, 0x6000
	s_nop 0
	global_load_lds_dwordx4 v[132:133], off
	v_lshl_add_u64 v[132:133], v[132:133], 0, s[64:65]
	v_mfma_f32_16x16x32_bf16 v[30:33], v[150:153], v[158:161], v[30:33]
	v_mfma_f32_16x16x32_bf16 v[78:81], v[150:153], v[162:165], v[78:81]
	v_mfma_f32_16x16x32_bf16 v[22:25], v[150:153], v[166:169], v[22:25]
	s_waitcnt lgkmcnt(0)
	v_mfma_f32_16x16x32_bf16 v[14:17], v[170:173], v[154:157], v[14:17]
	s_add_i32 m0, s27, 0xe000
	s_nop 0
	global_load_lds_dwordx4 v[130:131], off
	v_lshl_add_u64 v[130:131], v[130:131], 0, s[64:65]
	v_mfma_f32_16x16x32_bf16 v[18:21], v[170:173], v[158:161], v[18:21]
	v_mfma_f32_16x16x32_bf16 v[74:77], v[170:173], v[162:165], v[74:77]
	v_mfma_f32_16x16x32_bf16 v[10:13], v[170:173], v[166:169], v[10:13]
	ds_read_b128 v[150:153], v149 offset:1024
	ds_read_b128 v[154:157], v174 offset:33792
	ds_read_b128 v[158:161], v174 offset:35840
	ds_read_b128 v[162:165], v174 offset:37888
	ds_read_b128 v[166:169], v174 offset:39936
	s_waitcnt lgkmcnt(0)
	v_mfma_f32_16x16x32_bf16 v[126:129], v[150:153], v[154:157], v[126:129]
	ds_read_b128 v[170:173], v149 offset:3072
	v_mfma_f32_16x16x32_bf16 v[122:125], v[150:153], v[158:161], v[122:125]
	v_mfma_f32_16x16x32_bf16 v[118:121], v[150:153], v[162:165], v[118:121]
	v_mfma_f32_16x16x32_bf16 v[114:117], v[150:153], v[166:169], v[114:117]
	s_waitcnt lgkmcnt(0)
	v_mfma_f32_16x16x32_bf16 v[110:113], v[170:173], v[154:157], v[110:113]
	ds_read_b128 v[150:153], v149 offset:5120
	v_mfma_f32_16x16x32_bf16 v[106:109], v[170:173], v[158:161], v[106:109]
	v_mfma_f32_16x16x32_bf16 v[102:105], v[170:173], v[162:165], v[102:105]
	v_mfma_f32_16x16x32_bf16 v[98:101], v[170:173], v[166:169], v[98:101]
	s_waitcnt lgkmcnt(0)
	v_mfma_f32_16x16x32_bf16 v[94:97], v[150:153], v[154:157], v[94:97]
	ds_read_b128 v[170:173], v149 offset:7168
	v_mfma_f32_16x16x32_bf16 v[90:93], v[150:153], v[158:161], v[90:93]
	v_mfma_f32_16x16x32_bf16 v[86:89], v[150:153], v[162:165], v[86:89]
	v_mfma_f32_16x16x32_bf16 v[82:85], v[150:153], v[166:169], v[82:85]
	s_waitcnt lgkmcnt(0)
	v_mfma_f32_16x16x32_bf16 v[70:73], v[170:173], v[154:157], v[70:73]
	ds_read_b128 v[150:153], v149 offset:9216
	v_mfma_f32_16x16x32_bf16 v[66:69], v[170:173], v[158:161], v[66:69]
	v_mfma_f32_16x16x32_bf16 v[62:65], v[170:173], v[162:165], v[62:65]
	v_mfma_f32_16x16x32_bf16 v[58:61], v[170:173], v[166:169], v[58:61]
	s_waitcnt lgkmcnt(0)
; #define WAIT_V0() asm volatile("s_waitcnt vmcnt(0)" ::: "memory")
; DI void gemm_core(const int tid, const u16* __restrict__ Wb, int ldw, const u16* __restrict__ Xb, int ldx, int K, f32x4 (&acc)[8][4], const bool pre = false) {
;     ...
;     for (int ks = 0; ks < 2; ++ks) {
;       bf16x8 At[8], Bf[4];
;       const char* pb = shm + cur * STAGE_B + TILE_B + lds_byte(wc * 64 + fr, fq * 8) + ks * 1024;
;       const char* pa = shm + cur * STAGE_B + lds_byte(wr * 128 + fr, fq * 8) + ks * 1024;
; #pragma unroll
;       for (int n = 0; n < 4; ++n) Bf[n] = *(const bf16x8*)(pb + n * 2048);
; #pragma unroll
;       for (int m = 0; m < 8; ++m) At[m] = *(const bf16x8*)(pa + m * 2048);
; #pragma unroll
;       for (int m = 0; m < 8; ++m)
; #pragma unroll
;         for (int n = 0; n < 4; ++n)
;           acc[m][n] = __builtin_amdgcn_mfma_f32_16x16x32_bf16(At[m], Bf[n], acc[m][n], 0, 0, 0);
;       __builtin_amdgcn_sched_group_barrier(0x100, 5, 0);
; #pragma unroll
;       for (int m = 0; m < 8; ++m) {
;         __builtin_amdgcn_sched_group_barrier(0x008, 1, 0);
;         if (m < 7) __builtin_amdgcn_sched_group_barrier(0x100, 1, 0);
;         __builtin_amdgcn_sched_group_barrier(0x008, 3, 0);
;       }
;       __builtin_amdgcn_sched_barrier(0);
;     }
;     WAIT_V0(); __syncthreads();
;   }
	v_mfma_f32_16x16x32_bf16 v[42:45], v[150:153], v[154:157], v[42:45]
	ds_read_b128 v[170:173], v149 offset:11264
	v_mfma_f32_16x16x32_bf16 v[6:9], v[150:153], v[158:161], v[6:9]
	v_mfma_f32_16x16x32_bf16 v[2:5], v[150:153], v[162:165], v[2:5]
	v_mfma_f32_16x16x32_bf16 v[54:57], v[150:153], v[166:169], v[54:57]
	s_waitcnt lgkmcnt(0)
	v_mfma_f32_16x16x32_bf16 v[50:53], v[170:173], v[154:157], v[50:53]
	ds_read_b128 v[150:153], v149 offset:13312
	v_mfma_f32_16x16x32_bf16 v[38:41], v[170:173], v[158:161], v[38:41]
	v_mfma_f32_16x16x32_bf16 v[46:49], v[170:173], v[162:165], v[46:49]
	v_mfma_f32_16x16x32_bf16 v[34:37], v[170:173], v[166:169], v[34:37]
	s_waitcnt lgkmcnt(0)
	v_mfma_f32_16x16x32_bf16 v[26:29], v[150:153], v[154:157], v[26:29]
	ds_read_b128 v[170:173], v149 offset:15360
	v_mfma_f32_16x16x32_bf16 v[30:33], v[150:153], v[158:161], v[30:33]
	v_mfma_f32_16x16x32_bf16 v[78:81], v[150:153], v[162:165], v[78:81]
	v_mfma_f32_16x16x32_bf16 v[22:25], v[150:153], v[166:169], v[22:25]
	s_waitcnt lgkmcnt(0)
	v_mfma_f32_16x16x32_bf16 v[14:17], v[170:173], v[154:157], v[14:17]
	v_mfma_f32_16x16x32_bf16 v[18:21], v[170:173], v[158:161], v[18:21]
	v_mfma_f32_16x16x32_bf16 v[74:77], v[170:173], v[162:165], v[74:77]
	v_mfma_f32_16x16x32_bf16 v[10:13], v[170:173], v[166:169], v[10:13]
	s_add_i32 s8, s8, 0x10000
	s_waitcnt vmcnt(0)
	s_add_u32 s6, s6, 0x80
	s_addc_u32 s7, s7, 0
	s_cmpk_lg_i32 s6, 0x780
	s_waitcnt vmcnt(0)
	s_barrier
	s_cbranch_scc1 .LBB0_159
; #define WAIT_V0() asm volatile("s_waitcnt vmcnt(0)" ::: "memory")
; DI void gemm_core(const int tid, const u16* __restrict__ Wb, int ldw, const u16* __restrict__ Xb, int ldx, int K, f32x4 (&acc)[8][4], const bool pre = false) {
;     ...
; #pragma unroll
;     for (int ks = 0; ks < 2; ++ks) {
;       bf16x8 At[8], Bf[4];
;       const char* pb = shm + cur * STAGE_B + TILE_B + lds_byte(wc * 64 + fr, fq * 8) + ks * 1024;
;       const char* pa = shm + cur * STAGE_B + lds_byte(wr * 128 + fr, fq * 8) + ks * 1024;
; #pragma unroll
;       for (int n = 0; n < 4; ++n) Bf[n] = *(const bf16x8*)(pb + n * 2048);
; #pragma unroll
;       for (int m = 0; m < 8; ++m) At[m] = *(const bf16x8*)(pa + m * 2048);
; #pragma unroll
;       for (int m = 0; m < 8; ++m)
; #pragma unroll
;         for (int n = 0; n < 4; ++n)
;           acc[m][n] = __builtin_amdgcn_mfma_f32_16x16x32_bf16(At[m], Bf[n], acc[m][n], 0, 0, 0);
;       __builtin_amdgcn_sched_group_barrier(0x100, 5, 0);
; #pragma unroll
;       for (int m = 0; m < 8; ++m) {
;         __builtin_amdgcn_sched_group_barrier(0x008, 1, 0);
;         if (m < 7) __builtin_amdgcn_sched_group_barrier(0x100, 1, 0);
;         __builtin_amdgcn_sched_group_barrier(0x008, 3, 0);
;       }
;       __builtin_amdgcn_sched_barrier(0);
;     }
;     WAIT_V0(); __syncthreads();
; template <int CT>
; DI void phase_g3(int c, int l) {
;     ...
;     { int pm2, pn2;
;       pre = tile_map((it + 1) * G + vb, ntm, ntn, pm2, pn2);
;       if (pre) gemm_stage0(tid, WSU(WoutT) + ((size_t)l * 1024 + (pn2 << 8)) * 1024, 1024, WSU(MRG) + (size_t)(pm2 << 8) * 1024, 1024); }
	v_add_u32_e32 v130, s25, v148
	v_add_u32_e32 v198, 0x10000, v130
	ds_read_b128 v[150:153], v198 offset:12288
	v_add_u32_e32 v134, s24, v148
	v_add_u32_e32 v199, 0x18000, v134
	ds_read_b128 v[130:133], v198 offset:14336
	ds_read_b128 v[154:157], v198 offset:10240
	ds_read_b128 v[158:161], v198 offset:8192
	ds_read_b128 v[162:165], v198 offset:6144
	ds_read_b128 v[166:169], v199 offset:4096
	s_waitcnt lgkmcnt(0)
	v_mfma_f32_16x16x32_bf16 v[138:141], v[150:153], v[166:169], v[78:81]
	s_nop 2
	ds_read_b128 v[78:81], v199 offset:2048
	s_waitcnt lgkmcnt(0)
	v_mfma_f32_16x16x32_bf16 v[6:9], v[158:161], v[78:81], v[6:9]
	v_mfma_f32_16x16x32_bf16 v[134:137], v[130:133], v[166:169], v[74:77]
	v_mfma_f32_16x16x32_bf16 v[178:181], v[154:157], v[166:169], v[46:49]
	v_mfma_f32_16x16x32_bf16 v[170:173], v[130:133], v[78:81], v[18:21]
	s_nop 2
	ds_read_b128 v[18:21], v199 offset:6144
	s_waitcnt lgkmcnt(0)
	v_mfma_f32_16x16x32_bf16 v[174:177], v[150:153], v[18:21], v[22:25]
	s_nop 2
	ds_read_b128 v[22:25], v199
	s_waitcnt lgkmcnt(0)
	v_mfma_f32_16x16x32_bf16 v[42:45], v[158:161], v[22:25], v[42:45]
	ds_read_b128 v[74:77], v198 offset:4096
	v_mfma_f32_16x16x32_bf16 v[70:73], v[162:165], v[22:25], v[70:73]
	v_mfma_f32_16x16x32_bf16 v[142:145], v[130:133], v[18:21], v[10:13]
	v_mfma_f32_16x16x32_bf16 v[190:193], v[158:161], v[18:21], v[54:57]
	s_nop 1
	ds_read_b128 v[10:13], v198 offset:2048
	s_waitcnt lgkmcnt(0)
	v_mfma_f32_16x16x32_bf16 v[54:57], v[10:13], v[166:169], v[102:105]
	v_mfma_f32_16x16x32_bf16 v[102:105], v[74:77], v[78:81], v[90:93]
	v_mfma_f32_16x16x32_bf16 v[194:197], v[154:157], v[22:25], v[50:53]
	v_mfma_f32_16x16x32_bf16 v[50:53], v[74:77], v[18:21], v[82:85]
	v_mfma_f32_16x16x32_bf16 v[82:85], v[74:77], v[166:169], v[86:89]
	v_mfma_f32_16x16x32_bf16 v[74:77], v[74:77], v[22:25], v[94:97]
	v_mfma_f32_16x16x32_bf16 v[46:49], v[10:13], v[18:21], v[98:101]
	v_mfma_f32_16x16x32_bf16 v[86:89], v[10:13], v[78:81], v[106:109]
	v_mfma_f32_16x16x32_bf16 v[10:13], v[10:13], v[22:25], v[110:113]
	v_mfma_f32_16x16x32_bf16 v[182:185], v[150:153], v[78:81], v[30:33]
	v_mfma_f32_16x16x32_bf16 v[38:41], v[154:157], v[78:81], v[38:41]
	v_mfma_f32_16x16x32_bf16 v[66:69], v[162:165], v[78:81], v[66:69]
	v_mfma_f32_16x16x32_bf16 v[34:37], v[154:157], v[18:21], v[34:37]
	v_mfma_f32_16x16x32_bf16 v[98:101], v[162:165], v[166:169], v[62:65]
	v_mfma_f32_16x16x32_bf16 v[186:189], v[130:133], v[22:25], v[14:17]
	v_mfma_f32_16x16x32_bf16 v[148:151], v[150:153], v[22:25], v[26:29]
	s_nop 1
	ds_read_b128 v[14:17], v198
	s_waitcnt lgkmcnt(0)
	v_mfma_f32_16x16x32_bf16 v[26:29], v[14:17], v[18:21], v[114:117]
	v_mfma_f32_16x16x32_bf16 v[18:21], v[162:165], v[18:21], v[58:61]
	v_mfma_f32_16x16x32_bf16 v[30:33], v[14:17], v[166:169], v[118:121]
	v_mfma_f32_16x16x32_bf16 v[58:61], v[14:17], v[78:81], v[122:125]
	v_mfma_f32_16x16x32_bf16 v[14:17], v[14:17], v[22:25], v[126:129]
	v_mfma_f32_16x16x32_bf16 v[2:5], v[158:161], v[166:169], v[2:5]
	ds_read_b128 v[22:25], v198 offset:1024
	s_nop 0
	ds_read_b128 v[126:129], v199 offset:1024
	ds_read_b128 v[152:155], v199 offset:3072
	ds_read_b128 v[156:159], v199 offset:5120
	ds_read_b128 v[160:163], v199 offset:7168
	s_waitcnt lgkmcnt(3)
	v_mfma_f32_16x16x32_bf16 v[130:133], v[22:25], v[126:129], v[14:17]
	s_nop 2
	ds_read_b128 v[14:17], v198 offset:3072
	s_waitcnt lgkmcnt(3)
	v_mfma_f32_16x16x32_bf16 v[94:97], v[22:25], v[152:155], v[58:61]
	s_waitcnt lgkmcnt(2)
	v_mfma_f32_16x16x32_bf16 v[62:65], v[22:25], v[156:159], v[30:33]
	s_waitcnt lgkmcnt(1)
	v_mfma_f32_16x16x32_bf16 v[30:33], v[22:25], v[160:163], v[26:29]
	s_waitcnt lgkmcnt(0)
	v_mfma_f32_16x16x32_bf16 v[122:125], v[14:17], v[126:129], v[10:13]
	s_nop 2
	ds_read_b128 v[10:13], v198 offset:5120
	v_mfma_f32_16x16x32_bf16 v[90:93], v[14:17], v[152:155], v[86:89]
	v_mfma_f32_16x16x32_bf16 v[58:61], v[14:17], v[156:159], v[54:57]
	v_mfma_f32_16x16x32_bf16 v[26:29], v[14:17], v[160:163], v[46:49]
	s_waitcnt lgkmcnt(0)
	v_mfma_f32_16x16x32_bf16 v[118:121], v[10:13], v[126:129], v[74:77]
	ds_read_b128 v[14:17], v198 offset:7168
	v_mfma_f32_16x16x32_bf16 v[86:89], v[10:13], v[152:155], v[102:105]
	v_mfma_f32_16x16x32_bf16 v[54:57], v[10:13], v[156:159], v[82:85]
	v_mfma_f32_16x16x32_bf16 v[22:25], v[10:13], v[160:163], v[50:53]
	s_waitcnt lgkmcnt(0)
	v_mfma_f32_16x16x32_bf16 v[114:117], v[14:17], v[126:129], v[70:73]
	ds_read_b128 v[10:13], v198 offset:9216
	v_mfma_f32_16x16x32_bf16 v[82:85], v[14:17], v[152:155], v[66:69]
	v_mfma_f32_16x16x32_bf16 v[50:53], v[14:17], v[156:159], v[98:101]
	v_mfma_f32_16x16x32_bf16 v[18:21], v[14:17], v[160:163], v[18:21]
	s_waitcnt lgkmcnt(0)
	v_mfma_f32_16x16x32_bf16 v[110:113], v[10:13], v[126:129], v[42:45]
	ds_read_b128 v[66:69], v198 offset:11264
	v_mfma_f32_16x16x32_bf16 v[78:81], v[10:13], v[152:155], v[6:9]
	v_mfma_f32_16x16x32_bf16 v[46:49], v[10:13], v[156:159], v[2:5]
	v_mfma_f32_16x16x32_bf16 v[14:17], v[10:13], v[160:163], v[190:193]
	s_waitcnt lgkmcnt(0)
	v_mfma_f32_16x16x32_bf16 v[106:109], v[66:69], v[126:129], v[194:197]
	ds_read_b128 v[2:5], v198 offset:13312
	v_mfma_f32_16x16x32_bf16 v[74:77], v[66:69], v[152:155], v[38:41]
	v_mfma_f32_16x16x32_bf16 v[42:45], v[66:69], v[156:159], v[178:181]
	v_mfma_f32_16x16x32_bf16 v[10:13], v[66:69], v[160:163], v[34:37]
	s_waitcnt lgkmcnt(0)
	v_mfma_f32_16x16x32_bf16 v[102:105], v[2:5], v[126:129], v[148:151]
	ds_read_b128 v[6:9], v198 offset:15360
	v_mfma_f32_16x16x32_bf16 v[70:73], v[2:5], v[152:155], v[182:185]
	v_mfma_f32_16x16x32_bf16 v[38:41], v[2:5], v[156:159], v[138:141]
	v_mfma_f32_16x16x32_bf16 v[2:5], v[2:5], v[160:163], v[174:177]
	s_waitcnt lgkmcnt(0)
	v_mfma_f32_16x16x32_bf16 v[98:101], v[6:9], v[126:129], v[186:189]
	v_mfma_f32_16x16x32_bf16 v[66:69], v[6:9], v[152:155], v[170:173]
	v_mfma_f32_16x16x32_bf16 v[34:37], v[6:9], v[156:159], v[134:137]
	v_mfma_f32_16x16x32_bf16 v[6:9], v[6:9], v[160:163], v[142:145]
	s_add_i32 s35, s35, 1
	s_mul_i32 s6, s35, s3
	s_waitcnt vmcnt(0)
	s_add_i32 s6, s6, s1
	s_cmpk_lt_i32 s6, 0x200
	s_cselect_b64 s[24:25], -1, 0
	s_cmpk_gt_i32 s6, 0x1ff
	s_barrier
	s_cbranch_scc1 .LBB0_162
	s_ashr_i32 s7, s6, 31
	s_lshr_b32 s7, s7, 27
	s_add_i32 s7, s6, s7
	s_ashr_i32 s8, s7, 5
	s_and_b32 s7, s7, 0xffe0
	s_sub_i32 s6, s6, s7
	s_bfe_i32 s7, s6, 0x80000
	s_bfe_u32 s7, s7, 0x3000c
	s_add_i32 s7, s6, s7
	s_bfe_i32 s9, s7, 0x80000
	s_and_b32 s7, s7, 0xf8
	s_sub_i32 s6, s6, s7
	s_lshl_b32 s8, s8, 3
	s_sext_i32_i16 s9, s9
	s_sext_i32_i8 s6, s6
	s_add_i32 s46, s8, s6
	s_ashr_i32 s47, s9, 3

; #define WAIT_V0() asm volatile("s_waitcnt vmcnt(0)" ::: "memory")
; DI void gemm_core(const int tid, const u16* __restrict__ Wb, int ldw, const u16* __restrict__ Xb, int ldx, int K, f32x4 (&acc)[8][4], const bool pre = false) {
;     ...
;   auto stage = [&](int buf, int kt) {
; #pragma unroll
;     for (int i = 0; i < 4; ++i) {
;       __builtin_amdgcn_global_load_lds((const unsigned*)(Wb + offw[i] + kt * 64), (unsigned*)(shm + buf * STAGE_B + wid * 1024 + i * 8192), 16, 0, 0);
;       __builtin_amdgcn_global_load_lds((const unsigned*)(Xb + offx[i] + kt * 64), (unsigned*)(shm + buf * STAGE_B + TILE_B + wid * 1024 + i * 8192), 16, 0, 0);
;     }
;   };
;   const int nt = K >> 6;
;   if (!pre) stage(0, 0);
;   WAIT_V0(); __syncthreads();
;   for (int t = 0; t < nt; ++t) {
;     const int cur = t & 1;
;     if (t + 1 < nt) stage(cur ^ 1, t + 1);
; #pragma unroll
;     for (int ks = 0; ks < 2; ++ks) {
;       bf16x8 At[8], Bf[4];
;       const char* pb = shm + cur * STAGE_B + TILE_B + lds_byte(wc * 64 + fr, fq * 8) + ks * 1024;
;       const char* pa = shm + cur * STAGE_B + lds_byte(wr * 128 + fr, fq * 8) + ks * 1024;
; #pragma unroll
;       for (int n = 0; n < 4; ++n) Bf[n] = *(const bf16x8*)(pb + n * 2048);
; #pragma unroll
;       for (int m = 0; m < 8; ++m) At[m] = *(const bf16x8*)(pa + m * 2048);
; #pragma unroll
;       for (int m = 0; m < 8; ++m)
; #pragma unroll
;         for (int n = 0; n < 4; ++n)
;           acc[m][n] = __builtin_amdgcn_mfma_f32_16x16x32_bf16(At[m], Bf[n], acc[m][n], 0, 0, 0);
;       __builtin_amdgcn_sched_group_barrier(0x100, 5, 0);
; #pragma unroll
;       for (int m = 0; m < 8; ++m) {
;         __builtin_amdgcn_sched_group_barrier(0x008, 1, 0);
;         if (m < 7) __builtin_amdgcn_sched_group_barrier(0x100, 1, 0);
;         __builtin_amdgcn_sched_group_barrier(0x008, 3, 0);
;       }
;       __builtin_amdgcn_sched_barrier(0);
;     }
;     WAIT_V0(); __syncthreads();
.LBB0_219:
	s_and_b32 s21, s17, 0x10000
	s_xor_b32 s72, s21, 0x10000
	s_add_i32 s72, s1, s72
	s_add_i32 vcc_lo, s15, s21
	s_nop 1
	v_add_u32_e32 v0, vcc_lo, v146
	ds_read_b128 v[150:153], v0
	s_or_b32 s21, s13, s21
	v_add_u32_e32 v174, s21, v146
	ds_read_b128 v[154:157], v174 offset:32768
	ds_read_b128 v[158:161], v174 offset:34816
	ds_read_b128 v[162:165], v174 offset:36864
	ds_read_b128 v[166:169], v174 offset:38912
	s_mov_b32 m0, s72
	s_nop 0
	global_load_lds_dwordx4 v[144:145], off
	v_lshl_add_u64 v[144:145], v[144:145], 0, s[64:65]
	s_waitcnt lgkmcnt(0)
	v_mfma_f32_16x16x32_bf16 v[6:9], v[150:153], v[154:157], v[6:9]
	ds_read_b128 v[170:173], v0 offset:2048
	v_mfma_f32_16x16x32_bf16 v[14:17], v[150:153], v[158:161], v[14:17]
	v_mfma_f32_16x16x32_bf16 v[22:25], v[150:153], v[162:165], v[22:25]
	v_mfma_f32_16x16x32_bf16 v[30:33], v[150:153], v[166:169], v[30:33]
	s_waitcnt lgkmcnt(0)
	v_mfma_f32_16x16x32_bf16 v[18:21], v[170:173], v[154:157], v[18:21]
	ds_read_b128 v[150:153], v0 offset:4096
	s_add_i32 m0, s72, 0x8000
	s_nop 0
	global_load_lds_dwordx4 v[142:143], off
	v_lshl_add_u64 v[142:143], v[142:143], 0, s[64:65]
	v_mfma_f32_16x16x32_bf16 v[26:29], v[170:173], v[158:161], v[26:29]
	v_mfma_f32_16x16x32_bf16 v[38:41], v[170:173], v[162:165], v[38:41]
	v_mfma_f32_16x16x32_bf16 v[46:49], v[170:173], v[166:169], v[46:49]
	s_waitcnt lgkmcnt(0)
	v_mfma_f32_16x16x32_bf16 v[34:37], v[150:153], v[154:157], v[34:37]
	ds_read_b128 v[170:173], v0 offset:6144
	s_add_i32 m0, s72, 0x2000
	s_nop 0
	global_load_lds_dwordx4 v[140:141], off
	v_lshl_add_u64 v[140:141], v[140:141], 0, s[64:65]
	v_mfma_f32_16x16x32_bf16 v[42:45], v[150:153], v[158:161], v[42:45]
	v_mfma_f32_16x16x32_bf16 v[54:57], v[150:153], v[162:165], v[54:57]
	v_mfma_f32_16x16x32_bf16 v[62:65], v[150:153], v[166:169], v[62:65]
	s_waitcnt lgkmcnt(0)
	v_mfma_f32_16x16x32_bf16 v[50:53], v[170:173], v[154:157], v[50:53]
	ds_read_b128 v[150:153], v0 offset:8192
	s_add_i32 m0, s72, 0xa000
	s_nop 0
	global_load_lds_dwordx4 v[138:139], off
	v_lshl_add_u64 v[138:139], v[138:139], 0, s[64:65]
	v_mfma_f32_16x16x32_bf16 v[58:61], v[170:173], v[158:161], v[58:61]
	v_mfma_f32_16x16x32_bf16 v[70:73], v[170:173], v[162:165], v[70:73]
	v_mfma_f32_16x16x32_bf16 v[74:77], v[170:173], v[166:169], v[74:77]
	s_waitcnt lgkmcnt(0)
	v_mfma_f32_16x16x32_bf16 v[66:69], v[150:153], v[154:157], v[66:69]
	ds_read_b128 v[170:173], v0 offset:10240
	s_add_i32 m0, s72, 0x4000
	s_nop 0
	global_load_lds_dwordx4 v[136:137], off
	v_lshl_add_u64 v[136:137], v[136:137], 0, s[64:65]
	v_mfma_f32_16x16x32_bf16 v[10:13], v[150:153], v[158:161], v[10:13]
	v_mfma_f32_16x16x32_bf16 v[2:5], v[150:153], v[162:165], v[2:5]
	v_mfma_f32_16x16x32_bf16 v[78:81], v[150:153], v[166:169], v[78:81]
	s_waitcnt lgkmcnt(0)
	v_mfma_f32_16x16x32_bf16 v[82:85], v[170:173], v[154:157], v[82:85]
	ds_read_b128 v[150:153], v0 offset:12288
	s_add_i32 m0, s72, 0xc000
	s_nop 0
	global_load_lds_dwordx4 v[134:135], off
	v_lshl_add_u64 v[134:135], v[134:135], 0, s[64:65]
	v_mfma_f32_16x16x32_bf16 v[86:89], v[170:173], v[158:161], v[86:89]
	v_mfma_f32_16x16x32_bf16 v[94:97], v[170:173], v[162:165], v[94:97]
	v_mfma_f32_16x16x32_bf16 v[98:101], v[170:173], v[166:169], v[98:101]
	s_waitcnt lgkmcnt(0)
	v_mfma_f32_16x16x32_bf16 v[90:93], v[150:153], v[154:157], v[90:93]
	ds_read_b128 v[170:173], v0 offset:14336
	s_add_i32 m0, s72, 0x6000
	s_nop 0
	global_load_lds_dwordx4 v[132:133], off
	v_lshl_add_u64 v[132:133], v[132:133], 0, s[64:65]
	v_mfma_f32_16x16x32_bf16 v[102:105], v[150:153], v[158:161], v[102:105]
	v_mfma_f32_16x16x32_bf16 v[122:125], v[150:153], v[162:165], v[122:125]
	v_mfma_f32_16x16x32_bf16 v[110:113], v[150:153], v[166:169], v[110:113]
	s_waitcnt lgkmcnt(0)
	v_mfma_f32_16x16x32_bf16 v[106:109], v[170:173], v[154:157], v[106:109]
	s_add_i32 m0, s72, 0xe000
	s_nop 0
	global_load_lds_dwordx4 v[130:131], off
	v_lshl_add_u64 v[130:131], v[130:131], 0, s[64:65]
	v_mfma_f32_16x16x32_bf16 v[114:117], v[170:173], v[158:161], v[114:117]
	v_mfma_f32_16x16x32_bf16 v[126:129], v[170:173], v[162:165], v[126:129]
	v_mfma_f32_16x16x32_bf16 v[118:121], v[170:173], v[166:169], v[118:121]
	ds_read_b128 v[150:153], v0 offset:1024
	ds_read_b128 v[154:157], v174 offset:33792
	ds_read_b128 v[158:161], v174 offset:35840
	ds_read_b128 v[162:165], v174 offset:37888
	ds_read_b128 v[166:169], v174 offset:39936
	s_waitcnt lgkmcnt(0)
	v_mfma_f32_16x16x32_bf16 v[6:9], v[150:153], v[154:157], v[6:9]
	ds_read_b128 v[170:173], v0 offset:3072
	v_mfma_f32_16x16x32_bf16 v[14:17], v[150:153], v[158:161], v[14:17]
	v_mfma_f32_16x16x32_bf16 v[22:25], v[150:153], v[162:165], v[22:25]
	v_mfma_f32_16x16x32_bf16 v[30:33], v[150:153], v[166:169], v[30:33]
	s_waitcnt lgkmcnt(0)
	v_mfma_f32_16x16x32_bf16 v[18:21], v[170:173], v[154:157], v[18:21]
	ds_read_b128 v[150:153], v0 offset:5120
	v_mfma_f32_16x16x32_bf16 v[26:29], v[170:173], v[158:161], v[26:29]
	v_mfma_f32_16x16x32_bf16 v[38:41], v[170:173], v[162:165], v[38:41]
	v_mfma_f32_16x16x32_bf16 v[46:49], v[170:173], v[166:169], v[46:49]
	s_waitcnt lgkmcnt(0)
	v_mfma_f32_16x16x32_bf16 v[34:37], v[150:153], v[154:157], v[34:37]
	ds_read_b128 v[170:173], v0 offset:7168
	v_mfma_f32_16x16x32_bf16 v[42:45], v[150:153], v[158:161], v[42:45]
	v_mfma_f32_16x16x32_bf16 v[54:57], v[150:153], v[162:165], v[54:57]
	v_mfma_f32_16x16x32_bf16 v[62:65], v[150:153], v[166:169], v[62:65]
	s_waitcnt lgkmcnt(0)
	v_mfma_f32_16x16x32_bf16 v[50:53], v[170:173], v[154:157], v[50:53]
	ds_read_b128 v[150:153], v0 offset:9216
	v_mfma_f32_16x16x32_bf16 v[58:61], v[170:173], v[158:161], v[58:61]
	v_mfma_f32_16x16x32_bf16 v[70:73], v[170:173], v[162:165], v[70:73]
	v_mfma_f32_16x16x32_bf16 v[74:77], v[170:173], v[166:169], v[74:77]
	s_waitcnt lgkmcnt(0)
; #define WAIT_V0() asm volatile("s_waitcnt vmcnt(0)" ::: "memory")
; DI void gemm_core(const int tid, const u16* __restrict__ Wb, int ldw, const u16* __restrict__ Xb, int ldx, int K, f32x4 (&acc)[8][4], const bool pre = false) {
;     ...
;     for (int ks = 0; ks < 2; ++ks) {
;       bf16x8 At[8], Bf[4];
;       const char* pb = shm + cur * STAGE_B + TILE_B + lds_byte(wc * 64 + fr, fq * 8) + ks * 1024;
;       const char* pa = shm + cur * STAGE_B + lds_byte(wr * 128 + fr, fq * 8) + ks * 1024;
; #pragma unroll
;       for (int n = 0; n < 4; ++n) Bf[n] = *(const bf16x8*)(pb + n * 2048);
; #pragma unroll
;       for (int m = 0; m < 8; ++m) At[m] = *(const bf16x8*)(pa + m * 2048);
; #pragma unroll
;       for (int m = 0; m < 8; ++m)
; #pragma unroll
;         for (int n = 0; n < 4; ++n)
;           acc[m][n] = __builtin_amdgcn_mfma_f32_16x16x32_bf16(At[m], Bf[n], acc[m][n], 0, 0, 0);
;       __builtin_amdgcn_sched_group_barrier(0x100, 5, 0);
; #pragma unroll
;       for (int m = 0; m < 8; ++m) {
;         __builtin_amdgcn_sched_group_barrier(0x008, 1, 0);
;         if (m < 7) __builtin_amdgcn_sched_group_barrier(0x100, 1, 0);
;         __builtin_amdgcn_sched_group_barrier(0x008, 3, 0);
;       }
;       __builtin_amdgcn_sched_barrier(0);
;     }
;     WAIT_V0(); __syncthreads();
	v_mfma_f32_16x16x32_bf16 v[66:69], v[150:153], v[154:157], v[66:69]
	ds_read_b128 v[170:173], v0 offset:11264
	v_mfma_f32_16x16x32_bf16 v[10:13], v[150:153], v[158:161], v[10:13]
	v_mfma_f32_16x16x32_bf16 v[2:5], v[150:153], v[162:165], v[2:5]
	v_mfma_f32_16x16x32_bf16 v[78:81], v[150:153], v[166:169], v[78:81]
	s_waitcnt lgkmcnt(0)
	v_mfma_f32_16x16x32_bf16 v[82:85], v[170:173], v[154:157], v[82:85]
	ds_read_b128 v[150:153], v0 offset:13312
	v_mfma_f32_16x16x32_bf16 v[86:89], v[170:173], v[158:161], v[86:89]
	v_mfma_f32_16x16x32_bf16 v[94:97], v[170:173], v[162:165], v[94:97]
	v_mfma_f32_16x16x32_bf16 v[98:101], v[170:173], v[166:169], v[98:101]
	s_waitcnt lgkmcnt(0)
	v_mfma_f32_16x16x32_bf16 v[90:93], v[150:153], v[154:157], v[90:93]
	ds_read_b128 v[170:173], v0 offset:15360
	v_mfma_f32_16x16x32_bf16 v[102:105], v[150:153], v[158:161], v[102:105]
	v_mfma_f32_16x16x32_bf16 v[122:125], v[150:153], v[162:165], v[122:125]
	v_mfma_f32_16x16x32_bf16 v[110:113], v[150:153], v[166:169], v[110:113]
	s_waitcnt lgkmcnt(0)
	v_mfma_f32_16x16x32_bf16 v[106:109], v[170:173], v[154:157], v[106:109]
	v_mfma_f32_16x16x32_bf16 v[114:117], v[170:173], v[158:161], v[114:117]
	v_mfma_f32_16x16x32_bf16 v[126:129], v[170:173], v[162:165], v[126:129]
	v_mfma_f32_16x16x32_bf16 v[118:121], v[170:173], v[166:169], v[118:121]
	s_add_i32 s17, s17, 0x10000
	s_waitcnt vmcnt(0)
	s_add_u32 s30, s30, 0x80
	s_addc_u32 s31, s31, 0
	s_cmpk_lg_i32 s30, 0x380
	s_waitcnt vmcnt(0)
	s_barrier
	s_cbranch_scc1 .LBB0_219
	v_add_u32_e32 v0, s15, v146
	v_add_u32_e32 v0, 0x10000, v0
	ds_read_b128 v[142:145], v0 offset:14336
	ds_read_b128 v[152:155], v0 offset:12288
	ds_read_b128 v[156:159], v0 offset:10240
	v_or_b32_e32 v150, 0x18000, v146
	v_add_u32_e32 v151, s13, v150
	ds_read_b128 v[160:163], v0 offset:8192
	ds_read_b128 v[164:167], v0 offset:6144
	ds_read_b128 v[168:171], v151 offset:4096
	s_waitcnt lgkmcnt(0)
	v_mfma_f32_16x16x32_bf16 v[130:133], v[142:145], v[168:171], v[126:129]
	v_mfma_f32_16x16x32_bf16 v[134:137], v[152:155], v[168:171], v[122:125]
	v_mfma_f32_16x16x32_bf16 v[176:179], v[156:159], v[168:171], v[94:97]
	s_nop 1
	ds_read_b128 v[122:125], v151 offset:2048
	s_waitcnt lgkmcnt(0)
	v_mfma_f32_16x16x32_bf16 v[10:13], v[160:163], v[122:125], v[10:13]
	ds_read_b128 v[126:129], v0 offset:4096
	s_waitcnt lgkmcnt(0)
	v_mfma_f32_16x16x32_bf16 v[54:57], v[126:129], v[168:171], v[54:57]
	ds_read_b128 v[94:97], v151
	s_waitcnt lgkmcnt(0)
	v_mfma_f32_16x16x32_bf16 v[34:37], v[126:129], v[94:97], v[34:37]
	v_mfma_f32_16x16x32_bf16 v[50:53], v[164:167], v[94:97], v[50:53]
	v_mfma_f32_16x16x32_bf16 v[172:175], v[142:145], v[122:125], v[114:117]
	v_mfma_f32_16x16x32_bf16 v[184:187], v[152:155], v[122:125], v[102:105]
	s_nop 1
	ds_read_b128 v[114:117], v151 offset:6144
	s_waitcnt lgkmcnt(0)
	v_mfma_f32_16x16x32_bf16 v[110:113], v[152:155], v[114:117], v[110:113]
	v_mfma_f32_16x16x32_bf16 v[138:141], v[142:145], v[114:117], v[118:121]
	v_mfma_f32_16x16x32_bf16 v[180:183], v[156:159], v[114:117], v[98:101]
	s_nop 1
	ds_read_b128 v[118:121], v0 offset:2048
	s_waitcnt lgkmcnt(0)
	v_mfma_f32_16x16x32_bf16 v[18:21], v[118:121], v[94:97], v[18:21]
	v_mfma_f32_16x16x32_bf16 v[142:145], v[142:145], v[94:97], v[106:109]
	v_mfma_f32_16x16x32_bf16 v[82:85], v[156:159], v[94:97], v[82:85]
	v_mfma_f32_16x16x32_bf16 v[152:155], v[152:155], v[94:97], v[90:93]
	ds_read_b128 v[98:101], v0
	s_waitcnt lgkmcnt(0)
	v_mfma_f32_16x16x32_bf16 v[6:9], v[98:101], v[94:97], v[6:9]
	v_mfma_f32_16x16x32_bf16 v[94:97], v[160:163], v[94:97], v[66:69]
	v_mfma_f32_16x16x32_bf16 v[86:89], v[156:159], v[122:125], v[86:89]
	v_mfma_f32_16x16x32_bf16 v[102:105], v[164:167], v[168:171], v[70:73]
	v_mfma_f32_16x16x32_bf16 v[42:45], v[126:129], v[122:125], v[42:45]
	v_mfma_f32_16x16x32_bf16 v[46:49], v[118:121], v[114:117], v[46:49]
	v_mfma_f32_16x16x32_bf16 v[38:41], v[118:121], v[168:171], v[38:41]
	v_mfma_f32_16x16x32_bf16 v[26:29], v[118:121], v[122:125], v[26:29]
	v_mfma_f32_16x16x32_bf16 v[106:109], v[160:163], v[114:117], v[78:81]
	v_mfma_f32_16x16x32_bf16 v[30:33], v[98:101], v[114:117], v[30:33]
	v_mfma_f32_16x16x32_bf16 v[78:81], v[126:129], v[114:117], v[62:65]
	v_mfma_f32_16x16x32_bf16 v[90:93], v[164:167], v[114:117], v[74:77]
	v_mfma_f32_16x16x32_bf16 v[22:25], v[98:101], v[168:171], v[22:25]
	v_mfma_f32_16x16x32_bf16 v[14:17], v[98:101], v[122:125], v[14:17]
	v_mfma_f32_16x16x32_bf16 v[114:117], v[164:167], v[122:125], v[58:61]
	v_mfma_f32_16x16x32_bf16 v[98:101], v[160:163], v[168:171], v[2:5]
	ds_read_b128 v[62:65], v0 offset:1024
	ds_read_b128 v[156:159], v151 offset:1024
	ds_read_b128 v[160:163], v151 offset:3072
	ds_read_b128 v[164:167], v151 offset:5120
	ds_read_b128 v[168:171], v151 offset:7168
	s_waitcnt lgkmcnt(3)
	v_mfma_f32_16x16x32_bf16 v[2:5], v[62:65], v[156:159], v[6:9]
	ds_read_b128 v[66:69], v0 offset:3072
	s_waitcnt lgkmcnt(3)
	v_mfma_f32_16x16x32_bf16 v[58:61], v[62:65], v[160:163], v[14:17]
	s_waitcnt lgkmcnt(2)
	v_mfma_f32_16x16x32_bf16 v[122:125], v[62:65], v[164:167], v[22:25]
	s_waitcnt lgkmcnt(1)
	v_mfma_f32_16x16x32_bf16 v[70:73], v[62:65], v[168:171], v[30:33]
	s_waitcnt lgkmcnt(0)
	v_mfma_f32_16x16x32_bf16 v[6:9], v[66:69], v[156:159], v[18:21]
	ds_read_b128 v[14:17], v0 offset:5120
	v_mfma_f32_16x16x32_bf16 v[62:65], v[66:69], v[160:163], v[26:29]
	v_mfma_f32_16x16x32_bf16 v[126:129], v[66:69], v[164:167], v[38:41]
	v_mfma_f32_16x16x32_bf16 v[66:69], v[66:69], v[168:171], v[46:49]
	s_waitcnt lgkmcnt(0)
	v_mfma_f32_16x16x32_bf16 v[18:21], v[14:17], v[156:159], v[34:37]
	ds_read_b128 v[26:29], v0 offset:7168
	v_mfma_f32_16x16x32_bf16 v[74:77], v[14:17], v[160:163], v[42:45]
	v_mfma_f32_16x16x32_bf16 v[118:121], v[14:17], v[164:167], v[54:57]
	v_mfma_f32_16x16x32_bf16 v[54:57], v[14:17], v[168:171], v[78:81]
	s_waitcnt lgkmcnt(0)
; DI uint4 ld_nt16(const void* q) { const ntu4 t = __builtin_nontemporal_load((const ntu4*)q); uint4 v; v.x = t[0]; v.y = t[1]; v.z = t[2]; v.w = t[3]; return v; }
; DI int opaque_tid() { int t = threadIdx.x; asm volatile("" : "+v"(t)); return t; }
; DI int uni(int v) { return __builtin_amdgcn_readfirstlane(v); }
; DI float frcp(float x) { return __builtin_amdgcn_rcpf(x); }
; DI void gemm_stage0(const int tid, const u16* __restrict__ Wb, int ldw, const u16* __restrict__ Xb, int ldx) {
;   const int wid = uni(tid >> 6), lane = tid & 63;
; #pragma unroll
;   for (int i = 0; i < 4; ++i) {
;     int R, C; stage_rc(wid * 1024 + i * 8192 + lane * 16, R, C);
;     __builtin_amdgcn_global_load_lds((const unsigned*)(Wb + R * ldw + C), (unsigned*)(shm + wid * 1024 + i * 8192), 16, 0, 0);
;     __builtin_amdgcn_global_load_lds((const unsigned*)(Xb + R * ldx + C), (unsigned*)(shm + TILE_B + wid * 1024 + i * 8192), 16, 0, 0);
;   }
; template <int CT>
; DI void phase_g2(int c, int l) {
;     ...
;     gemm_stage0(tid, WSU(WbT) + ((size_t)l * 1024 + fbase) * 512, 512, WSU(GB) + (size_t)tbase * 512, 512);
;     { const int etid = opaque_tid(), wid = uni(etid >> 6), lane = etid & 63, wr = wid >> 2, wc = wid & 3, fr = lane & 15, fq = lane >> 4; (void)lane; (void)wr; (void)wc; (void)fr; (void)fq;
; #pragma unroll
;     for (int n = 0; n < 4; ++n) {
; #pragma unroll
;       for (int mp = 0; mp < 4; ++mp) {
;         const size_t fo = frag_off(pm, pn, wid, n, mp, lane);
;         float a8[8], b8[8];
;         unpack8(ld_nt16(WSU(MGA) + fo), a8); unpack8(ld_nt16(WSU(MGB) + fo), b8);
; #pragma unroll
;         for (int j = 0; j < 8; ++j) acc[mp * 2 + (j >> 2)][n][j & 3] *= (1.f + __expf(-b8[j])) * frcp(1.f + __expf(-a8[j]));
	v_mfma_f32_16x16x32_bf16 v[22:25], v[26:29], v[156:159], v[50:53]
	ds_read_b128 v[14:17], v0 offset:9216
	v_mfma_f32_16x16x32_bf16 v[78:81], v[26:29], v[160:163], v[114:117]
	v_mfma_f32_16x16x32_bf16 v[114:117], v[26:29], v[164:167], v[102:105]
	v_mfma_f32_16x16x32_bf16 v[50:53], v[26:29], v[168:171], v[90:93]
	s_waitcnt lgkmcnt(0)
	v_mfma_f32_16x16x32_bf16 v[26:29], v[14:17], v[156:159], v[94:97]
	ds_read_b128 v[34:37], v0 offset:11264
	v_mfma_f32_16x16x32_bf16 v[90:93], v[14:17], v[160:163], v[10:13]
	v_mfma_f32_16x16x32_bf16 v[102:105], v[14:17], v[164:167], v[98:101]
	v_mfma_f32_16x16x32_bf16 v[38:41], v[14:17], v[168:171], v[106:109]
	s_waitcnt lgkmcnt(0)
	v_mfma_f32_16x16x32_bf16 v[30:33], v[34:37], v[156:159], v[82:85]
	ds_read_b128 v[10:13], v0 offset:13312
	v_mfma_f32_16x16x32_bf16 v[94:97], v[34:37], v[160:163], v[86:89]
	v_mfma_f32_16x16x32_bf16 v[98:101], v[34:37], v[164:167], v[176:179]
	v_mfma_f32_16x16x32_bf16 v[34:37], v[34:37], v[168:171], v[180:183]
	s_waitcnt lgkmcnt(0)
	v_mfma_f32_16x16x32_bf16 v[42:45], v[10:13], v[156:159], v[152:155]
	s_nop 2
	ds_read_b128 v[152:155], v0 offset:15360
	v_mfma_f32_16x16x32_bf16 v[106:109], v[10:13], v[160:163], v[184:187]
	v_mfma_f32_16x16x32_bf16 v[86:89], v[10:13], v[164:167], v[134:137]
	v_mfma_f32_16x16x32_bf16 v[14:17], v[10:13], v[168:171], v[110:113]
	s_waitcnt lgkmcnt(0)
	v_mfma_f32_16x16x32_bf16 v[46:49], v[152:155], v[156:159], v[142:145]
	v_mfma_f32_16x16x32_bf16 v[110:113], v[152:155], v[160:163], v[172:175]
	v_mfma_f32_16x16x32_bf16 v[82:85], v[152:155], v[164:167], v[130:133]
	v_mfma_f32_16x16x32_bf16 v[10:13], v[152:155], v[168:171], v[138:141]
	s_add_u32 s26, s45, s26
	s_addc_u32 s27, s46, s27
	s_lshl_b64 s[28:29], s[28:29], 1
	s_add_u32 s28, s47, s28
	v_readfirstlane_b32 s1, v192
	s_addc_u32 s29, s50, s29
	s_lshr_b32 s17, s1, 1
	v_and_or_b32 v0, s17, 32, v147
	s_lshr_b32 s21, s1, 3
	v_lshlrev_b32_e32 v0, 1, v0
	s_and_b32 s21, s21, 0x7ffff0
	v_lshl_add_u64 v[130:131], s[26:27], 0, v[0:1]
	v_lshl_add_u64 v[132:133], s[28:29], 0, v[0:1]
	v_or_b32_e32 v0, s21, v196
	v_lshlrev_b32_e32 v134, 9, v0
	s_lshl_b32 s13, s1, 4
	v_ashrrev_i32_e32 v135, 31, v134
	s_and_b32 s15, s13, 0xfffffc00
	v_lshlrev_b64 v[134:135], 1, v[134:135]
	s_add_i32 s17, s15, 0x8000
	v_lshl_add_u64 v[136:137], v[130:131], 0, v[134:135]
	s_mov_b32 m0, s15
	s_waitcnt vmcnt(0)
	s_barrier
	global_load_lds_dwordx4 v[136:137], off
	s_mov_b32 m0, s17
	s_add_i32 s17, s13, 0x2000
	s_lshr_b32 s17, s17, 7
	s_and_b32 s17, s17, 0x7ffff0
	v_lshl_add_u64 v[134:135], v[132:133], 0, v[134:135]
	v_or_b32_e32 v0, s17, v196
	global_load_lds_dwordx4 v[134:135], off
	v_lshlrev_b32_e32 v134, 9, v0
	v_ashrrev_i32_e32 v135, 31, v134
	s_add_i32 s17, s13, 0x4000
	v_lshlrev_b64 v[134:135], 1, v[134:135]
	s_lshr_b32 s17, s17, 7
	v_lshl_add_u64 v[136:137], v[130:131], 0, v[134:135]
	s_add_i32 m0, s15, 0x2000
	s_and_b32 s17, s17, 0x7ffff0
	global_load_lds_dwordx4 v[136:137], off
	v_lshl_add_u64 v[134:135], v[132:133], 0, v[134:135]
	s_add_i32 m0, s15, 0xa000
	v_or_b32_e32 v0, s17, v196
	global_load_lds_dwordx4 v[134:135], off
	v_lshlrev_b32_e32 v134, 9, v0
	v_ashrrev_i32_e32 v135, 31, v134
	s_addk_i32 s13, 0x6000
	v_lshlrev_b64 v[134:135], 1, v[134:135]
	s_lshr_b32 s13, s13, 7
	v_lshl_add_u64 v[136:137], v[130:131], 0, v[134:135]
	s_add_i32 m0, s15, 0x4000
	s_and_b32 s13, s13, 0x7ffff0
	global_load_lds_dwordx4 v[136:137], off
	v_lshl_add_u64 v[134:135], v[132:133], 0, v[134:135]
	s_add_i32 m0, s15, 0xc000
	v_or_b32_e32 v0, s13, v196
	global_load_lds_dwordx4 v[134:135], off
	v_lshlrev_b32_e32 v134, 9, v0
	v_ashrrev_i32_e32 v135, 31, v134
	v_lshlrev_b64 v[134:135], 1, v[134:135]
	v_lshl_add_u64 v[130:131], v[130:131], 0, v[134:135]
	s_add_i32 m0, s15, 0x6000
	v_mov_b32_e32 v0, v210
	global_load_lds_dwordx4 v[130:131], off
	v_lshl_add_u64 v[130:131], v[132:133], 0, v[134:135]
	s_add_i32 m0, s15, 0xe000
	s_ashr_i32 s15, s14, 31
	global_load_lds_dwordx4 v[130:131], off
	s_lshl_b64 s[28:29], s[14:15], 3
	v_readfirstlane_b32 s13, v0
	s_ashr_i32 s17, s13, 6
	s_ashr_i32 s13, s12, 31
	s_lshl_b64 s[26:27], s[12:13], 5
	s_add_u32 s13, s28, s26
	s_addc_u32 s15, s29, s27
	s_ashr_i32 s21, s17, 31
	s_add_u32 s26, s13, s17
	s_addc_u32 s27, s15, s21
	v_lshlrev_b32_e32 v0, 4, v0
	s_lshl_b64 s[26:27], s[26:27], 14
	v_and_b32_e32 v0, 0x3f0, v0
	v_or_b32_e32 v130, s26, v0
	v_mov_b32_e32 v131, s27
	v_mov_b32_e32 v222, v130
	v_mov_b32_e32 v223, s27
	v_lshl_add_u64 v[228:229], s[6:7], 0, v[222:223]
	global_load_dwordx4 v[156:159], v[228:229], off nt
	v_lshl_add_u64 v[228:229], s[8:9], 0, v[222:223]
	global_load_dwordx4 v[160:163], v[228:229], off
	v_or_b32_e32 v222, 0x400, v130
	v_mov_b32_e32 v223, s27
	v_lshl_add_u64 v[228:229], s[6:7], 0, v[222:223]
	global_load_dwordx4 v[164:167], v[228:229], off nt
	v_lshl_add_u64 v[228:229], s[8:9], 0, v[222:223]
	global_load_dwordx4 v[168:171], v[228:229], off
	v_or_b32_e32 v222, 0x800, v130
	v_mov_b32_e32 v223, s27
	v_lshl_add_u64 v[228:229], s[6:7], 0, v[222:223]
	global_load_dwordx4 v[172:175], v[228:229], off nt
	v_lshl_add_u64 v[228:229], s[8:9], 0, v[222:223]
	global_load_dwordx4 v[232:235], v[228:229], off
	v_or_b32_e32 v222, 0xc00, v130
	v_mov_b32_e32 v223, s27
	v_lshl_add_u64 v[228:229], s[6:7], 0, v[222:223]
	global_load_dwordx4 v[236:239], v[228:229], off nt
	v_lshl_add_u64 v[228:229], s[8:9], 0, v[222:223]
	global_load_dwordx4 v[240:243], v[228:229], off
	v_or_b32_e32 v222, 0x1000, v130
	v_mov_b32_e32 v223, s27
	v_lshl_add_u64 v[228:229], s[6:7], 0, v[222:223]
	global_load_dwordx4 v[244:247], v[228:229], off nt
	v_lshl_add_u64 v[228:229], s[8:9], 0, v[222:223]
	global_load_dwordx4 v[248:251], v[228:229], off
	v_or_b32_e32 v222, 0x1400, v130
	v_mov_b32_e32 v223, s27
	v_lshl_add_u64 v[228:229], s[6:7], 0, v[222:223]
	global_load_dwordx4 v[216:219], v[228:229], off nt
	v_lshl_add_u64 v[228:229], s[8:9], 0, v[222:223]
	global_load_dwordx4 v[224:227], v[228:229], off
	s_ashr_i32 s21, s1, 6
	s_lshl_b32 s26, s21, 5
	s_lshl_b32 s1, s1, 7
	s_lshl_b32 s17, s21, 10
	s_and_b32 s26, s26, 32
	s_and_b32 s1, s1, 0x6000
	s_movk_i32 s89, 0x1000
	s_waitcnt vmcnt(11)
; DI uint4 ld_nt16(const void* q) { const ntu4 t = __builtin_nontemporal_load((const ntu4*)q); uint4 v; v.x = t[0]; v.y = t[1]; v.z = t[2]; v.w = t[3]; return v; }
; DI float frcp(float x) { return __builtin_amdgcn_rcpf(x); }
; template <int CT>
; DI void phase_g2(int c, int l) {
;     ...
; #pragma unroll
;     for (int n = 0; n < 4; ++n) {
; #pragma unroll
;       for (int mp = 0; mp < 4; ++mp) {
;         const size_t fo = frag_off(pm, pn, wid, n, mp, lane);
;         float a8[8], b8[8];
;         unpack8(ld_nt16(WSU(MGA) + fo), a8); unpack8(ld_nt16(WSU(MGB) + fo), b8);
; #pragma unroll
;         for (int j = 0; j < 8; ++j) acc[mp * 2 + (j >> 2)][n][j & 3] *= (1.f + __expf(-b8[j])) * frcp(1.f + __expf(-a8[j]));
;       }
	v_lshlrev_b32_e32 v0, 16, v156
	v_and_b32_e32 v136, 0xffff0000, v156
	v_lshlrev_b32_e32 v137, 16, v157
	v_and_b32_e32 v139, 0xffff0000, v157
	v_lshlrev_b32_e32 v140, 16, v158
	v_and_b32_e32 v141, 0xffff0000, v158
	v_lshlrev_b32_e32 v142, 16, v159
	v_and_b32_e32 v143, 0xffff0000, v159
	v_mul_f32_e32 v0, 0xbfb8aa3b, v0
	v_exp_f32_e32 v0, v0
	s_waitcnt vmcnt(10)
	v_and_b32_e32 v144, 0xffff0000, v160
	v_add_f32_e32 v0, 1.0, v0
	v_lshlrev_b32_e32 v152, 16, v162
	v_and_b32_e32 v153, 0xffff0000, v162
	v_rcp_f32_e32 v134, v0
	v_mul_f32_e32 v0, 0xbfb8aa3b, v144
	v_lshlrev_b32_e32 v145, 16, v161
	v_and_b32_e32 v151, 0xffff0000, v161
	v_exp_f32_e32 v133, v0
	v_mul_f32_e32 v0, 0xbfb8aa3b, v136
	v_exp_f32_e32 v0, v0
	v_lshlrev_b32_e32 v154, 16, v163
	v_and_b32_e32 v155, 0xffff0000, v163
	v_lshlrev_b32_e32 v138, 16, v160
	v_add_f32_e32 v0, 1.0, v0
	v_rcp_f32_e32 v135, v0
	v_mul_f32_e32 v0, 0xbfb8aa3b, v145
	v_exp_f32_e32 v136, v0
	v_mul_f32_e32 v0, 0xbfb8aa3b, v137
	v_exp_f32_e32 v0, v0
	v_mul_f32_e32 v132, 0xbfb8aa3b, v138
	v_exp_f32_e32 v132, v132
	v_add_f32_e32 v0, 1.0, v0
	v_rcp_f32_e32 v138, v0
	v_mul_f32_e32 v0, 0xbfb8aa3b, v151
	v_exp_f32_e32 v137, v0
	v_mul_f32_e32 v0, 0xbfb8aa3b, v139
	v_exp_f32_e32 v0, v0
	v_pk_add_f32 v[132:133], v[132:133], 1.0 op_sel_hi:[1,0]
	v_pk_add_f32 v[136:137], v[136:137], 1.0 op_sel_hi:[1,0]
	v_pk_mul_f32 v[132:133], v[132:133], v[134:135]
	v_add_f32_e32 v0, 1.0, v0
	v_rcp_f32_e32 v139, v0
	v_mul_f32_e32 v0, 0xbfb8aa3b, v152
	v_pk_mul_f32 v[2:3], v[2:3], v[132:133]
	v_exp_f32_e32 v132, v0
	v_mul_f32_e32 v0, 0xbfb8aa3b, v140
	v_exp_f32_e32 v0, v0
	v_pk_mul_f32 v[134:135], v[136:137], v[138:139]
	v_add_f32_e32 v0, 1.0, v0
	v_pk_mul_f32 v[4:5], v[4:5], v[134:135]
	v_rcp_f32_e32 v134, v0
	v_mul_f32_e32 v0, 0xbfb8aa3b, v153
	v_exp_f32_e32 v133, v0
	v_mul_f32_e32 v0, 0xbfb8aa3b, v141
	v_exp_f32_e32 v0, v0
	v_pk_add_f32 v[132:133], v[132:133], 1.0 op_sel_hi:[1,0]
	v_add_f32_e32 v0, 1.0, v0
	v_rcp_f32_e32 v135, v0
	v_mul_f32_e32 v0, 0xbfb8aa3b, v154
	v_exp_f32_e32 v136, v0
	v_mul_f32_e32 v0, 0xbfb8aa3b, v142
	v_exp_f32_e32 v0, v0
	v_pk_mul_f32 v[132:133], v[132:133], v[134:135]
	v_add_f32_e32 v0, 1.0, v0
	v_rcp_f32_e32 v138, v0
	v_mul_f32_e32 v0, 0xbfb8aa3b, v155
	v_exp_f32_e32 v137, v0
	v_mul_f32_e32 v0, 0xbfb8aa3b, v143
	v_exp_f32_e32 v0, v0
	v_pk_mul_f32 v[6:7], v[6:7], v[132:133]
	v_pk_add_f32 v[136:137], v[136:137], 1.0 op_sel_hi:[1,0]
	v_add_f32_e32 v0, 1.0, v0
	v_rcp_f32_e32 v139, v0
	s_nop 0
	v_pk_mul_f32 v[134:135], v[136:137], v[138:139]
	v_or_b32_e32 v136, 0x400, v130
	v_mov_b32_e32 v137, s27
	v_pk_mul_f32 v[8:9], v[8:9], v[134:135]
	v_or_b32_e32 v222, 0x1800, v130
	v_mov_b32_e32 v223, s27
	v_lshl_add_u64 v[228:229], s[6:7], 0, v[222:223]
	global_load_dwordx4 v[156:159], v[228:229], off nt
	v_lshl_add_u64 v[228:229], s[8:9], 0, v[222:223]
	global_load_dwordx4 v[160:163], v[228:229], off
	s_waitcnt vmcnt(11)
	v_lshlrev_b32_e32 v0, 16, v164
	v_and_b32_e32 v138, 0xffff0000, v164
	v_lshlrev_b32_e32 v139, 16, v165
	v_and_b32_e32 v140, 0xffff0000, v165
	v_lshlrev_b32_e32 v141, 16, v166
	v_and_b32_e32 v142, 0xffff0000, v166
	v_lshlrev_b32_e32 v143, 16, v167
	v_and_b32_e32 v144, 0xffff0000, v167
	v_mul_f32_e32 v0, 0xbfb8aa3b, v0
	v_exp_f32_e32 v0, v0
	s_waitcnt vmcnt(10)
	v_and_b32_e32 v137, 0xffff0000, v168
	v_add_f32_e32 v0, 1.0, v0
	v_lshlrev_b32_e32 v152, 16, v170
	v_and_b32_e32 v153, 0xffff0000, v170
	v_rcp_f32_e32 v134, v0
	v_mul_f32_e32 v0, 0xbfb8aa3b, v137
	v_lshlrev_b32_e32 v145, 16, v169
	v_and_b32_e32 v151, 0xffff0000, v169
	v_exp_f32_e32 v133, v0
	v_mul_f32_e32 v0, 0xbfb8aa3b, v138
	v_exp_f32_e32 v0, v0
	v_lshlrev_b32_e32 v136, 16, v168
	v_lshlrev_b32_e32 v154, 16, v171
	v_and_b32_e32 v155, 0xffff0000, v171
	v_add_f32_e32 v0, 1.0, v0
	v_rcp_f32_e32 v135, v0
	v_mul_f32_e32 v0, 0xbfb8aa3b, v145
	v_mul_f32_e32 v132, 0xbfb8aa3b, v136
	v_exp_f32_e32 v136, v0
	v_mul_f32_e32 v0, 0xbfb8aa3b, v139
	v_exp_f32_e32 v0, v0
	v_exp_f32_e32 v132, v132
	v_add_f32_e32 v0, 1.0, v0
	v_rcp_f32_e32 v138, v0
	v_mul_f32_e32 v0, 0xbfb8aa3b, v151
	v_exp_f32_e32 v137, v0
	v_mul_f32_e32 v0, 0xbfb8aa3b, v140
	v_exp_f32_e32 v0, v0
	v_pk_add_f32 v[132:133], v[132:133], 1.0 op_sel_hi:[1,0]
	v_pk_add_f32 v[136:137], v[136:137], 1.0 op_sel_hi:[1,0]
	v_pk_mul_f32 v[132:133], v[132:133], v[134:135]
	v_add_f32_e32 v0, 1.0, v0
	v_rcp_f32_e32 v139, v0
	v_mul_f32_e32 v0, 0xbfb8aa3b, v152
	v_pk_mul_f32 v[18:19], v[18:19], v[132:133]
	v_exp_f32_e32 v132, v0
	v_mul_f32_e32 v0, 0xbfb8aa3b, v141
	v_exp_f32_e32 v0, v0
	v_pk_mul_f32 v[134:135], v[136:137], v[138:139]
	v_add_f32_e32 v0, 1.0, v0
	v_pk_mul_f32 v[20:21], v[20:21], v[134:135]
	v_rcp_f32_e32 v134, v0
	v_mul_f32_e32 v0, 0xbfb8aa3b, v153
	v_exp_f32_e32 v133, v0
	v_mul_f32_e32 v0, 0xbfb8aa3b, v142
	v_exp_f32_e32 v0, v0
	v_pk_add_f32 v[132:133], v[132:133], 1.0 op_sel_hi:[1,0]
	v_add_f32_e32 v0, 1.0, v0
	v_rcp_f32_e32 v135, v0
	v_mul_f32_e32 v0, 0xbfb8aa3b, v154
	v_exp_f32_e32 v136, v0
	v_mul_f32_e32 v0, 0xbfb8aa3b, v143
	v_exp_f32_e32 v0, v0
	v_pk_mul_f32 v[132:133], v[132:133], v[134:135]
	v_add_f32_e32 v0, 1.0, v0
	v_rcp_f32_e32 v138, v0
	v_mul_f32_e32 v0, 0xbfb8aa3b, v155
	v_exp_f32_e32 v137, v0
	v_mul_f32_e32 v0, 0xbfb8aa3b, v144
	v_exp_f32_e32 v0, v0
	v_pk_mul_f32 v[22:23], v[22:23], v[132:133]
	v_pk_add_f32 v[136:137], v[136:137], 1.0 op_sel_hi:[1,0]
	v_add_f32_e32 v0, 1.0, v0
	v_rcp_f32_e32 v139, v0
	s_nop 0
	v_pk_mul_f32 v[134:135], v[136:137], v[138:139]
	v_or_b32_e32 v136, 0x800, v130
	v_mov_b32_e32 v137, s27
	v_pk_mul_f32 v[24:25], v[24:25], v[134:135]
	v_or_b32_e32 v222, 0x1c00, v130
	v_mov_b32_e32 v223, s27
	v_lshl_add_u64 v[228:229], s[6:7], 0, v[222:223]
	global_load_dwordx4 v[164:167], v[228:229], off nt
	v_lshl_add_u64 v[228:229], s[8:9], 0, v[222:223]
	global_load_dwordx4 v[168:171], v[228:229], off
	s_waitcnt vmcnt(11)
; DI uint4 ld_nt16(const void* q) { const ntu4 t = __builtin_nontemporal_load((const ntu4*)q); uint4 v; v.x = t[0]; v.y = t[1]; v.z = t[2]; v.w = t[3]; return v; }
; DI float frcp(float x) { return __builtin_amdgcn_rcpf(x); }
; template <int CT>
; DI void phase_g2(int c, int l) {
;     ...
; #pragma unroll
;     for (int n = 0; n < 4; ++n) {
; #pragma unroll
;       for (int mp = 0; mp < 4; ++mp) {
;         const size_t fo = frag_off(pm, pn, wid, n, mp, lane);
;         float a8[8], b8[8];
;         unpack8(ld_nt16(WSU(MGA) + fo), a8); unpack8(ld_nt16(WSU(MGB) + fo), b8);
; #pragma unroll
;         for (int j = 0; j < 8; ++j) acc[mp * 2 + (j >> 2)][n][j & 3] *= (1.f + __expf(-b8[j])) * frcp(1.f + __expf(-a8[j]));
;       }
	v_lshlrev_b32_e32 v0, 16, v172
	v_and_b32_e32 v138, 0xffff0000, v172
	v_lshlrev_b32_e32 v139, 16, v173
	v_and_b32_e32 v140, 0xffff0000, v173
	v_lshlrev_b32_e32 v141, 16, v174
	v_and_b32_e32 v142, 0xffff0000, v174
	v_lshlrev_b32_e32 v143, 16, v175
	v_and_b32_e32 v144, 0xffff0000, v175
	v_mul_f32_e32 v0, 0xbfb8aa3b, v0
	v_exp_f32_e32 v0, v0
	s_waitcnt vmcnt(10)
	v_and_b32_e32 v137, 0xffff0000, v232
	v_add_f32_e32 v0, 1.0, v0
	v_lshlrev_b32_e32 v152, 16, v234
	v_and_b32_e32 v153, 0xffff0000, v234
	v_rcp_f32_e32 v134, v0
	v_mul_f32_e32 v0, 0xbfb8aa3b, v137
	v_lshlrev_b32_e32 v145, 16, v233
	v_and_b32_e32 v151, 0xffff0000, v233
	v_exp_f32_e32 v133, v0
	v_mul_f32_e32 v0, 0xbfb8aa3b, v138
	v_exp_f32_e32 v0, v0
	v_lshlrev_b32_e32 v136, 16, v232
	v_lshlrev_b32_e32 v154, 16, v235
	v_and_b32_e32 v155, 0xffff0000, v235
	v_add_f32_e32 v0, 1.0, v0
	v_rcp_f32_e32 v135, v0
	v_mul_f32_e32 v0, 0xbfb8aa3b, v145
	v_mul_f32_e32 v132, 0xbfb8aa3b, v136
	v_exp_f32_e32 v136, v0
	v_mul_f32_e32 v0, 0xbfb8aa3b, v139
	v_exp_f32_e32 v0, v0
	v_exp_f32_e32 v132, v132
	v_add_f32_e32 v0, 1.0, v0
	v_rcp_f32_e32 v138, v0
	v_mul_f32_e32 v0, 0xbfb8aa3b, v151
	v_exp_f32_e32 v137, v0
	v_mul_f32_e32 v0, 0xbfb8aa3b, v140
	v_exp_f32_e32 v0, v0
	v_pk_add_f32 v[132:133], v[132:133], 1.0 op_sel_hi:[1,0]
	v_pk_add_f32 v[136:137], v[136:137], 1.0 op_sel_hi:[1,0]
	v_pk_mul_f32 v[132:133], v[132:133], v[134:135]
	v_add_f32_e32 v0, 1.0, v0
	v_rcp_f32_e32 v139, v0
	v_mul_f32_e32 v0, 0xbfb8aa3b, v152
	v_pk_mul_f32 v[26:27], v[26:27], v[132:133]
	v_exp_f32_e32 v132, v0
	v_mul_f32_e32 v0, 0xbfb8aa3b, v141
	v_exp_f32_e32 v0, v0
	v_pk_mul_f32 v[134:135], v[136:137], v[138:139]
	v_add_f32_e32 v0, 1.0, v0
	v_pk_mul_f32 v[28:29], v[28:29], v[134:135]
	v_rcp_f32_e32 v134, v0
	v_mul_f32_e32 v0, 0xbfb8aa3b, v153
	v_exp_f32_e32 v133, v0
	v_mul_f32_e32 v0, 0xbfb8aa3b, v142
	v_exp_f32_e32 v0, v0
	v_pk_add_f32 v[132:133], v[132:133], 1.0 op_sel_hi:[1,0]
	v_add_f32_e32 v0, 1.0, v0
	v_rcp_f32_e32 v135, v0
	v_mul_f32_e32 v0, 0xbfb8aa3b, v154
	v_exp_f32_e32 v136, v0
	v_mul_f32_e32 v0, 0xbfb8aa3b, v143
	v_exp_f32_e32 v0, v0
	v_pk_mul_f32 v[132:133], v[132:133], v[134:135]
	v_add_f32_e32 v0, 1.0, v0
	v_rcp_f32_e32 v138, v0
	v_mul_f32_e32 v0, 0xbfb8aa3b, v155
	v_exp_f32_e32 v137, v0
	v_mul_f32_e32 v0, 0xbfb8aa3b, v144
	v_exp_f32_e32 v0, v0
	v_pk_mul_f32 v[30:31], v[30:31], v[132:133]
	v_pk_add_f32 v[136:137], v[136:137], 1.0 op_sel_hi:[1,0]
	v_add_f32_e32 v0, 1.0, v0
	v_rcp_f32_e32 v139, v0
	s_nop 0
	v_pk_mul_f32 v[134:135], v[136:137], v[138:139]
	v_or_b32_e32 v136, 0xc00, v130
	v_mov_b32_e32 v137, s27
	v_pk_mul_f32 v[32:33], v[32:33], v[134:135]
	v_or_b32_e32 v222, 0x2000, v130
	v_mov_b32_e32 v223, s27
	v_lshl_add_u64 v[228:229], s[6:7], 0, v[222:223]
	global_load_dwordx4 v[172:175], v[228:229], off nt
	v_lshl_add_u64 v[228:229], s[8:9], 0, v[222:223]
	global_load_dwordx4 v[232:235], v[228:229], off
	s_waitcnt vmcnt(11)
	v_lshlrev_b32_e32 v0, 16, v236
	v_and_b32_e32 v138, 0xffff0000, v236
	v_lshlrev_b32_e32 v139, 16, v237
	v_and_b32_e32 v140, 0xffff0000, v237
	v_lshlrev_b32_e32 v141, 16, v238
	v_and_b32_e32 v142, 0xffff0000, v238
	v_lshlrev_b32_e32 v143, 16, v239
	v_and_b32_e32 v144, 0xffff0000, v239
	v_mul_f32_e32 v0, 0xbfb8aa3b, v0
	v_exp_f32_e32 v0, v0
	s_waitcnt vmcnt(10)
	v_and_b32_e32 v137, 0xffff0000, v240
	v_add_f32_e32 v0, 1.0, v0
	v_lshlrev_b32_e32 v152, 16, v242
	v_and_b32_e32 v153, 0xffff0000, v242
	v_rcp_f32_e32 v134, v0
	v_mul_f32_e32 v0, 0xbfb8aa3b, v137
	v_lshlrev_b32_e32 v145, 16, v241
	v_and_b32_e32 v151, 0xffff0000, v241
	v_exp_f32_e32 v133, v0
	v_mul_f32_e32 v0, 0xbfb8aa3b, v138
	v_exp_f32_e32 v0, v0
	v_lshlrev_b32_e32 v136, 16, v240
	v_lshlrev_b32_e32 v154, 16, v243
	v_and_b32_e32 v155, 0xffff0000, v243
	v_add_f32_e32 v0, 1.0, v0
	v_rcp_f32_e32 v135, v0
	v_mul_f32_e32 v0, 0xbfb8aa3b, v145
	v_mul_f32_e32 v132, 0xbfb8aa3b, v136
	v_exp_f32_e32 v136, v0
	v_mul_f32_e32 v0, 0xbfb8aa3b, v139
	v_exp_f32_e32 v0, v0
	v_exp_f32_e32 v132, v132
	v_add_f32_e32 v0, 1.0, v0
	v_rcp_f32_e32 v138, v0
	v_mul_f32_e32 v0, 0xbfb8aa3b, v151
	v_exp_f32_e32 v137, v0
	v_mul_f32_e32 v0, 0xbfb8aa3b, v140
	v_exp_f32_e32 v0, v0
	v_pk_add_f32 v[132:133], v[132:133], 1.0 op_sel_hi:[1,0]
	v_pk_add_f32 v[136:137], v[136:137], 1.0 op_sel_hi:[1,0]
	v_pk_mul_f32 v[132:133], v[132:133], v[134:135]
	v_add_f32_e32 v0, 1.0, v0
	v_rcp_f32_e32 v139, v0
	v_mul_f32_e32 v0, 0xbfb8aa3b, v152
	v_pk_mul_f32 v[42:43], v[42:43], v[132:133]
	v_exp_f32_e32 v132, v0
	v_mul_f32_e32 v0, 0xbfb8aa3b, v141
	v_exp_f32_e32 v0, v0
	v_pk_mul_f32 v[134:135], v[136:137], v[138:139]
	v_add_f32_e32 v0, 1.0, v0
	v_pk_mul_f32 v[44:45], v[44:45], v[134:135]
	v_rcp_f32_e32 v134, v0
	v_mul_f32_e32 v0, 0xbfb8aa3b, v153
	v_exp_f32_e32 v133, v0
	v_mul_f32_e32 v0, 0xbfb8aa3b, v142
	v_exp_f32_e32 v0, v0
	v_pk_add_f32 v[132:133], v[132:133], 1.0 op_sel_hi:[1,0]
	v_add_f32_e32 v0, 1.0, v0
	v_rcp_f32_e32 v135, v0
	v_mul_f32_e32 v0, 0xbfb8aa3b, v154
	v_exp_f32_e32 v136, v0
	v_mul_f32_e32 v0, 0xbfb8aa3b, v143
	v_exp_f32_e32 v0, v0
	v_pk_mul_f32 v[132:133], v[132:133], v[134:135]
	v_add_f32_e32 v0, 1.0, v0
	v_rcp_f32_e32 v138, v0
	v_mul_f32_e32 v0, 0xbfb8aa3b, v155
	v_exp_f32_e32 v137, v0
	v_mul_f32_e32 v0, 0xbfb8aa3b, v144
	v_exp_f32_e32 v0, v0
	v_pk_mul_f32 v[46:47], v[46:47], v[132:133]
	v_pk_add_f32 v[136:137], v[136:137], 1.0 op_sel_hi:[1,0]
	v_add_f32_e32 v0, 1.0, v0
	v_rcp_f32_e32 v139, v0
	s_nop 0
	v_pk_mul_f32 v[134:135], v[136:137], v[138:139]
	v_or_b32_e32 v136, 0x1000, v130
	v_mov_b32_e32 v137, s27
	v_pk_mul_f32 v[48:49], v[48:49], v[134:135]
	v_or_b32_e32 v222, 0x2400, v130
	v_mov_b32_e32 v223, s27
	v_lshl_add_u64 v[228:229], s[6:7], 0, v[222:223]
	global_load_dwordx4 v[236:239], v[228:229], off nt
	v_lshl_add_u64 v[228:229], s[8:9], 0, v[222:223]
	global_load_dwordx4 v[240:243], v[228:229], off
	s_waitcnt vmcnt(11)
; DI uint4 ld_nt16(const void* q) { const ntu4 t = __builtin_nontemporal_load((const ntu4*)q); uint4 v; v.x = t[0]; v.y = t[1]; v.z = t[2]; v.w = t[3]; return v; }
; DI float frcp(float x) { return __builtin_amdgcn_rcpf(x); }
; template <int CT>
; DI void phase_g2(int c, int l) {
;     ...
; #pragma unroll
;     for (int n = 0; n < 4; ++n) {
; #pragma unroll
;       for (int mp = 0; mp < 4; ++mp) {
;         const size_t fo = frag_off(pm, pn, wid, n, mp, lane);
;         float a8[8], b8[8];
;         unpack8(ld_nt16(WSU(MGA) + fo), a8); unpack8(ld_nt16(WSU(MGB) + fo), b8);
; #pragma unroll
;         for (int j = 0; j < 8; ++j) acc[mp * 2 + (j >> 2)][n][j & 3] *= (1.f + __expf(-b8[j])) * frcp(1.f + __expf(-a8[j]));
;       }
	v_lshlrev_b32_e32 v0, 16, v244
	v_and_b32_e32 v138, 0xffff0000, v244
	v_lshlrev_b32_e32 v139, 16, v245
	v_and_b32_e32 v140, 0xffff0000, v245
	v_lshlrev_b32_e32 v141, 16, v246
	v_and_b32_e32 v142, 0xffff0000, v246
	v_lshlrev_b32_e32 v143, 16, v247
	v_and_b32_e32 v144, 0xffff0000, v247
	v_mul_f32_e32 v0, 0xbfb8aa3b, v0
	v_exp_f32_e32 v0, v0
	s_waitcnt vmcnt(10)
	v_and_b32_e32 v137, 0xffff0000, v248
	v_add_f32_e32 v0, 1.0, v0
	v_lshlrev_b32_e32 v152, 16, v250
	v_and_b32_e32 v153, 0xffff0000, v250
	v_rcp_f32_e32 v134, v0
	v_mul_f32_e32 v0, 0xbfb8aa3b, v137
	v_lshlrev_b32_e32 v145, 16, v249
	v_and_b32_e32 v151, 0xffff0000, v249
	v_exp_f32_e32 v133, v0
	v_mul_f32_e32 v0, 0xbfb8aa3b, v138
	v_exp_f32_e32 v0, v0
	v_lshlrev_b32_e32 v136, 16, v248
	v_lshlrev_b32_e32 v154, 16, v251
	v_and_b32_e32 v155, 0xffff0000, v251
	v_add_f32_e32 v0, 1.0, v0
	v_rcp_f32_e32 v135, v0
	v_mul_f32_e32 v0, 0xbfb8aa3b, v145
	v_mul_f32_e32 v132, 0xbfb8aa3b, v136
	v_exp_f32_e32 v136, v0
	v_mul_f32_e32 v0, 0xbfb8aa3b, v139
	v_exp_f32_e32 v0, v0
	v_exp_f32_e32 v132, v132
	v_add_f32_e32 v0, 1.0, v0
	v_rcp_f32_e32 v138, v0
	v_mul_f32_e32 v0, 0xbfb8aa3b, v151
	v_exp_f32_e32 v137, v0
	v_mul_f32_e32 v0, 0xbfb8aa3b, v140
	v_exp_f32_e32 v0, v0
	v_pk_add_f32 v[132:133], v[132:133], 1.0 op_sel_hi:[1,0]
	v_pk_add_f32 v[136:137], v[136:137], 1.0 op_sel_hi:[1,0]
	v_pk_mul_f32 v[132:133], v[132:133], v[134:135]
	v_add_f32_e32 v0, 1.0, v0
	v_rcp_f32_e32 v139, v0
	v_mul_f32_e32 v0, 0xbfb8aa3b, v152
	v_pk_mul_f32 v[58:59], v[58:59], v[132:133]
	v_exp_f32_e32 v132, v0
	v_mul_f32_e32 v0, 0xbfb8aa3b, v141
	v_exp_f32_e32 v0, v0
	v_pk_mul_f32 v[134:135], v[136:137], v[138:139]
	v_add_f32_e32 v0, 1.0, v0
	v_pk_mul_f32 v[60:61], v[60:61], v[134:135]
	v_rcp_f32_e32 v134, v0
	v_mul_f32_e32 v0, 0xbfb8aa3b, v153
	v_exp_f32_e32 v133, v0
	v_mul_f32_e32 v0, 0xbfb8aa3b, v142
	v_exp_f32_e32 v0, v0
	v_pk_add_f32 v[132:133], v[132:133], 1.0 op_sel_hi:[1,0]
	v_add_f32_e32 v0, 1.0, v0
	v_rcp_f32_e32 v135, v0
	v_mul_f32_e32 v0, 0xbfb8aa3b, v154
	v_exp_f32_e32 v136, v0
	v_mul_f32_e32 v0, 0xbfb8aa3b, v143
	v_exp_f32_e32 v0, v0
	v_pk_mul_f32 v[132:133], v[132:133], v[134:135]
	v_add_f32_e32 v0, 1.0, v0
	v_rcp_f32_e32 v138, v0
	v_mul_f32_e32 v0, 0xbfb8aa3b, v155
	v_exp_f32_e32 v137, v0
	v_mul_f32_e32 v0, 0xbfb8aa3b, v144
	v_exp_f32_e32 v0, v0
	v_pk_mul_f32 v[62:63], v[62:63], v[132:133]
	v_pk_add_f32 v[136:137], v[136:137], 1.0 op_sel_hi:[1,0]
	v_add_f32_e32 v0, 1.0, v0
	v_rcp_f32_e32 v139, v0
	s_nop 0
	v_pk_mul_f32 v[134:135], v[136:137], v[138:139]
	v_or_b32_e32 v136, 0x1400, v130
	v_mov_b32_e32 v137, s27
	v_pk_mul_f32 v[64:65], v[64:65], v[134:135]
	v_or_b32_e32 v222, 0x2800, v130
	v_mov_b32_e32 v223, s27
	v_lshl_add_u64 v[228:229], s[6:7], 0, v[222:223]
	global_load_dwordx4 v[244:247], v[228:229], off nt
	v_lshl_add_u64 v[228:229], s[8:9], 0, v[222:223]
	global_load_dwordx4 v[248:251], v[228:229], off
	s_waitcnt vmcnt(11)
	v_lshlrev_b32_e32 v0, 16, v216
	v_and_b32_e32 v138, 0xffff0000, v216
	v_lshlrev_b32_e32 v139, 16, v217
	v_and_b32_e32 v140, 0xffff0000, v217
	v_lshlrev_b32_e32 v141, 16, v218
	v_and_b32_e32 v142, 0xffff0000, v218
	v_lshlrev_b32_e32 v143, 16, v219
	v_and_b32_e32 v144, 0xffff0000, v219
	v_mul_f32_e32 v0, 0xbfb8aa3b, v0
	v_exp_f32_e32 v0, v0
	s_waitcnt vmcnt(10)
	v_and_b32_e32 v137, 0xffff0000, v224
	v_add_f32_e32 v0, 1.0, v0
	v_lshlrev_b32_e32 v152, 16, v226
	v_and_b32_e32 v153, 0xffff0000, v226
	v_rcp_f32_e32 v134, v0
	v_mul_f32_e32 v0, 0xbfb8aa3b, v137
	v_lshlrev_b32_e32 v145, 16, v225
	v_and_b32_e32 v151, 0xffff0000, v225
	v_exp_f32_e32 v133, v0
	v_mul_f32_e32 v0, 0xbfb8aa3b, v138
	v_exp_f32_e32 v0, v0
	v_lshlrev_b32_e32 v136, 16, v224
	v_lshlrev_b32_e32 v154, 16, v227
	v_and_b32_e32 v155, 0xffff0000, v227
	v_add_f32_e32 v0, 1.0, v0
	v_rcp_f32_e32 v135, v0
	v_mul_f32_e32 v0, 0xbfb8aa3b, v145
	v_mul_f32_e32 v132, 0xbfb8aa3b, v136
	v_exp_f32_e32 v136, v0
	v_mul_f32_e32 v0, 0xbfb8aa3b, v139
	v_exp_f32_e32 v0, v0
	v_exp_f32_e32 v132, v132
	v_add_f32_e32 v0, 1.0, v0
	v_rcp_f32_e32 v138, v0
	v_mul_f32_e32 v0, 0xbfb8aa3b, v151
	v_exp_f32_e32 v137, v0
	v_mul_f32_e32 v0, 0xbfb8aa3b, v140
	v_exp_f32_e32 v0, v0
	v_pk_add_f32 v[132:133], v[132:133], 1.0 op_sel_hi:[1,0]
	v_pk_add_f32 v[136:137], v[136:137], 1.0 op_sel_hi:[1,0]
	v_pk_mul_f32 v[132:133], v[132:133], v[134:135]
	v_add_f32_e32 v0, 1.0, v0
	v_rcp_f32_e32 v139, v0
	v_mul_f32_e32 v0, 0xbfb8aa3b, v152
	v_pk_mul_f32 v[74:75], v[74:75], v[132:133]
	v_exp_f32_e32 v132, v0
	v_mul_f32_e32 v0, 0xbfb8aa3b, v141
	v_exp_f32_e32 v0, v0
	v_pk_mul_f32 v[134:135], v[136:137], v[138:139]
	v_add_f32_e32 v0, 1.0, v0
	v_pk_mul_f32 v[76:77], v[76:77], v[134:135]
	v_rcp_f32_e32 v134, v0
	v_mul_f32_e32 v0, 0xbfb8aa3b, v153
	v_exp_f32_e32 v133, v0
	v_mul_f32_e32 v0, 0xbfb8aa3b, v142
	v_exp_f32_e32 v0, v0
	v_pk_add_f32 v[132:133], v[132:133], 1.0 op_sel_hi:[1,0]
	v_add_f32_e32 v0, 1.0, v0
	v_rcp_f32_e32 v135, v0
	v_mul_f32_e32 v0, 0xbfb8aa3b, v154
	v_exp_f32_e32 v136, v0
	v_mul_f32_e32 v0, 0xbfb8aa3b, v143
	v_exp_f32_e32 v0, v0
	v_pk_mul_f32 v[132:133], v[132:133], v[134:135]
	v_add_f32_e32 v0, 1.0, v0
	v_rcp_f32_e32 v138, v0
	v_mul_f32_e32 v0, 0xbfb8aa3b, v155
	v_exp_f32_e32 v137, v0
	v_mul_f32_e32 v0, 0xbfb8aa3b, v144
	v_exp_f32_e32 v0, v0
	v_pk_mul_f32 v[78:79], v[78:79], v[132:133]
	v_pk_add_f32 v[136:137], v[136:137], 1.0 op_sel_hi:[1,0]
	v_add_f32_e32 v0, 1.0, v0
	v_rcp_f32_e32 v139, v0
	s_nop 0
	v_pk_mul_f32 v[134:135], v[136:137], v[138:139]
	v_or_b32_e32 v136, 0x1800, v130
	v_mov_b32_e32 v137, s27
	v_pk_mul_f32 v[80:81], v[80:81], v[134:135]
	v_or_b32_e32 v222, 0x2c00, v130
	v_mov_b32_e32 v223, s27
	v_lshl_add_u64 v[228:229], s[6:7], 0, v[222:223]
	global_load_dwordx4 v[216:219], v[228:229], off nt
	v_lshl_add_u64 v[228:229], s[8:9], 0, v[222:223]
	global_load_dwordx4 v[224:227], v[228:229], off
	s_waitcnt vmcnt(11)
; DI uint4 ld_nt16(const void* q) { const ntu4 t = __builtin_nontemporal_load((const ntu4*)q); uint4 v; v.x = t[0]; v.y = t[1]; v.z = t[2]; v.w = t[3]; return v; }
; DI float frcp(float x) { return __builtin_amdgcn_rcpf(x); }
; template <int CT>
; DI void phase_g2(int c, int l) {
;     ...
; #pragma unroll
;     for (int n = 0; n < 4; ++n) {
; #pragma unroll
;       for (int mp = 0; mp < 4; ++mp) {
;         const size_t fo = frag_off(pm, pn, wid, n, mp, lane);
;         float a8[8], b8[8];
;         unpack8(ld_nt16(WSU(MGA) + fo), a8); unpack8(ld_nt16(WSU(MGB) + fo), b8);
; #pragma unroll
;         for (int j = 0; j < 8; ++j) acc[mp * 2 + (j >> 2)][n][j & 3] *= (1.f + __expf(-b8[j])) * frcp(1.f + __expf(-a8[j]));
;       }
	v_lshlrev_b32_e32 v0, 16, v156
	v_and_b32_e32 v138, 0xffff0000, v156
	v_lshlrev_b32_e32 v139, 16, v157
	v_and_b32_e32 v140, 0xffff0000, v157
	v_lshlrev_b32_e32 v141, 16, v158
	v_and_b32_e32 v142, 0xffff0000, v158
	v_lshlrev_b32_e32 v143, 16, v159
	v_and_b32_e32 v144, 0xffff0000, v159
	v_mul_f32_e32 v0, 0xbfb8aa3b, v0
	v_exp_f32_e32 v0, v0
	s_waitcnt vmcnt(10)
	v_and_b32_e32 v137, 0xffff0000, v160
	v_add_f32_e32 v0, 1.0, v0
	v_lshlrev_b32_e32 v152, 16, v162
	v_and_b32_e32 v153, 0xffff0000, v162
	v_rcp_f32_e32 v134, v0
	v_mul_f32_e32 v0, 0xbfb8aa3b, v137
	v_lshlrev_b32_e32 v145, 16, v161
	v_and_b32_e32 v151, 0xffff0000, v161
	v_exp_f32_e32 v133, v0
	v_mul_f32_e32 v0, 0xbfb8aa3b, v138
	v_exp_f32_e32 v0, v0
	v_lshlrev_b32_e32 v136, 16, v160
	v_lshlrev_b32_e32 v154, 16, v163
	v_and_b32_e32 v155, 0xffff0000, v163
	v_add_f32_e32 v0, 1.0, v0
	v_rcp_f32_e32 v135, v0
	v_mul_f32_e32 v0, 0xbfb8aa3b, v145
	v_mul_f32_e32 v132, 0xbfb8aa3b, v136
	v_exp_f32_e32 v136, v0
	v_mul_f32_e32 v0, 0xbfb8aa3b, v139
	v_exp_f32_e32 v0, v0
	v_exp_f32_e32 v132, v132
	v_add_f32_e32 v0, 1.0, v0
	v_rcp_f32_e32 v138, v0
	v_mul_f32_e32 v0, 0xbfb8aa3b, v151
	v_exp_f32_e32 v137, v0
	v_mul_f32_e32 v0, 0xbfb8aa3b, v140
	v_exp_f32_e32 v0, v0
	v_pk_add_f32 v[132:133], v[132:133], 1.0 op_sel_hi:[1,0]
	v_pk_add_f32 v[136:137], v[136:137], 1.0 op_sel_hi:[1,0]
	v_pk_mul_f32 v[132:133], v[132:133], v[134:135]
	v_add_f32_e32 v0, 1.0, v0
	v_rcp_f32_e32 v139, v0
	v_mul_f32_e32 v0, 0xbfb8aa3b, v152
	v_pk_mul_f32 v[90:91], v[90:91], v[132:133]
	v_exp_f32_e32 v132, v0
	v_mul_f32_e32 v0, 0xbfb8aa3b, v141
	v_exp_f32_e32 v0, v0
	v_pk_mul_f32 v[134:135], v[136:137], v[138:139]
	v_add_f32_e32 v0, 1.0, v0
	v_pk_mul_f32 v[92:93], v[92:93], v[134:135]
	v_rcp_f32_e32 v134, v0
	v_mul_f32_e32 v0, 0xbfb8aa3b, v153
	v_exp_f32_e32 v133, v0
	v_mul_f32_e32 v0, 0xbfb8aa3b, v142
	v_exp_f32_e32 v0, v0
	v_pk_add_f32 v[132:133], v[132:133], 1.0 op_sel_hi:[1,0]
	v_add_f32_e32 v0, 1.0, v0
	v_rcp_f32_e32 v135, v0
	v_mul_f32_e32 v0, 0xbfb8aa3b, v154
	v_exp_f32_e32 v136, v0
	v_mul_f32_e32 v0, 0xbfb8aa3b, v143
	v_exp_f32_e32 v0, v0
	v_pk_mul_f32 v[132:133], v[132:133], v[134:135]
	v_add_f32_e32 v0, 1.0, v0
	v_rcp_f32_e32 v138, v0
	v_mul_f32_e32 v0, 0xbfb8aa3b, v155
	v_exp_f32_e32 v137, v0
	v_mul_f32_e32 v0, 0xbfb8aa3b, v144
	v_exp_f32_e32 v0, v0
	v_pk_mul_f32 v[94:95], v[94:95], v[132:133]
	v_pk_add_f32 v[136:137], v[136:137], 1.0 op_sel_hi:[1,0]
	v_add_f32_e32 v0, 1.0, v0
	v_rcp_f32_e32 v139, v0
	s_nop 0
	v_pk_mul_f32 v[134:135], v[136:137], v[138:139]
	v_or_b32_e32 v136, 0x1c00, v130
	v_mov_b32_e32 v137, s27
	v_pk_mul_f32 v[96:97], v[96:97], v[134:135]
	v_or_b32_e32 v222, 0x3000, v130
	v_mov_b32_e32 v223, s27
	v_lshl_add_u64 v[228:229], s[6:7], 0, v[222:223]
	global_load_dwordx4 v[156:159], v[228:229], off nt
	v_lshl_add_u64 v[228:229], s[8:9], 0, v[222:223]
	global_load_dwordx4 v[160:163], v[228:229], off
	s_waitcnt vmcnt(11)
	v_lshlrev_b32_e32 v0, 16, v164
	v_and_b32_e32 v138, 0xffff0000, v164
	v_lshlrev_b32_e32 v139, 16, v165
	v_and_b32_e32 v140, 0xffff0000, v165
	v_lshlrev_b32_e32 v141, 16, v166
	v_and_b32_e32 v142, 0xffff0000, v166
	v_lshlrev_b32_e32 v143, 16, v167
	v_and_b32_e32 v144, 0xffff0000, v167
	v_mul_f32_e32 v0, 0xbfb8aa3b, v0
	v_exp_f32_e32 v0, v0
	s_waitcnt vmcnt(10)
	v_and_b32_e32 v137, 0xffff0000, v168
	v_add_f32_e32 v0, 1.0, v0
	v_lshlrev_b32_e32 v152, 16, v170
	v_and_b32_e32 v153, 0xffff0000, v170
	v_rcp_f32_e32 v134, v0
	v_mul_f32_e32 v0, 0xbfb8aa3b, v137
	v_lshlrev_b32_e32 v145, 16, v169
	v_and_b32_e32 v151, 0xffff0000, v169
	v_exp_f32_e32 v133, v0
	v_mul_f32_e32 v0, 0xbfb8aa3b, v138
	v_exp_f32_e32 v0, v0
	v_lshlrev_b32_e32 v136, 16, v168
	v_lshlrev_b32_e32 v154, 16, v171
	v_and_b32_e32 v155, 0xffff0000, v171
	v_add_f32_e32 v0, 1.0, v0
	v_rcp_f32_e32 v135, v0
	v_mul_f32_e32 v0, 0xbfb8aa3b, v145
	v_mul_f32_e32 v132, 0xbfb8aa3b, v136
	v_exp_f32_e32 v136, v0
	v_mul_f32_e32 v0, 0xbfb8aa3b, v139
	v_exp_f32_e32 v0, v0
	v_exp_f32_e32 v132, v132
	v_add_f32_e32 v0, 1.0, v0
	v_rcp_f32_e32 v138, v0
	v_mul_f32_e32 v0, 0xbfb8aa3b, v151
	v_exp_f32_e32 v137, v0
	v_mul_f32_e32 v0, 0xbfb8aa3b, v140
	v_exp_f32_e32 v0, v0
	v_pk_add_f32 v[132:133], v[132:133], 1.0 op_sel_hi:[1,0]
	v_pk_add_f32 v[136:137], v[136:137], 1.0 op_sel_hi:[1,0]
	v_pk_mul_f32 v[132:133], v[132:133], v[134:135]
	v_add_f32_e32 v0, 1.0, v0
	v_rcp_f32_e32 v139, v0
	v_mul_f32_e32 v0, 0xbfb8aa3b, v152
	v_pk_mul_f32 v[106:107], v[106:107], v[132:133]
	v_exp_f32_e32 v132, v0
	v_mul_f32_e32 v0, 0xbfb8aa3b, v141
	v_exp_f32_e32 v0, v0
	v_pk_mul_f32 v[134:135], v[136:137], v[138:139]
	v_add_f32_e32 v0, 1.0, v0
	v_pk_mul_f32 v[108:109], v[108:109], v[134:135]
	v_rcp_f32_e32 v134, v0
	v_mul_f32_e32 v0, 0xbfb8aa3b, v153
	v_exp_f32_e32 v133, v0
	v_mul_f32_e32 v0, 0xbfb8aa3b, v142
	v_exp_f32_e32 v0, v0
	v_pk_add_f32 v[132:133], v[132:133], 1.0 op_sel_hi:[1,0]
	v_add_f32_e32 v0, 1.0, v0
	v_rcp_f32_e32 v135, v0
	v_mul_f32_e32 v0, 0xbfb8aa3b, v154
	v_exp_f32_e32 v136, v0
	v_mul_f32_e32 v0, 0xbfb8aa3b, v143
	v_exp_f32_e32 v0, v0
	v_pk_mul_f32 v[132:133], v[132:133], v[134:135]
	v_add_f32_e32 v0, 1.0, v0
	v_rcp_f32_e32 v138, v0
	v_mul_f32_e32 v0, 0xbfb8aa3b, v155
	v_exp_f32_e32 v137, v0
	v_mul_f32_e32 v0, 0xbfb8aa3b, v144
	v_exp_f32_e32 v0, v0
	v_pk_mul_f32 v[110:111], v[110:111], v[132:133]
	v_pk_add_f32 v[136:137], v[136:137], 1.0 op_sel_hi:[1,0]
	v_add_f32_e32 v0, 1.0, v0
	v_rcp_f32_e32 v139, v0
	s_nop 0
	v_pk_mul_f32 v[134:135], v[136:137], v[138:139]
	v_or_b32_e32 v136, 0x2000, v130
	v_mov_b32_e32 v137, s27
	v_pk_mul_f32 v[112:113], v[112:113], v[134:135]
	v_or_b32_e32 v222, 0x3400, v130
	v_mov_b32_e32 v223, s27
	v_lshl_add_u64 v[228:229], s[6:7], 0, v[222:223]
	global_load_dwordx4 v[164:167], v[228:229], off nt
	v_lshl_add_u64 v[228:229], s[8:9], 0, v[222:223]
	global_load_dwordx4 v[168:171], v[228:229], off
	s_waitcnt vmcnt(11)
; DI uint4 ld_nt16(const void* q) { const ntu4 t = __builtin_nontemporal_load((const ntu4*)q); uint4 v; v.x = t[0]; v.y = t[1]; v.z = t[2]; v.w = t[3]; return v; }
; DI float frcp(float x) { return __builtin_amdgcn_rcpf(x); }
; template <int CT>
; DI void phase_g2(int c, int l) {
;     ...
; #pragma unroll
;     for (int n = 0; n < 4; ++n) {
; #pragma unroll
;       for (int mp = 0; mp < 4; ++mp) {
;         const size_t fo = frag_off(pm, pn, wid, n, mp, lane);
;         float a8[8], b8[8];
;         unpack8(ld_nt16(WSU(MGA) + fo), a8); unpack8(ld_nt16(WSU(MGB) + fo), b8);
; #pragma unroll
;         for (int j = 0; j < 8; ++j) acc[mp * 2 + (j >> 2)][n][j & 3] *= (1.f + __expf(-b8[j])) * frcp(1.f + __expf(-a8[j]));
;       }
	v_lshlrev_b32_e32 v0, 16, v172
	v_and_b32_e32 v138, 0xffff0000, v172
	v_lshlrev_b32_e32 v139, 16, v173
	v_and_b32_e32 v140, 0xffff0000, v173
	v_lshlrev_b32_e32 v141, 16, v174
	v_and_b32_e32 v142, 0xffff0000, v174
	v_lshlrev_b32_e32 v143, 16, v175
	v_and_b32_e32 v144, 0xffff0000, v175
	v_mul_f32_e32 v0, 0xbfb8aa3b, v0
	v_exp_f32_e32 v0, v0
	s_waitcnt vmcnt(10)
	v_and_b32_e32 v137, 0xffff0000, v232
	v_add_f32_e32 v0, 1.0, v0
	v_lshlrev_b32_e32 v152, 16, v234
	v_and_b32_e32 v153, 0xffff0000, v234
	v_rcp_f32_e32 v134, v0
	v_mul_f32_e32 v0, 0xbfb8aa3b, v137
	v_lshlrev_b32_e32 v145, 16, v233
	v_and_b32_e32 v151, 0xffff0000, v233
	v_exp_f32_e32 v133, v0
	v_mul_f32_e32 v0, 0xbfb8aa3b, v138
	v_exp_f32_e32 v0, v0
	v_lshlrev_b32_e32 v136, 16, v232
	v_lshlrev_b32_e32 v154, 16, v235
	v_and_b32_e32 v155, 0xffff0000, v235
	v_add_f32_e32 v0, 1.0, v0
	v_rcp_f32_e32 v135, v0
	v_mul_f32_e32 v0, 0xbfb8aa3b, v145
	v_mul_f32_e32 v132, 0xbfb8aa3b, v136
	v_exp_f32_e32 v136, v0
	v_mul_f32_e32 v0, 0xbfb8aa3b, v139
	v_exp_f32_e32 v0, v0
	v_exp_f32_e32 v132, v132
	v_add_f32_e32 v0, 1.0, v0
	v_rcp_f32_e32 v138, v0
	v_mul_f32_e32 v0, 0xbfb8aa3b, v151
	v_exp_f32_e32 v137, v0
	v_mul_f32_e32 v0, 0xbfb8aa3b, v140
	v_exp_f32_e32 v0, v0
	v_pk_add_f32 v[132:133], v[132:133], 1.0 op_sel_hi:[1,0]
	v_pk_add_f32 v[136:137], v[136:137], 1.0 op_sel_hi:[1,0]
	v_pk_mul_f32 v[132:133], v[132:133], v[134:135]
	v_add_f32_e32 v0, 1.0, v0
	v_rcp_f32_e32 v139, v0
	v_mul_f32_e32 v0, 0xbfb8aa3b, v152
	v_pk_mul_f32 v[122:123], v[122:123], v[132:133]
	v_exp_f32_e32 v132, v0
	v_mul_f32_e32 v0, 0xbfb8aa3b, v141
	v_exp_f32_e32 v0, v0
	v_pk_mul_f32 v[134:135], v[136:137], v[138:139]
	v_add_f32_e32 v0, 1.0, v0
	v_pk_mul_f32 v[124:125], v[124:125], v[134:135]
	v_rcp_f32_e32 v134, v0
	v_mul_f32_e32 v0, 0xbfb8aa3b, v153
	v_exp_f32_e32 v133, v0
	v_mul_f32_e32 v0, 0xbfb8aa3b, v142
	v_exp_f32_e32 v0, v0
	v_pk_add_f32 v[132:133], v[132:133], 1.0 op_sel_hi:[1,0]
	v_add_f32_e32 v0, 1.0, v0
	v_rcp_f32_e32 v135, v0
	v_mul_f32_e32 v0, 0xbfb8aa3b, v154
	v_exp_f32_e32 v136, v0
	v_mul_f32_e32 v0, 0xbfb8aa3b, v143
	v_exp_f32_e32 v0, v0
	v_pk_mul_f32 v[132:133], v[132:133], v[134:135]
	v_add_f32_e32 v0, 1.0, v0
	v_rcp_f32_e32 v138, v0
	v_mul_f32_e32 v0, 0xbfb8aa3b, v155
	v_exp_f32_e32 v137, v0
	v_mul_f32_e32 v0, 0xbfb8aa3b, v144
	v_exp_f32_e32 v0, v0
	v_pk_mul_f32 v[126:127], v[126:127], v[132:133]
	v_pk_add_f32 v[136:137], v[136:137], 1.0 op_sel_hi:[1,0]
	v_add_f32_e32 v0, 1.0, v0
	v_rcp_f32_e32 v139, v0
	s_nop 0
	v_pk_mul_f32 v[134:135], v[136:137], v[138:139]
	v_or_b32_e32 v136, 0x2400, v130
	v_mov_b32_e32 v137, s27
	v_pk_mul_f32 v[128:129], v[128:129], v[134:135]
	v_or_b32_e32 v222, 0x3800, v130
	v_mov_b32_e32 v223, s27
	v_lshl_add_u64 v[228:229], s[6:7], 0, v[222:223]
	global_load_dwordx4 v[172:175], v[228:229], off nt
	v_lshl_add_u64 v[228:229], s[8:9], 0, v[222:223]
	global_load_dwordx4 v[232:235], v[228:229], off
	s_waitcnt vmcnt(11)
	v_lshlrev_b32_e32 v0, 16, v236
	v_and_b32_e32 v138, 0xffff0000, v236
	v_lshlrev_b32_e32 v139, 16, v237
	v_and_b32_e32 v140, 0xffff0000, v237
	v_lshlrev_b32_e32 v141, 16, v238
	v_and_b32_e32 v142, 0xffff0000, v238
	v_lshlrev_b32_e32 v143, 16, v239
	v_and_b32_e32 v144, 0xffff0000, v239
	v_mul_f32_e32 v0, 0xbfb8aa3b, v0
	v_exp_f32_e32 v0, v0
	s_waitcnt vmcnt(10)
	v_and_b32_e32 v137, 0xffff0000, v240
	v_add_f32_e32 v0, 1.0, v0
	v_lshlrev_b32_e32 v152, 16, v242
	v_and_b32_e32 v153, 0xffff0000, v242
	v_rcp_f32_e32 v134, v0
	v_mul_f32_e32 v0, 0xbfb8aa3b, v137
	v_lshlrev_b32_e32 v145, 16, v241
	v_and_b32_e32 v151, 0xffff0000, v241
	v_exp_f32_e32 v133, v0
	v_mul_f32_e32 v0, 0xbfb8aa3b, v138
	v_exp_f32_e32 v0, v0
	v_lshlrev_b32_e32 v136, 16, v240
	v_lshlrev_b32_e32 v154, 16, v243
	v_and_b32_e32 v155, 0xffff0000, v243
	v_add_f32_e32 v0, 1.0, v0
	v_rcp_f32_e32 v135, v0
	v_mul_f32_e32 v0, 0xbfb8aa3b, v145
	v_mul_f32_e32 v132, 0xbfb8aa3b, v136
	v_exp_f32_e32 v136, v0
	v_mul_f32_e32 v0, 0xbfb8aa3b, v139
	v_exp_f32_e32 v0, v0
	v_exp_f32_e32 v132, v132
	v_add_f32_e32 v0, 1.0, v0
	v_rcp_f32_e32 v138, v0
	v_mul_f32_e32 v0, 0xbfb8aa3b, v151
	v_exp_f32_e32 v137, v0
	v_mul_f32_e32 v0, 0xbfb8aa3b, v140
	v_exp_f32_e32 v0, v0
	v_pk_add_f32 v[132:133], v[132:133], 1.0 op_sel_hi:[1,0]
	v_pk_add_f32 v[136:137], v[136:137], 1.0 op_sel_hi:[1,0]
	v_pk_mul_f32 v[132:133], v[132:133], v[134:135]
	v_add_f32_e32 v0, 1.0, v0
	v_rcp_f32_e32 v139, v0
	v_mul_f32_e32 v0, 0xbfb8aa3b, v152
	v_pk_mul_f32 v[118:119], v[118:119], v[132:133]
	v_exp_f32_e32 v132, v0
	v_mul_f32_e32 v0, 0xbfb8aa3b, v141
	v_exp_f32_e32 v0, v0
	v_pk_mul_f32 v[134:135], v[136:137], v[138:139]
	v_add_f32_e32 v0, 1.0, v0
	v_pk_mul_f32 v[120:121], v[120:121], v[134:135]
	v_rcp_f32_e32 v134, v0
	v_mul_f32_e32 v0, 0xbfb8aa3b, v153
	v_exp_f32_e32 v133, v0
	v_mul_f32_e32 v0, 0xbfb8aa3b, v142
	v_exp_f32_e32 v0, v0
	v_pk_add_f32 v[132:133], v[132:133], 1.0 op_sel_hi:[1,0]
	v_add_f32_e32 v0, 1.0, v0
	v_rcp_f32_e32 v135, v0
	v_mul_f32_e32 v0, 0xbfb8aa3b, v154
	v_exp_f32_e32 v136, v0
	v_mul_f32_e32 v0, 0xbfb8aa3b, v143
	v_exp_f32_e32 v0, v0
	v_pk_mul_f32 v[132:133], v[132:133], v[134:135]
	v_add_f32_e32 v0, 1.0, v0
	v_rcp_f32_e32 v138, v0
	v_mul_f32_e32 v0, 0xbfb8aa3b, v155
	v_exp_f32_e32 v137, v0
	v_mul_f32_e32 v0, 0xbfb8aa3b, v144
	v_exp_f32_e32 v0, v0
	v_pk_mul_f32 v[114:115], v[114:115], v[132:133]
	v_pk_add_f32 v[136:137], v[136:137], 1.0 op_sel_hi:[1,0]
	v_add_f32_e32 v0, 1.0, v0
	v_rcp_f32_e32 v139, v0
	s_nop 0
	v_pk_mul_f32 v[134:135], v[136:137], v[138:139]
	v_or_b32_e32 v136, 0x2800, v130
	v_mov_b32_e32 v137, s27
	v_pk_mul_f32 v[116:117], v[116:117], v[134:135]
	v_or_b32_e32 v222, 0x3c00, v130
	v_mov_b32_e32 v223, s27
	v_lshl_add_u64 v[228:229], s[6:7], 0, v[222:223]
	global_load_dwordx4 v[236:239], v[228:229], off nt
	v_lshl_add_u64 v[228:229], s[8:9], 0, v[222:223]
	global_load_dwordx4 v[240:243], v[228:229], off
	s_waitcnt vmcnt(11)
; DI uint4 ld_nt16(const void* q) { const ntu4 t = __builtin_nontemporal_load((const ntu4*)q); uint4 v; v.x = t[0]; v.y = t[1]; v.z = t[2]; v.w = t[3]; return v; }
; DI float frcp(float x) { return __builtin_amdgcn_rcpf(x); }
; template <int CT>
; DI void phase_g2(int c, int l) {
;     ...
; #pragma unroll
;     for (int n = 0; n < 4; ++n) {
; #pragma unroll
;       for (int mp = 0; mp < 4; ++mp) {
;         const size_t fo = frag_off(pm, pn, wid, n, mp, lane);
;         float a8[8], b8[8];
;         unpack8(ld_nt16(WSU(MGA) + fo), a8); unpack8(ld_nt16(WSU(MGB) + fo), b8);
; #pragma unroll
;         for (int j = 0; j < 8; ++j) acc[mp * 2 + (j >> 2)][n][j & 3] *= (1.f + __expf(-b8[j])) * frcp(1.f + __expf(-a8[j]));
;       }
	v_lshlrev_b32_e32 v0, 16, v244
	v_and_b32_e32 v138, 0xffff0000, v244
	v_lshlrev_b32_e32 v139, 16, v245
	v_and_b32_e32 v140, 0xffff0000, v245
	v_lshlrev_b32_e32 v141, 16, v246
	v_and_b32_e32 v142, 0xffff0000, v246
	v_lshlrev_b32_e32 v143, 16, v247
	v_and_b32_e32 v144, 0xffff0000, v247
	v_mul_f32_e32 v0, 0xbfb8aa3b, v0
	v_exp_f32_e32 v0, v0
	s_waitcnt vmcnt(10)
	v_and_b32_e32 v137, 0xffff0000, v248
	v_add_f32_e32 v0, 1.0, v0
	v_lshlrev_b32_e32 v152, 16, v250
	v_and_b32_e32 v153, 0xffff0000, v250
	v_rcp_f32_e32 v134, v0
	v_mul_f32_e32 v0, 0xbfb8aa3b, v137
	v_lshlrev_b32_e32 v145, 16, v249
	v_and_b32_e32 v151, 0xffff0000, v249
	v_exp_f32_e32 v133, v0
	v_mul_f32_e32 v0, 0xbfb8aa3b, v138
	v_exp_f32_e32 v0, v0
	v_lshlrev_b32_e32 v136, 16, v248
	v_lshlrev_b32_e32 v154, 16, v251
	v_and_b32_e32 v155, 0xffff0000, v251
	v_add_f32_e32 v0, 1.0, v0
	v_rcp_f32_e32 v135, v0
	v_mul_f32_e32 v0, 0xbfb8aa3b, v145
	v_mul_f32_e32 v132, 0xbfb8aa3b, v136
	v_exp_f32_e32 v136, v0
	v_mul_f32_e32 v0, 0xbfb8aa3b, v139
	v_exp_f32_e32 v0, v0
	v_exp_f32_e32 v132, v132
	v_add_f32_e32 v0, 1.0, v0
	v_rcp_f32_e32 v138, v0
	v_mul_f32_e32 v0, 0xbfb8aa3b, v151
	v_exp_f32_e32 v137, v0
	v_mul_f32_e32 v0, 0xbfb8aa3b, v140
	v_exp_f32_e32 v0, v0
	v_pk_add_f32 v[132:133], v[132:133], 1.0 op_sel_hi:[1,0]
	v_pk_add_f32 v[136:137], v[136:137], 1.0 op_sel_hi:[1,0]
	v_pk_mul_f32 v[132:133], v[132:133], v[134:135]
	v_add_f32_e32 v0, 1.0, v0
	v_rcp_f32_e32 v139, v0
	v_mul_f32_e32 v0, 0xbfb8aa3b, v152
	v_pk_mul_f32 v[102:103], v[102:103], v[132:133]
	v_exp_f32_e32 v132, v0
	v_mul_f32_e32 v0, 0xbfb8aa3b, v141
	v_exp_f32_e32 v0, v0
	v_pk_mul_f32 v[134:135], v[136:137], v[138:139]
	v_add_f32_e32 v0, 1.0, v0
	v_pk_mul_f32 v[104:105], v[104:105], v[134:135]
	v_rcp_f32_e32 v134, v0
	v_mul_f32_e32 v0, 0xbfb8aa3b, v153
	v_exp_f32_e32 v133, v0
	v_mul_f32_e32 v0, 0xbfb8aa3b, v142
	v_exp_f32_e32 v0, v0
	v_pk_add_f32 v[132:133], v[132:133], 1.0 op_sel_hi:[1,0]
	v_add_f32_e32 v0, 1.0, v0
	v_rcp_f32_e32 v135, v0
	v_mul_f32_e32 v0, 0xbfb8aa3b, v154
	v_exp_f32_e32 v136, v0
	v_mul_f32_e32 v0, 0xbfb8aa3b, v143
	v_exp_f32_e32 v0, v0
	v_pk_mul_f32 v[132:133], v[132:133], v[134:135]
	v_add_f32_e32 v0, 1.0, v0
	v_rcp_f32_e32 v138, v0
	v_mul_f32_e32 v0, 0xbfb8aa3b, v155
	v_exp_f32_e32 v137, v0
	v_mul_f32_e32 v0, 0xbfb8aa3b, v144
	v_exp_f32_e32 v0, v0
	v_pk_mul_f32 v[98:99], v[98:99], v[132:133]
	v_pk_add_f32 v[136:137], v[136:137], 1.0 op_sel_hi:[1,0]
	v_add_f32_e32 v0, 1.0, v0
	v_rcp_f32_e32 v139, v0
	s_nop 0
	v_pk_mul_f32 v[134:135], v[136:137], v[138:139]
	v_or_b32_e32 v136, 0x2c00, v130
	v_mov_b32_e32 v137, s27
	v_pk_mul_f32 v[100:101], v[100:101], v[134:135]
	s_waitcnt vmcnt(9)
	v_lshlrev_b32_e32 v0, 16, v216
	v_and_b32_e32 v138, 0xffff0000, v216
	v_lshlrev_b32_e32 v139, 16, v217
	v_and_b32_e32 v140, 0xffff0000, v217
	v_lshlrev_b32_e32 v141, 16, v218
	v_and_b32_e32 v142, 0xffff0000, v218
	v_lshlrev_b32_e32 v143, 16, v219
	v_and_b32_e32 v144, 0xffff0000, v219
	v_mul_f32_e32 v0, 0xbfb8aa3b, v0
	v_exp_f32_e32 v0, v0
	s_waitcnt vmcnt(8)
	v_and_b32_e32 v137, 0xffff0000, v224
	v_add_f32_e32 v0, 1.0, v0
	v_lshlrev_b32_e32 v152, 16, v226
	v_and_b32_e32 v153, 0xffff0000, v226
	v_rcp_f32_e32 v134, v0
	v_mul_f32_e32 v0, 0xbfb8aa3b, v137
	v_lshlrev_b32_e32 v145, 16, v225
	v_and_b32_e32 v151, 0xffff0000, v225
	v_exp_f32_e32 v133, v0
	v_mul_f32_e32 v0, 0xbfb8aa3b, v138
	v_exp_f32_e32 v0, v0
	v_lshlrev_b32_e32 v136, 16, v224
	v_lshlrev_b32_e32 v154, 16, v227
	v_and_b32_e32 v155, 0xffff0000, v227
	v_add_f32_e32 v0, 1.0, v0
	v_rcp_f32_e32 v135, v0
	v_mul_f32_e32 v0, 0xbfb8aa3b, v145
	v_mul_f32_e32 v132, 0xbfb8aa3b, v136
	v_exp_f32_e32 v136, v0
	v_mul_f32_e32 v0, 0xbfb8aa3b, v139
	v_exp_f32_e32 v0, v0
	v_exp_f32_e32 v132, v132
	v_add_f32_e32 v0, 1.0, v0
	v_rcp_f32_e32 v138, v0
	v_mul_f32_e32 v0, 0xbfb8aa3b, v151
	v_exp_f32_e32 v137, v0
	v_mul_f32_e32 v0, 0xbfb8aa3b, v140
	v_exp_f32_e32 v0, v0
	v_pk_add_f32 v[132:133], v[132:133], 1.0 op_sel_hi:[1,0]
	v_pk_add_f32 v[136:137], v[136:137], 1.0 op_sel_hi:[1,0]
	v_pk_mul_f32 v[132:133], v[132:133], v[134:135]
	v_add_f32_e32 v0, 1.0, v0
	v_rcp_f32_e32 v139, v0
	v_mul_f32_e32 v0, 0xbfb8aa3b, v152
	v_pk_mul_f32 v[86:87], v[86:87], v[132:133]
	v_exp_f32_e32 v132, v0
	v_mul_f32_e32 v0, 0xbfb8aa3b, v141
	v_exp_f32_e32 v0, v0
	v_pk_mul_f32 v[134:135], v[136:137], v[138:139]
	v_add_f32_e32 v0, 1.0, v0
	v_pk_mul_f32 v[88:89], v[88:89], v[134:135]
	v_rcp_f32_e32 v134, v0
	v_mul_f32_e32 v0, 0xbfb8aa3b, v153
	v_exp_f32_e32 v133, v0
	v_mul_f32_e32 v0, 0xbfb8aa3b, v142
	v_exp_f32_e32 v0, v0
	v_pk_add_f32 v[132:133], v[132:133], 1.0 op_sel_hi:[1,0]
	v_add_f32_e32 v0, 1.0, v0
	v_rcp_f32_e32 v135, v0
	v_mul_f32_e32 v0, 0xbfb8aa3b, v154
	v_exp_f32_e32 v136, v0
	v_mul_f32_e32 v0, 0xbfb8aa3b, v143
	v_exp_f32_e32 v0, v0
	v_pk_mul_f32 v[132:133], v[132:133], v[134:135]
	v_add_f32_e32 v0, 1.0, v0
	v_rcp_f32_e32 v138, v0
	v_mul_f32_e32 v0, 0xbfb8aa3b, v155
	v_exp_f32_e32 v137, v0
	v_mul_f32_e32 v0, 0xbfb8aa3b, v144
	v_exp_f32_e32 v0, v0
	v_pk_mul_f32 v[82:83], v[82:83], v[132:133]
	v_pk_add_f32 v[136:137], v[136:137], 1.0 op_sel_hi:[1,0]
	v_add_f32_e32 v0, 1.0, v0
	v_rcp_f32_e32 v139, v0
	s_nop 0
	v_pk_mul_f32 v[134:135], v[136:137], v[138:139]
	v_or_b32_e32 v136, 0x3000, v130
	v_mov_b32_e32 v137, s27
	v_pk_mul_f32 v[84:85], v[84:85], v[134:135]
	s_waitcnt vmcnt(7)
	v_lshlrev_b32_e32 v0, 16, v156
	v_and_b32_e32 v138, 0xffff0000, v156
	v_lshlrev_b32_e32 v139, 16, v157
	v_and_b32_e32 v140, 0xffff0000, v157
	v_lshlrev_b32_e32 v141, 16, v158
	v_and_b32_e32 v142, 0xffff0000, v158
	v_lshlrev_b32_e32 v143, 16, v159
	v_and_b32_e32 v144, 0xffff0000, v159
	v_mul_f32_e32 v0, 0xbfb8aa3b, v0
	v_exp_f32_e32 v0, v0
	s_waitcnt vmcnt(6)
; DI uint4 ld_nt16(const void* q) { const ntu4 t = __builtin_nontemporal_load((const ntu4*)q); uint4 v; v.x = t[0]; v.y = t[1]; v.z = t[2]; v.w = t[3]; return v; }
; DI float frcp(float x) { return __builtin_amdgcn_rcpf(x); }
; template <int CT>
; DI void phase_g2(int c, int l) {
;     ...
; #pragma unroll
;     for (int n = 0; n < 4; ++n) {
; #pragma unroll
;       for (int mp = 0; mp < 4; ++mp) {
;         const size_t fo = frag_off(pm, pn, wid, n, mp, lane);
;         float a8[8], b8[8];
;         unpack8(ld_nt16(WSU(MGA) + fo), a8); unpack8(ld_nt16(WSU(MGB) + fo), b8);
; #pragma unroll
;         for (int j = 0; j < 8; ++j) acc[mp * 2 + (j >> 2)][n][j & 3] *= (1.f + __expf(-b8[j])) * frcp(1.f + __expf(-a8[j]));
;       }
	v_and_b32_e32 v137, 0xffff0000, v160
	v_add_f32_e32 v0, 1.0, v0
	v_lshlrev_b32_e32 v152, 16, v162
	v_and_b32_e32 v153, 0xffff0000, v162
	v_rcp_f32_e32 v134, v0
	v_mul_f32_e32 v0, 0xbfb8aa3b, v137
	v_lshlrev_b32_e32 v145, 16, v161
	v_and_b32_e32 v151, 0xffff0000, v161
	v_exp_f32_e32 v133, v0
	v_mul_f32_e32 v0, 0xbfb8aa3b, v138
	v_exp_f32_e32 v0, v0
	v_lshlrev_b32_e32 v136, 16, v160
	v_lshlrev_b32_e32 v154, 16, v163
	v_and_b32_e32 v155, 0xffff0000, v163
	v_add_f32_e32 v0, 1.0, v0
	v_rcp_f32_e32 v135, v0
	v_mul_f32_e32 v0, 0xbfb8aa3b, v145
	v_mul_f32_e32 v132, 0xbfb8aa3b, v136
	v_exp_f32_e32 v136, v0
	v_mul_f32_e32 v0, 0xbfb8aa3b, v139
	v_exp_f32_e32 v0, v0
	v_exp_f32_e32 v132, v132
	v_add_f32_e32 v0, 1.0, v0
	v_rcp_f32_e32 v138, v0
	v_mul_f32_e32 v0, 0xbfb8aa3b, v151
	v_exp_f32_e32 v137, v0
	v_mul_f32_e32 v0, 0xbfb8aa3b, v140
	v_exp_f32_e32 v0, v0
	v_pk_add_f32 v[132:133], v[132:133], 1.0 op_sel_hi:[1,0]
	v_pk_add_f32 v[136:137], v[136:137], 1.0 op_sel_hi:[1,0]
	v_pk_mul_f32 v[132:133], v[132:133], v[134:135]
	v_add_f32_e32 v0, 1.0, v0
	v_rcp_f32_e32 v139, v0
	v_mul_f32_e32 v0, 0xbfb8aa3b, v152
	v_pk_mul_f32 v[70:71], v[70:71], v[132:133]
	v_exp_f32_e32 v132, v0
	v_mul_f32_e32 v0, 0xbfb8aa3b, v141
	v_exp_f32_e32 v0, v0
	v_pk_mul_f32 v[134:135], v[136:137], v[138:139]
	v_add_f32_e32 v0, 1.0, v0
	v_pk_mul_f32 v[72:73], v[72:73], v[134:135]
	v_rcp_f32_e32 v134, v0
	v_mul_f32_e32 v0, 0xbfb8aa3b, v153
	v_exp_f32_e32 v133, v0
	v_mul_f32_e32 v0, 0xbfb8aa3b, v142
	v_exp_f32_e32 v0, v0
	v_pk_add_f32 v[132:133], v[132:133], 1.0 op_sel_hi:[1,0]
	v_add_f32_e32 v0, 1.0, v0
	v_rcp_f32_e32 v135, v0
	v_mul_f32_e32 v0, 0xbfb8aa3b, v154
	v_exp_f32_e32 v136, v0
	v_mul_f32_e32 v0, 0xbfb8aa3b, v143
	v_exp_f32_e32 v0, v0
	v_pk_mul_f32 v[132:133], v[132:133], v[134:135]
	v_add_f32_e32 v0, 1.0, v0
	v_rcp_f32_e32 v138, v0
	v_mul_f32_e32 v0, 0xbfb8aa3b, v155
	v_exp_f32_e32 v137, v0
	v_mul_f32_e32 v0, 0xbfb8aa3b, v144
	v_exp_f32_e32 v0, v0
	v_pk_mul_f32 v[66:67], v[66:67], v[132:133]
	v_pk_add_f32 v[136:137], v[136:137], 1.0 op_sel_hi:[1,0]
	v_add_f32_e32 v0, 1.0, v0
	v_rcp_f32_e32 v139, v0
	s_nop 0
	v_pk_mul_f32 v[134:135], v[136:137], v[138:139]
	v_or_b32_e32 v136, 0x3400, v130
	v_mov_b32_e32 v137, s27
	v_pk_mul_f32 v[68:69], v[68:69], v[134:135]
	s_waitcnt vmcnt(5)
	v_lshlrev_b32_e32 v0, 16, v164
	v_and_b32_e32 v138, 0xffff0000, v164
	v_lshlrev_b32_e32 v139, 16, v165
	v_and_b32_e32 v140, 0xffff0000, v165
	v_lshlrev_b32_e32 v141, 16, v166
	v_and_b32_e32 v142, 0xffff0000, v166
	v_lshlrev_b32_e32 v143, 16, v167
	v_and_b32_e32 v144, 0xffff0000, v167
	v_mul_f32_e32 v0, 0xbfb8aa3b, v0
	v_exp_f32_e32 v0, v0
	s_waitcnt vmcnt(4)
	v_and_b32_e32 v137, 0xffff0000, v168
	v_add_f32_e32 v0, 1.0, v0
	v_lshlrev_b32_e32 v152, 16, v170
	v_and_b32_e32 v153, 0xffff0000, v170
	v_rcp_f32_e32 v134, v0
	v_mul_f32_e32 v0, 0xbfb8aa3b, v137
	v_lshlrev_b32_e32 v145, 16, v169
	v_and_b32_e32 v151, 0xffff0000, v169
	v_exp_f32_e32 v133, v0
	v_mul_f32_e32 v0, 0xbfb8aa3b, v138
	v_exp_f32_e32 v0, v0
	v_lshlrev_b32_e32 v136, 16, v168
	v_lshlrev_b32_e32 v154, 16, v171
	v_and_b32_e32 v155, 0xffff0000, v171
	v_add_f32_e32 v0, 1.0, v0
	v_rcp_f32_e32 v135, v0
	v_mul_f32_e32 v0, 0xbfb8aa3b, v145
	v_mul_f32_e32 v132, 0xbfb8aa3b, v136
	v_exp_f32_e32 v136, v0
	v_mul_f32_e32 v0, 0xbfb8aa3b, v139
	v_exp_f32_e32 v0, v0
	v_exp_f32_e32 v132, v132
	v_add_f32_e32 v0, 1.0, v0
	v_rcp_f32_e32 v138, v0
	v_mul_f32_e32 v0, 0xbfb8aa3b, v151
	v_exp_f32_e32 v137, v0
	v_mul_f32_e32 v0, 0xbfb8aa3b, v140
	v_exp_f32_e32 v0, v0
	v_pk_add_f32 v[132:133], v[132:133], 1.0 op_sel_hi:[1,0]
	v_pk_add_f32 v[136:137], v[136:137], 1.0 op_sel_hi:[1,0]
	v_pk_mul_f32 v[132:133], v[132:133], v[134:135]
	v_add_f32_e32 v0, 1.0, v0
	v_rcp_f32_e32 v139, v0
	v_mul_f32_e32 v0, 0xbfb8aa3b, v152
	v_pk_mul_f32 v[54:55], v[54:55], v[132:133]
	v_exp_f32_e32 v132, v0
	v_mul_f32_e32 v0, 0xbfb8aa3b, v141
	v_exp_f32_e32 v0, v0
	v_pk_mul_f32 v[134:135], v[136:137], v[138:139]
	v_add_f32_e32 v0, 1.0, v0
	v_pk_mul_f32 v[56:57], v[56:57], v[134:135]
	v_rcp_f32_e32 v134, v0
	v_mul_f32_e32 v0, 0xbfb8aa3b, v153
	v_exp_f32_e32 v133, v0
	v_mul_f32_e32 v0, 0xbfb8aa3b, v142
	v_exp_f32_e32 v0, v0
	v_pk_add_f32 v[132:133], v[132:133], 1.0 op_sel_hi:[1,0]
	v_add_f32_e32 v0, 1.0, v0
	v_rcp_f32_e32 v135, v0
	v_mul_f32_e32 v0, 0xbfb8aa3b, v154
	v_exp_f32_e32 v136, v0
	v_mul_f32_e32 v0, 0xbfb8aa3b, v143
	v_exp_f32_e32 v0, v0
	v_pk_mul_f32 v[132:133], v[132:133], v[134:135]
	v_add_f32_e32 v0, 1.0, v0
	v_rcp_f32_e32 v138, v0
	v_mul_f32_e32 v0, 0xbfb8aa3b, v155
	v_exp_f32_e32 v137, v0
	v_mul_f32_e32 v0, 0xbfb8aa3b, v144
	v_exp_f32_e32 v0, v0
	v_pk_mul_f32 v[50:51], v[50:51], v[132:133]
	v_pk_add_f32 v[136:137], v[136:137], 1.0 op_sel_hi:[1,0]
	v_add_f32_e32 v0, 1.0, v0
	v_rcp_f32_e32 v139, v0
	s_nop 0
	v_pk_mul_f32 v[134:135], v[136:137], v[138:139]
	v_or_b32_e32 v136, 0x3800, v130
	v_mov_b32_e32 v137, s27
	v_pk_mul_f32 v[52:53], v[52:53], v[134:135]
	v_or_b32_e32 v130, 0x3c00, v130
	s_lshl_b32 s27, s21, 12
	s_add_i32 s28, s27, 0x18000
	s_and_b32 s21, s27, 0xffffc000
	s_and_b32 s28, s28, 0xffffe000
	s_add_u32 s22, s67, s22
	s_addc_u32 s23, s81, s23
	s_add_u32 s24, s84, s24
	s_addc_u32 s25, s85, s25
	s_waitcnt vmcnt(3)
	v_lshlrev_b32_e32 v0, 16, v172
	v_and_b32_e32 v138, 0xffff0000, v172
	v_lshlrev_b32_e32 v139, 16, v173
	v_and_b32_e32 v140, 0xffff0000, v173
	v_lshlrev_b32_e32 v141, 16, v174
	v_and_b32_e32 v142, 0xffff0000, v174
	v_lshlrev_b32_e32 v143, 16, v175
	v_and_b32_e32 v144, 0xffff0000, v175
	v_mul_f32_e32 v0, 0xbfb8aa3b, v0
	v_exp_f32_e32 v0, v0
	s_waitcnt vmcnt(2)
; DI uint4 ld_nt16(const void* q) { const ntu4 t = __builtin_nontemporal_load((const ntu4*)q); uint4 v; v.x = t[0]; v.y = t[1]; v.z = t[2]; v.w = t[3]; return v; }
; DI int uni(int v) { return __builtin_amdgcn_readfirstlane(v); }
; DI float frcp(float x) { return __builtin_amdgcn_rcpf(x); }
; #define WAIT_V0() asm volatile("s_waitcnt vmcnt(0)" ::: "memory")
; DI void gemm_core(const int tid, const u16* __restrict__ Wb, int ldw, const u16* __restrict__ Xb, int ldx, int K, f32x4 (&acc)[8][4], const bool pre = false) {
;   const int wid = uni(tid >> 6), lane = tid & 63, wr = wid >> 2, wc = wid & 3, fr = lane & 15, fq = lane >> 4;
;   int offw[4], offx[4];
; #pragma unroll
;   for (int i = 0; i < 4; ++i) {
;     int R, C; stage_rc(wid * 1024 + i * 8192 + lane * 16, R, C);
;     offw[i] = R * ldw + C; offx[i] = R * ldx + C;
;   }
;   auto stage = [&](int buf, int kt) {
; #pragma unroll
;     for (int i = 0; i < 4; ++i) {
;       __builtin_amdgcn_global_load_lds((const unsigned*)(Wb + offw[i] + kt * 64), (unsigned*)(shm + buf * STAGE_B + wid * 1024 + i * 8192), 16, 0, 0);
;       __builtin_amdgcn_global_load_lds((const unsigned*)(Xb + offx[i] + kt * 64), (unsigned*)(shm + buf * STAGE_B + TILE_B + wid * 1024 + i * 8192), 16, 0, 0);
;     }
;   };
;   const int nt = K >> 6;
;   if (!pre) stage(0, 0);
;   WAIT_V0(); __syncthreads();
; template <int CT>
; DI void phase_g2(int c, int l) {
;     ...
;         unpack8(ld_nt16(WSU(MGA) + fo), a8); unpack8(ld_nt16(WSU(MGB) + fo), b8);
; #pragma unroll
;         for (int j = 0; j < 8; ++j) acc[mp * 2 + (j >> 2)][n][j & 3] *= (1.f + __expf(-b8[j])) * frcp(1.f + __expf(-a8[j]));
;       }
;     }
;     }
;     gemm_core(tid, WSU(WbT) + ((size_t)l * 1024 + fbase) * 512, 512, WSU(GB) + (size_t)tbase * 512, 512, 512, acc, true);
	v_and_b32_e32 v137, 0xffff0000, v232
	v_add_f32_e32 v0, 1.0, v0
	v_lshlrev_b32_e32 v152, 16, v234
	v_and_b32_e32 v153, 0xffff0000, v234
	v_rcp_f32_e32 v134, v0
	v_mul_f32_e32 v0, 0xbfb8aa3b, v137
	v_lshlrev_b32_e32 v145, 16, v233
	v_and_b32_e32 v151, 0xffff0000, v233
	v_exp_f32_e32 v133, v0
	v_mul_f32_e32 v0, 0xbfb8aa3b, v138
	v_exp_f32_e32 v0, v0
	v_lshlrev_b32_e32 v136, 16, v232
	v_lshlrev_b32_e32 v154, 16, v235
	v_and_b32_e32 v155, 0xffff0000, v235
	v_add_f32_e32 v0, 1.0, v0
	v_rcp_f32_e32 v135, v0
	v_mul_f32_e32 v0, 0xbfb8aa3b, v145
	v_mul_f32_e32 v132, 0xbfb8aa3b, v136
	v_exp_f32_e32 v136, v0
	v_mul_f32_e32 v0, 0xbfb8aa3b, v139
	v_exp_f32_e32 v0, v0
	v_exp_f32_e32 v132, v132
	v_add_f32_e32 v0, 1.0, v0
	v_rcp_f32_e32 v138, v0
	v_mul_f32_e32 v0, 0xbfb8aa3b, v151
	v_exp_f32_e32 v137, v0
	v_mul_f32_e32 v0, 0xbfb8aa3b, v140
	v_exp_f32_e32 v0, v0
	v_pk_add_f32 v[132:133], v[132:133], 1.0 op_sel_hi:[1,0]
	v_pk_add_f32 v[136:137], v[136:137], 1.0 op_sel_hi:[1,0]
	v_pk_mul_f32 v[132:133], v[132:133], v[134:135]
	v_add_f32_e32 v0, 1.0, v0
	v_rcp_f32_e32 v139, v0
	v_mul_f32_e32 v0, 0xbfb8aa3b, v152
	v_pk_mul_f32 v[38:39], v[38:39], v[132:133]
	v_exp_f32_e32 v132, v0
	v_mul_f32_e32 v0, 0xbfb8aa3b, v141
	v_exp_f32_e32 v0, v0
	v_pk_mul_f32 v[134:135], v[136:137], v[138:139]
	v_add_f32_e32 v0, 1.0, v0
	v_pk_mul_f32 v[40:41], v[40:41], v[134:135]
	v_rcp_f32_e32 v134, v0
	v_mul_f32_e32 v0, 0xbfb8aa3b, v153
	v_exp_f32_e32 v133, v0
	v_mul_f32_e32 v0, 0xbfb8aa3b, v142
	v_exp_f32_e32 v0, v0
	v_pk_add_f32 v[132:133], v[132:133], 1.0 op_sel_hi:[1,0]
	v_add_f32_e32 v0, 1.0, v0
	v_rcp_f32_e32 v135, v0
	v_mul_f32_e32 v0, 0xbfb8aa3b, v154
	v_exp_f32_e32 v136, v0
	v_mul_f32_e32 v0, 0xbfb8aa3b, v143
	v_exp_f32_e32 v0, v0
	v_pk_mul_f32 v[132:133], v[132:133], v[134:135]
	v_add_f32_e32 v0, 1.0, v0
	v_rcp_f32_e32 v138, v0
	v_mul_f32_e32 v0, 0xbfb8aa3b, v155
	v_exp_f32_e32 v137, v0
	v_mul_f32_e32 v0, 0xbfb8aa3b, v144
	v_exp_f32_e32 v0, v0
	v_pk_mul_f32 v[34:35], v[34:35], v[132:133]
	v_pk_add_f32 v[136:137], v[136:137], 1.0 op_sel_hi:[1,0]
	v_add_f32_e32 v0, 1.0, v0
	v_rcp_f32_e32 v139, v0
	s_nop 0
	v_pk_mul_f32 v[134:135], v[136:137], v[138:139]
	s_nop 0
	v_pk_mul_f32 v[36:37], v[36:37], v[134:135]
	s_waitcnt vmcnt(1)
	v_lshlrev_b32_e32 v0, 16, v236
	v_and_b32_e32 v136, 0xffff0000, v236
	v_lshlrev_b32_e32 v137, 16, v237
	v_and_b32_e32 v138, 0xffff0000, v237
	v_mul_f32_e32 v0, 0xbfb8aa3b, v0
	v_exp_f32_e32 v0, v0
	v_lshlrev_b32_e32 v141, 16, v239
	v_and_b32_e32 v142, 0xffff0000, v239
	v_lshlrev_b32_e32 v139, 16, v238
	v_add_f32_e32 v0, 1.0, v0
	v_and_b32_e32 v140, 0xffff0000, v238
	s_waitcnt vmcnt(0)
	s_waitcnt lgkmcnt(0)
	s_barrier
	s_waitcnt vmcnt(0)
	v_and_b32_e32 v135, 0xffff0000, v240
	v_lshlrev_b32_e32 v145, 16, v242
	v_and_b32_e32 v151, 0xffff0000, v242
	v_rcp_f32_e32 v132, v0
	v_mul_f32_e32 v0, 0xbfb8aa3b, v135
	v_lshlrev_b32_e32 v143, 16, v241
	v_and_b32_e32 v144, 0xffff0000, v241
	v_exp_f32_e32 v131, v0
	v_mul_f32_e32 v0, 0xbfb8aa3b, v136
	v_exp_f32_e32 v0, v0
	v_lshlrev_b32_e32 v134, 16, v240
	v_lshlrev_b32_e32 v152, 16, v243
	v_and_b32_e32 v153, 0xffff0000, v243
	v_add_f32_e32 v0, 1.0, v0
	v_rcp_f32_e32 v133, v0
	v_mul_f32_e32 v0, 0xbfb8aa3b, v143
	v_mul_f32_e32 v130, 0xbfb8aa3b, v134
	v_exp_f32_e32 v134, v0
	v_mul_f32_e32 v0, 0xbfb8aa3b, v137
	v_exp_f32_e32 v0, v0
	v_exp_f32_e32 v130, v130
	v_add_f32_e32 v0, 1.0, v0
	v_rcp_f32_e32 v136, v0
	v_mul_f32_e32 v0, 0xbfb8aa3b, v144
	v_exp_f32_e32 v135, v0
	v_mul_f32_e32 v0, 0xbfb8aa3b, v138
	v_exp_f32_e32 v0, v0
	v_pk_add_f32 v[130:131], v[130:131], 1.0 op_sel_hi:[1,0]
	v_pk_add_f32 v[134:135], v[134:135], 1.0 op_sel_hi:[1,0]
	v_pk_mul_f32 v[130:131], v[130:131], v[132:133]
	v_add_f32_e32 v0, 1.0, v0
	v_rcp_f32_e32 v137, v0
	v_mul_f32_e32 v0, 0xbfb8aa3b, v145
	v_pk_mul_f32 v[14:15], v[14:15], v[130:131]
	v_exp_f32_e32 v130, v0
	v_mul_f32_e32 v0, 0xbfb8aa3b, v139
	v_exp_f32_e32 v0, v0
	v_pk_mul_f32 v[132:133], v[134:135], v[136:137]
	v_add_f32_e32 v0, 1.0, v0
	v_pk_mul_f32 v[16:17], v[16:17], v[132:133]
	v_rcp_f32_e32 v132, v0
	v_mul_f32_e32 v0, 0xbfb8aa3b, v151
	v_exp_f32_e32 v131, v0
	v_mul_f32_e32 v0, 0xbfb8aa3b, v140
	v_exp_f32_e32 v0, v0
	v_pk_add_f32 v[130:131], v[130:131], 1.0 op_sel_hi:[1,0]
	v_add_f32_e32 v0, 1.0, v0
	v_rcp_f32_e32 v133, v0
	v_mul_f32_e32 v0, 0xbfb8aa3b, v152
	v_exp_f32_e32 v134, v0
	v_mul_f32_e32 v0, 0xbfb8aa3b, v141
	v_exp_f32_e32 v0, v0
	v_pk_mul_f32 v[130:131], v[130:131], v[132:133]
	v_add_f32_e32 v0, 1.0, v0
	v_rcp_f32_e32 v136, v0
	v_mul_f32_e32 v0, 0xbfb8aa3b, v153
	v_exp_f32_e32 v135, v0
	v_mul_f32_e32 v0, 0xbfb8aa3b, v142
	v_exp_f32_e32 v0, v0
	v_pk_mul_f32 v[10:11], v[10:11], v[130:131]
	v_or_b32_e32 v130, s28, v147
	s_add_i32 s28, s27, 0x10000
	v_add_f32_e32 v0, 1.0, v0
	v_rcp_f32_e32 v137, v0
	v_pk_add_f32 v[134:135], v[134:135], 1.0 op_sel_hi:[1,0]
	s_and_b32 s28, s28, 0xffffe000
	v_add3_u32 v130, v130, v149, s26
	v_pk_mul_f32 v[132:133], v[134:135], v[136:137]
	v_or_b32_e32 v134, s28, v147
	s_add_i32 s28, s27, 0x8000
	s_and_b32 s28, s28, 0xffffe000
	s_and_b32 s27, s27, 0xffffe000
	v_or_b32_e32 v138, s28, v147
	v_or_b32_e32 v142, s27, v147
	v_add3_u32 v134, v134, v149, s26
	v_add3_u32 v138, v138, v149, s26
	v_add3_u32 v142, v142, v149, s26
	v_lshlrev_b32_e32 v0, 2, v148
	v_ashrrev_i32_e32 v131, 31, v130
	v_ashrrev_i32_e32 v135, 31, v134
	v_ashrrev_i32_e32 v139, 31, v138
	v_ashrrev_i32_e32 v143, 31, v142
	v_pk_mul_f32 v[12:13], v[12:13], v[132:133]
	v_and_b32_e32 v0, 32, v0
	v_lshlrev_b64 v[132:133], 1, v[130:131]
	v_lshlrev_b64 v[136:137], 1, v[134:135]
	v_lshlrev_b64 v[140:141], 1, v[138:139]
	v_lshlrev_b64 v[144:145], 1, v[142:143]
	v_bitop3_b32 v0, v194, v0, v193 bitop3:0x36
	v_lshl_add_u64 v[130:131], s[22:23], 0, v[132:133]
	v_lshl_add_u64 v[132:133], s[24:25], 0, v[132:133]
	v_lshl_add_u64 v[134:135], s[22:23], 0, v[136:137]
	v_lshl_add_u64 v[136:137], s[24:25], 0, v[136:137]
	v_lshl_add_u64 v[138:139], s[22:23], 0, v[140:141]
	v_lshl_add_u64 v[140:141], s[24:25], 0, v[140:141]
	v_lshl_add_u64 v[142:143], s[22:23], 0, v[144:145]
	v_lshl_add_u64 v[144:145], s[24:25], 0, v[144:145]
	s_mov_b32 s24, 0
	s_mov_b64 s[22:23], 0
; #define WAIT_V0() asm volatile("s_waitcnt vmcnt(0)" ::: "memory")
; DI void gemm_core(const int tid, const u16* __restrict__ Wb, int ldw, const u16* __restrict__ Xb, int ldx, int K, f32x4 (&acc)[8][4], const bool pre = false) {
;     ...
;   auto stage = [&](int buf, int kt) {
; #pragma unroll
;     for (int i = 0; i < 4; ++i) {
;       __builtin_amdgcn_global_load_lds((const unsigned*)(Wb + offw[i] + kt * 64), (unsigned*)(shm + buf * STAGE_B + wid * 1024 + i * 8192), 16, 0, 0);
;       __builtin_amdgcn_global_load_lds((const unsigned*)(Xb + offx[i] + kt * 64), (unsigned*)(shm + buf * STAGE_B + TILE_B + wid * 1024 + i * 8192), 16, 0, 0);
;     }
;   };
;   const int nt = K >> 6;
;   if (!pre) stage(0, 0);
;   WAIT_V0(); __syncthreads();
;   for (int t = 0; t < nt; ++t) {
;     const int cur = t & 1;
;     if (t + 1 < nt) stage(cur ^ 1, t + 1);
; #pragma unroll
;     for (int ks = 0; ks < 2; ++ks) {
;       bf16x8 At[8], Bf[4];
;       const char* pb = shm + cur * STAGE_B + TILE_B + lds_byte(wc * 64 + fr, fq * 8) + ks * 1024;
;       const char* pa = shm + cur * STAGE_B + lds_byte(wr * 128 + fr, fq * 8) + ks * 1024;
; #pragma unroll
;       for (int n = 0; n < 4; ++n) Bf[n] = *(const bf16x8*)(pb + n * 2048);
; #pragma unroll
;       for (int m = 0; m < 8; ++m) At[m] = *(const bf16x8*)(pa + m * 2048);
; #pragma unroll
;       for (int m = 0; m < 8; ++m)
; #pragma unroll
;         for (int n = 0; n < 4; ++n)
;           acc[m][n] = __builtin_amdgcn_mfma_f32_16x16x32_bf16(At[m], Bf[n], acc[m][n], 0, 0, 0);
;       __builtin_amdgcn_sched_group_barrier(0x100, 5, 0);
; #pragma unroll
;       for (int m = 0; m < 8; ++m) {
;         __builtin_amdgcn_sched_group_barrier(0x008, 1, 0);
;         if (m < 7) __builtin_amdgcn_sched_group_barrier(0x100, 1, 0);
;         __builtin_amdgcn_sched_group_barrier(0x008, 3, 0);
;       }
;       __builtin_amdgcn_sched_barrier(0);
;     }
;     WAIT_V0(); __syncthreads();
.LBB0_221:
	s_and_b32 s25, s24, 0x10000
	s_xor_b32 s26, s25, 0x10000
	s_add_i32 s26, s17, s26
	s_add_i32 vcc_lo, s21, s25
	s_nop 1
	v_add_u32_e32 v147, vcc_lo, v0
	ds_read_b128 v[152:155], v147
	s_or_b32 s25, s1, s25
	v_add_u32_e32 v148, s25, v146
	ds_read_b128 v[156:159], v148 offset:32768
	ds_read_b128 v[160:163], v148 offset:34816
	ds_read_b128 v[164:167], v148 offset:36864
	ds_read_b128 v[168:171], v148 offset:38912
	s_mov_b32 m0, s26
	s_nop 0
	global_load_lds_dwordx4 v[144:145], off
	v_lshl_add_u64 v[144:145], v[144:145], 0, s[64:65]
	s_waitcnt lgkmcnt(0)
	v_mfma_f32_16x16x32_bf16 v[2:5], v[152:155], v[156:159], v[2:5]
	ds_read_b128 v[172:175], v147 offset:2048
	v_mfma_f32_16x16x32_bf16 v[58:61], v[152:155], v[160:163], v[58:61]
	v_mfma_f32_16x16x32_bf16 v[122:125], v[152:155], v[164:167], v[122:125]
	v_mfma_f32_16x16x32_bf16 v[70:73], v[152:155], v[168:171], v[70:73]
	s_waitcnt lgkmcnt(0)
	v_mfma_f32_16x16x32_bf16 v[6:9], v[172:175], v[156:159], v[6:9]
	ds_read_b128 v[152:155], v147 offset:4096
	s_add_i32 m0, s26, 0x8000
	s_nop 0
	global_load_lds_dwordx4 v[142:143], off
	v_lshl_add_u64 v[142:143], v[142:143], 0, s[64:65]
	v_mfma_f32_16x16x32_bf16 v[62:65], v[172:175], v[160:163], v[62:65]
	v_mfma_f32_16x16x32_bf16 v[126:129], v[172:175], v[164:167], v[126:129]
	v_mfma_f32_16x16x32_bf16 v[66:69], v[172:175], v[168:171], v[66:69]
	s_waitcnt lgkmcnt(0)
	v_mfma_f32_16x16x32_bf16 v[18:21], v[152:155], v[156:159], v[18:21]
	ds_read_b128 v[172:175], v147 offset:6144
	s_add_i32 m0, s26, 0x2000
	s_nop 0
	global_load_lds_dwordx4 v[140:141], off
	v_lshl_add_u64 v[140:141], v[140:141], 0, s[64:65]
	v_mfma_f32_16x16x32_bf16 v[74:77], v[152:155], v[160:163], v[74:77]
	v_mfma_f32_16x16x32_bf16 v[118:121], v[152:155], v[164:167], v[118:121]
	v_mfma_f32_16x16x32_bf16 v[54:57], v[152:155], v[168:171], v[54:57]
	s_waitcnt lgkmcnt(0)
	v_mfma_f32_16x16x32_bf16 v[22:25], v[172:175], v[156:159], v[22:25]
	ds_read_b128 v[152:155], v147 offset:8192
	s_add_i32 m0, s26, 0xa000
	s_nop 0
	global_load_lds_dwordx4 v[138:139], off
	v_lshl_add_u64 v[138:139], v[138:139], 0, s[64:65]
	v_mfma_f32_16x16x32_bf16 v[78:81], v[172:175], v[160:163], v[78:81]
	v_mfma_f32_16x16x32_bf16 v[114:117], v[172:175], v[164:167], v[114:117]
	v_mfma_f32_16x16x32_bf16 v[50:53], v[172:175], v[168:171], v[50:53]
	s_waitcnt lgkmcnt(0)
	v_mfma_f32_16x16x32_bf16 v[26:29], v[152:155], v[156:159], v[26:29]
	ds_read_b128 v[172:175], v147 offset:10240
	s_add_i32 m0, s26, 0x4000
	s_nop 0
	global_load_lds_dwordx4 v[136:137], off
	v_lshl_add_u64 v[136:137], v[136:137], 0, s[64:65]
	v_mfma_f32_16x16x32_bf16 v[90:93], v[152:155], v[160:163], v[90:93]
	v_mfma_f32_16x16x32_bf16 v[102:105], v[152:155], v[164:167], v[102:105]
	v_mfma_f32_16x16x32_bf16 v[38:41], v[152:155], v[168:171], v[38:41]
	s_waitcnt lgkmcnt(0)
	v_mfma_f32_16x16x32_bf16 v[30:33], v[172:175], v[156:159], v[30:33]
	ds_read_b128 v[152:155], v147 offset:12288
	s_add_i32 m0, s26, 0xc000
	s_nop 0
	global_load_lds_dwordx4 v[134:135], off
	v_lshl_add_u64 v[134:135], v[134:135], 0, s[64:65]
	v_mfma_f32_16x16x32_bf16 v[94:97], v[172:175], v[160:163], v[94:97]
	v_mfma_f32_16x16x32_bf16 v[98:101], v[172:175], v[164:167], v[98:101]
	v_mfma_f32_16x16x32_bf16 v[34:37], v[172:175], v[168:171], v[34:37]
	s_waitcnt lgkmcnt(0)
	v_mfma_f32_16x16x32_bf16 v[42:45], v[152:155], v[156:159], v[42:45]
	ds_read_b128 v[172:175], v147 offset:14336
	s_add_i32 m0, s26, 0x6000
	s_nop 0
	global_load_lds_dwordx4 v[132:133], off
	v_lshl_add_u64 v[132:133], v[132:133], 0, s[64:65]
	v_mfma_f32_16x16x32_bf16 v[106:109], v[152:155], v[160:163], v[106:109]
	v_mfma_f32_16x16x32_bf16 v[86:89], v[152:155], v[164:167], v[86:89]
	v_mfma_f32_16x16x32_bf16 v[14:17], v[152:155], v[168:171], v[14:17]
	s_waitcnt lgkmcnt(0)
	v_mfma_f32_16x16x32_bf16 v[46:49], v[172:175], v[156:159], v[46:49]
	s_add_i32 m0, s26, 0xe000
	s_nop 0
	global_load_lds_dwordx4 v[130:131], off
	v_lshl_add_u64 v[130:131], v[130:131], 0, s[64:65]
	v_mfma_f32_16x16x32_bf16 v[110:113], v[172:175], v[160:163], v[110:113]
	v_mfma_f32_16x16x32_bf16 v[82:85], v[172:175], v[164:167], v[82:85]
	v_mfma_f32_16x16x32_bf16 v[10:13], v[172:175], v[168:171], v[10:13]
	ds_read_b128 v[152:155], v147 offset:1024
	ds_read_b128 v[156:159], v148 offset:33792
	ds_read_b128 v[160:163], v148 offset:35840
	ds_read_b128 v[164:167], v148 offset:37888
	ds_read_b128 v[168:171], v148 offset:39936
	s_waitcnt lgkmcnt(0)
	v_mfma_f32_16x16x32_bf16 v[2:5], v[152:155], v[156:159], v[2:5]
	ds_read_b128 v[172:175], v147 offset:3072
	v_mfma_f32_16x16x32_bf16 v[58:61], v[152:155], v[160:163], v[58:61]
	v_mfma_f32_16x16x32_bf16 v[122:125], v[152:155], v[164:167], v[122:125]
	v_mfma_f32_16x16x32_bf16 v[70:73], v[152:155], v[168:171], v[70:73]
	s_waitcnt lgkmcnt(0)
	v_mfma_f32_16x16x32_bf16 v[6:9], v[172:175], v[156:159], v[6:9]
	ds_read_b128 v[152:155], v147 offset:5120
	v_mfma_f32_16x16x32_bf16 v[62:65], v[172:175], v[160:163], v[62:65]
	v_mfma_f32_16x16x32_bf16 v[126:129], v[172:175], v[164:167], v[126:129]
	v_mfma_f32_16x16x32_bf16 v[66:69], v[172:175], v[168:171], v[66:69]
	s_waitcnt lgkmcnt(0)
	v_mfma_f32_16x16x32_bf16 v[18:21], v[152:155], v[156:159], v[18:21]
	ds_read_b128 v[172:175], v147 offset:7168
	v_mfma_f32_16x16x32_bf16 v[74:77], v[152:155], v[160:163], v[74:77]
	v_mfma_f32_16x16x32_bf16 v[118:121], v[152:155], v[164:167], v[118:121]
	v_mfma_f32_16x16x32_bf16 v[54:57], v[152:155], v[168:171], v[54:57]
	s_waitcnt lgkmcnt(0)
	v_mfma_f32_16x16x32_bf16 v[22:25], v[172:175], v[156:159], v[22:25]
	ds_read_b128 v[152:155], v147 offset:9216
	v_mfma_f32_16x16x32_bf16 v[78:81], v[172:175], v[160:163], v[78:81]
	v_mfma_f32_16x16x32_bf16 v[114:117], v[172:175], v[164:167], v[114:117]
	v_mfma_f32_16x16x32_bf16 v[50:53], v[172:175], v[168:171], v[50:53]
	s_waitcnt lgkmcnt(0)
; #define WAIT_V0() asm volatile("s_waitcnt vmcnt(0)" ::: "memory")
; DI void gemm_core(const int tid, const u16* __restrict__ Wb, int ldw, const u16* __restrict__ Xb, int ldx, int K, f32x4 (&acc)[8][4], const bool pre = false) {
;     ...
;     for (int ks = 0; ks < 2; ++ks) {
;       bf16x8 At[8], Bf[4];
;       const char* pb = shm + cur * STAGE_B + TILE_B + lds_byte(wc * 64 + fr, fq * 8) + ks * 1024;
;       const char* pa = shm + cur * STAGE_B + lds_byte(wr * 128 + fr, fq * 8) + ks * 1024;
; #pragma unroll
;       for (int n = 0; n < 4; ++n) Bf[n] = *(const bf16x8*)(pb + n * 2048);
; #pragma unroll
;       for (int m = 0; m < 8; ++m) At[m] = *(const bf16x8*)(pa + m * 2048);
; #pragma unroll
;       for (int m = 0; m < 8; ++m)
; #pragma unroll
;         for (int n = 0; n < 4; ++n)
;           acc[m][n] = __builtin_amdgcn_mfma_f32_16x16x32_bf16(At[m], Bf[n], acc[m][n], 0, 0, 0);
;       __builtin_amdgcn_sched_group_barrier(0x100, 5, 0);
; #pragma unroll
;       for (int m = 0; m < 8; ++m) {
;         __builtin_amdgcn_sched_group_barrier(0x008, 1, 0);
;         if (m < 7) __builtin_amdgcn_sched_group_barrier(0x100, 1, 0);
;         __builtin_amdgcn_sched_group_barrier(0x008, 3, 0);
;       }
;       __builtin_amdgcn_sched_barrier(0);
;     }
;     WAIT_V0(); __syncthreads();
	v_mfma_f32_16x16x32_bf16 v[26:29], v[152:155], v[156:159], v[26:29]
	ds_read_b128 v[172:175], v147 offset:11264
	v_mfma_f32_16x16x32_bf16 v[90:93], v[152:155], v[160:163], v[90:93]
	v_mfma_f32_16x16x32_bf16 v[102:105], v[152:155], v[164:167], v[102:105]
	v_mfma_f32_16x16x32_bf16 v[38:41], v[152:155], v[168:171], v[38:41]
	s_waitcnt lgkmcnt(0)
	v_mfma_f32_16x16x32_bf16 v[30:33], v[172:175], v[156:159], v[30:33]
	ds_read_b128 v[152:155], v147 offset:13312
	v_mfma_f32_16x16x32_bf16 v[94:97], v[172:175], v[160:163], v[94:97]
	v_mfma_f32_16x16x32_bf16 v[98:101], v[172:175], v[164:167], v[98:101]
	v_mfma_f32_16x16x32_bf16 v[34:37], v[172:175], v[168:171], v[34:37]
	s_waitcnt lgkmcnt(0)
	v_mfma_f32_16x16x32_bf16 v[42:45], v[152:155], v[156:159], v[42:45]
	ds_read_b128 v[172:175], v147 offset:15360
	v_mfma_f32_16x16x32_bf16 v[106:109], v[152:155], v[160:163], v[106:109]
	v_mfma_f32_16x16x32_bf16 v[86:89], v[152:155], v[164:167], v[86:89]
	v_mfma_f32_16x16x32_bf16 v[14:17], v[152:155], v[168:171], v[14:17]
	s_waitcnt lgkmcnt(0)
	v_mfma_f32_16x16x32_bf16 v[46:49], v[172:175], v[156:159], v[46:49]
	v_mfma_f32_16x16x32_bf16 v[110:113], v[172:175], v[160:163], v[110:113]
	v_mfma_f32_16x16x32_bf16 v[82:85], v[172:175], v[164:167], v[82:85]
	v_mfma_f32_16x16x32_bf16 v[10:13], v[172:175], v[168:171], v[10:13]
	s_add_i32 s24, s24, 0x10000
	s_waitcnt vmcnt(0)
	s_add_u32 s22, s22, 0x80
	s_addc_u32 s23, s23, 0
	s_cmpk_lg_i32 s22, 0x380
	s_waitcnt vmcnt(0)
	s_barrier
	s_cbranch_scc1 .LBB0_221
	v_add_u32_e32 v0, s21, v0
	v_add_u32_e32 v0, 0x10000, v0
	ds_read_b128 v[134:137], v0 offset:12288
	v_add_u32_e32 v150, s1, v150
	ds_read_b128 v[130:133], v0 offset:14336
	ds_read_b128 v[146:149], v0 offset:10240
	ds_read_b128 v[152:155], v0 offset:8192
	ds_read_b128 v[156:159], v0 offset:6144
	ds_read_b128 v[160:163], v150 offset:4096
	s_waitcnt lgkmcnt(0)
	v_mfma_f32_16x16x32_bf16 v[142:145], v[134:137], v[160:163], v[86:89]
	s_nop 2
	ds_read_b128 v[86:89], v150 offset:2048
	s_waitcnt lgkmcnt(0)
	v_mfma_f32_16x16x32_bf16 v[90:93], v[152:155], v[86:89], v[90:93]
	v_mfma_f32_16x16x32_bf16 v[138:141], v[130:133], v[160:163], v[82:85]
	v_mfma_f32_16x16x32_bf16 v[98:101], v[146:149], v[160:163], v[98:101]
	v_mfma_f32_16x16x32_bf16 v[114:117], v[156:159], v[160:163], v[114:117]
	s_nop 0
	ds_read_b128 v[82:85], v0 offset:4096
	s_waitcnt lgkmcnt(0)
	v_mfma_f32_16x16x32_bf16 v[118:121], v[82:85], v[160:163], v[118:121]
	v_mfma_f32_16x16x32_bf16 v[200:203], v[134:137], v[86:89], v[106:109]
	ds_read_b128 v[164:167], v150 offset:6144
	s_waitcnt lgkmcnt(0)
	v_mfma_f32_16x16x32_bf16 v[182:185], v[146:149], v[164:167], v[34:37]
	v_mfma_f32_16x16x32_bf16 v[204:207], v[152:155], v[164:167], v[38:41]
	s_nop 1
	ds_read_b128 v[34:37], v150
	ds_read_b128 v[106:109], v0
	s_waitcnt lgkmcnt(0)
	v_mfma_f32_16x16x32_bf16 v[38:41], v[106:109], v[164:167], v[70:73]
	v_mfma_f32_16x16x32_bf16 v[70:73], v[106:109], v[160:163], v[122:125]
	v_mfma_f32_16x16x32_bf16 v[58:61], v[106:109], v[86:89], v[58:61]
	v_mfma_f32_16x16x32_bf16 v[2:5], v[106:109], v[34:37], v[2:5]
	v_mfma_f32_16x16x32_bf16 v[106:109], v[152:155], v[34:37], v[26:29]
	v_mfma_f32_16x16x32_bf16 v[170:173], v[134:137], v[164:167], v[14:17]
	v_mfma_f32_16x16x32_bf16 v[14:17], v[130:133], v[164:167], v[10:13]
	s_nop 2
	ds_read_b128 v[10:13], v0 offset:2048
	s_waitcnt lgkmcnt(0)
	v_mfma_f32_16x16x32_bf16 v[66:69], v[10:13], v[164:167], v[66:69]
	v_mfma_f32_16x16x32_bf16 v[62:65], v[10:13], v[86:89], v[62:65]
	v_mfma_f32_16x16x32_bf16 v[122:125], v[10:13], v[160:163], v[126:129]
	v_mfma_f32_16x16x32_bf16 v[6:9], v[10:13], v[34:37], v[6:9]
	v_mfma_f32_16x16x32_bf16 v[10:13], v[82:85], v[34:37], v[18:21]
	v_mfma_f32_16x16x32_bf16 v[18:21], v[156:159], v[34:37], v[22:25]
	v_mfma_f32_16x16x32_bf16 v[110:113], v[130:133], v[86:89], v[110:113]
	v_mfma_f32_16x16x32_bf16 v[94:97], v[146:149], v[86:89], v[94:97]
	v_mfma_f32_16x16x32_bf16 v[74:77], v[82:85], v[86:89], v[74:77]
	v_mfma_f32_16x16x32_bf16 v[54:57], v[82:85], v[164:167], v[54:57]
	v_mfma_f32_16x16x32_bf16 v[50:53], v[156:159], v[164:167], v[50:53]
	v_mfma_f32_16x16x32_bf16 v[46:49], v[130:133], v[34:37], v[46:49]
	v_mfma_f32_16x16x32_bf16 v[30:33], v[146:149], v[34:37], v[30:33]
	v_mfma_f32_16x16x32_bf16 v[42:45], v[134:137], v[34:37], v[42:45]
	v_mfma_f32_16x16x32_bf16 v[146:149], v[156:159], v[86:89], v[78:81]
	v_mfma_f32_16x16x32_bf16 v[102:105], v[152:155], v[160:163], v[102:105]
	ds_read_b128 v[22:25], v0 offset:1024
	ds_read_b128 v[158:161], v150 offset:1024
	ds_read_b128 v[216:219], v150 offset:3072
	ds_read_b128 v[222:225], v150 offset:5120
	ds_read_b128 v[226:229], v150 offset:7168
	s_waitcnt lgkmcnt(3)
	v_mfma_f32_16x16x32_bf16 v[186:189], v[22:25], v[158:161], v[2:5]
	s_nop 2
	ds_read_b128 v[2:5], v0 offset:3072
	s_waitcnt lgkmcnt(3)
	v_mfma_f32_16x16x32_bf16 v[134:137], v[22:25], v[216:219], v[58:61]
	s_waitcnt lgkmcnt(2)
	v_mfma_f32_16x16x32_bf16 v[86:89], v[22:25], v[222:225], v[70:73]
	s_waitcnt lgkmcnt(1)
	v_mfma_f32_16x16x32_bf16 v[38:41], v[22:25], v[226:229], v[38:41]
	s_waitcnt lgkmcnt(0)
	v_mfma_f32_16x16x32_bf16 v[178:181], v[2:5], v[158:161], v[6:9]
	s_nop 2
	ds_read_b128 v[6:9], v0 offset:5120
	v_mfma_f32_16x16x32_bf16 v[130:133], v[2:5], v[216:219], v[62:65]
	v_mfma_f32_16x16x32_bf16 v[82:85], v[2:5], v[222:225], v[122:125]
	v_mfma_f32_16x16x32_bf16 v[34:37], v[2:5], v[226:229], v[66:69]
	s_waitcnt lgkmcnt(0)
	v_mfma_f32_16x16x32_bf16 v[174:177], v[6:9], v[158:161], v[10:13]
	ds_read_b128 v[2:5], v0 offset:7168
	v_mfma_f32_16x16x32_bf16 v[126:129], v[6:9], v[216:219], v[74:77]
	v_mfma_f32_16x16x32_bf16 v[78:81], v[6:9], v[222:225], v[118:121]
	v_mfma_f32_16x16x32_bf16 v[26:29], v[6:9], v[226:229], v[54:57]
	s_waitcnt lgkmcnt(0)
; DI uint4 ld_nt16(const void* q) { const ntu4 t = __builtin_nontemporal_load((const ntu4*)q); uint4 v; v.x = t[0]; v.y = t[1]; v.z = t[2]; v.w = t[3]; return v; }
; DI float sigmoidf_(float x) { return frcp(1.f + __expf(-x)); }
; #define WAIT_V0() asm volatile("s_waitcnt vmcnt(0)" ::: "memory")
; DI void gemm_core(const int tid, const u16* __restrict__ Wb, int ldw, const u16* __restrict__ Xb, int ldx, int K, f32x4 (&acc)[8][4], const bool pre = false) {
;     ...
;       for (int n = 0; n < 4; ++n) Bf[n] = *(const bf16x8*)(pb + n * 2048);
; #pragma unroll
;       for (int m = 0; m < 8; ++m) At[m] = *(const bf16x8*)(pa + m * 2048);
; #pragma unroll
;       for (int m = 0; m < 8; ++m)
; #pragma unroll
;         for (int n = 0; n < 4; ++n)
;           acc[m][n] = __builtin_amdgcn_mfma_f32_16x16x32_bf16(At[m], Bf[n], acc[m][n], 0, 0, 0);
;       __builtin_amdgcn_sched_group_barrier(0x100, 5, 0);
; #pragma unroll
;       for (int m = 0; m < 8; ++m) {
;         __builtin_amdgcn_sched_group_barrier(0x008, 1, 0);
;         if (m < 7) __builtin_amdgcn_sched_group_barrier(0x100, 1, 0);
;         __builtin_amdgcn_sched_group_barrier(0x008, 3, 0);
;       }
;       __builtin_amdgcn_sched_barrier(0);
;     }
;     WAIT_V0(); __syncthreads();
; template <int CT>
; DI void phase_g2(int c, int l) {
;     ...
;     uint4 gb16[4][4];
; #pragma unroll
;     for (int n = 0; n < 4; ++n)
; #pragma unroll
;       for (int mp = 0; mp < 4; ++mp) gb16[n][mp] = ld_nt16(WSU(MGB) + frag_off(pm, pn, wid, n, mp, lane));
; #pragma unroll
;     for (int n = 0; n < 4; ++n) {
;       const size_t tl = tbase + wc * 64 + n * 16 + fr;
; #pragma unroll
;       for (int mp = 0; mp < 4; ++mp) {
;         float b8[8];
;         unpack8(gb16[n][mp], b8);
; #pragma unroll
;         for (int mh = 0; mh < 2; ++mh) {
;           const int m = mp * 2 + mh, f = fbase + wr * 128 + m * 16 + fq * 4;
;           uint2 o;
;           o.x = pk2(acc[m][n][0] * sigmoidf_(b8[mh * 4 + 0]), acc[m][n][1] * sigmoidf_(b8[mh * 4 + 1]));
;           o.y = pk2(acc[m][n][2] * sigmoidf_(b8[mh * 4 + 2]), acc[m][n][3] * sigmoidf_(b8[mh * 4 + 3]));
;           *(uint2*)(WSU(MRG) + tl * 1024 + f) = o;
;         }
;       }
	v_mfma_f32_16x16x32_bf16 v[166:169], v[2:5], v[158:161], v[18:21]
	ds_read_b128 v[6:9], v0 offset:9216
	v_mfma_f32_16x16x32_bf16 v[118:121], v[2:5], v[216:219], v[146:149]
	v_mfma_f32_16x16x32_bf16 v[70:73], v[2:5], v[222:225], v[114:117]
	v_mfma_f32_16x16x32_bf16 v[22:25], v[2:5], v[226:229], v[50:53]
	s_waitcnt lgkmcnt(0)
	v_mfma_f32_16x16x32_bf16 v[162:165], v[6:9], v[158:161], v[106:109]
	ds_read_b128 v[2:5], v0 offset:11264
	v_mfma_f32_16x16x32_bf16 v[114:117], v[6:9], v[216:219], v[90:93]
	v_mfma_f32_16x16x32_bf16 v[66:69], v[6:9], v[222:225], v[102:105]
	v_mfma_f32_16x16x32_bf16 v[18:21], v[6:9], v[226:229], v[204:207]
	s_waitcnt lgkmcnt(0)
	v_mfma_f32_16x16x32_bf16 v[154:157], v[2:5], v[158:161], v[30:33]
	ds_read_b128 v[6:9], v0 offset:13312
	v_mfma_f32_16x16x32_bf16 v[106:109], v[2:5], v[216:219], v[94:97]
	v_mfma_f32_16x16x32_bf16 v[58:61], v[2:5], v[222:225], v[98:101]
	v_mfma_f32_16x16x32_bf16 v[10:13], v[2:5], v[226:229], v[182:185]
	s_waitcnt lgkmcnt(0)
	v_mfma_f32_16x16x32_bf16 v[150:153], v[6:9], v[158:161], v[42:45]
	ds_read_b128 v[2:5], v0 offset:15360
	v_mfma_f32_16x16x32_bf16 v[102:105], v[6:9], v[216:219], v[200:203]
	v_mfma_f32_16x16x32_bf16 v[54:57], v[6:9], v[222:225], v[142:145]
	v_mfma_f32_16x16x32_bf16 v[6:9], v[6:9], v[226:229], v[170:173]
	s_waitcnt lgkmcnt(0)
	v_mfma_f32_16x16x32_bf16 v[142:145], v[2:5], v[158:161], v[46:49]
	v_mfma_f32_16x16x32_bf16 v[94:97], v[2:5], v[216:219], v[110:113]
	v_mfma_f32_16x16x32_bf16 v[46:49], v[2:5], v[222:225], v[138:141]
	v_mfma_f32_16x16x32_bf16 v[2:5], v[2:5], v[226:229], v[14:17]
	v_mov_b32_e32 v191, v210
	s_waitcnt vmcnt(0)
	s_barrier
	s_mov_b64 s[24:25], 0
	v_readfirstlane_b32 s1, v191
	s_ashr_i32 s17, s1, 6
	s_ashr_i32 s21, s17, 31
	s_add_u32 s22, s13, s17
	s_addc_u32 s23, s15, s21
	s_lshl_b64 s[22:23], s[22:23], 14
	s_add_u32 s22, s8, s22
	v_lshlrev_b32_e32 v0, 4, v191
	s_addc_u32 s23, s9, s23
	v_and_b32_e32 v0, 0x3f0, v0
	global_load_dwordx4 v[200:203], v0, s[22:23] nt
	global_load_dwordx4 v[182:185], v0, s[22:23] offset:1024 nt
	s_and_b32 s1, s1, 0xc0
	v_lshl_add_u64 v[14:15], s[22:23], 0, v[0:1]
	global_load_dwordx4 v[170:173], v0, s[22:23] offset:2048 nt
	global_load_dwordx4 v[158:161], v0, s[22:23] offset:3072 nt
	v_and_or_b32 v0, v191, 15, s1
	s_lshl_b32 s1, s17, 5
	s_and_b32 s1, s1, 0xffffff80
	v_or_b32_e32 v190, s16, v0
	s_add_i32 s1, s1, s20
	v_lshrrev_b32_e32 v0, 2, v191
	v_and_or_b32 v204, v0, 12, s1
	v_ashrrev_i32_e32 v191, 31, v190
	v_lshlrev_b64 v[206:207], 11, v[190:191]
	v_add_co_u32_e32 v16, vcc, s89, v14
	s_movk_i32 s13, 0x3000
	s_nop 0
	v_addc_co_u32_e32 v17, vcc, 0, v15, vcc
	v_add_co_u32_e32 v30, vcc, s95, v14
	v_lshl_add_u64 v[206:207], s[10:11], 0, v[206:207]
	s_nop 0
	v_addc_co_u32_e32 v31, vcc, 0, v15, vcc
	v_add_co_u32_e32 v14, vcc, s13, v14
	global_load_dwordx4 v[146:149], v[30:31], off offset:-4096 nt
	s_nop 0
	v_addc_co_u32_e32 v15, vcc, 0, v15, vcc
	global_load_dwordx4 v[138:141], v[16:17], off offset:1024 nt
	global_load_dwordx4 v[122:125], v[16:17], off offset:2048 nt
	global_load_dwordx4 v[110:113], v[16:17], off offset:3072 nt
	global_load_dwordx4 v[98:101], v[30:31], off nt
	global_load_dwordx4 v[90:93], v[30:31], off offset:1024 nt
	global_load_dwordx4 v[74:77], v[30:31], off offset:2048 nt
	global_load_dwordx4 v[62:65], v[30:31], off offset:3072 nt
	global_load_dwordx4 v[50:53], v[14:15], off nt
	global_load_dwordx4 v[42:45], v[14:15], off offset:1024 nt
	s_mov_b32 s88, 0x800000
	global_load_dwordx4 v[30:33], v[14:15], off offset:2048 nt
	s_waitcnt vmcnt(14)
	v_lshlrev_b32_e32 v0, 16, v200
	v_mul_f32_e32 v0, 0xbfb8aa3b, v0
	v_exp_f32_e32 v0, v0
	v_and_b32_e32 v191, 0xffff0000, v200
	v_lshlrev_b32_e32 v199, 16, v201
	v_and_b32_e32 v205, 0xffff0000, v201
	v_add_f32_e32 v0, 1.0, v0
	v_rcp_f32_e32 v200, v0
	v_mul_f32_e32 v0, 0xbfb8aa3b, v191
	v_exp_f32_e32 v0, v0
	v_lshlrev_b32_e32 v208, 16, v202
	v_and_b32_e32 v202, 0xffff0000, v202
	global_load_dwordx4 v[14:17], v[14:15], off offset:3072 nt
	v_add_f32_e32 v0, 1.0, v0
	v_rcp_f32_e32 v201, v0
	v_mul_f32_e32 v0, 0xbfb8aa3b, v199
	v_exp_f32_e32 v0, v0
	v_lshlrev_b32_e32 v209, 16, v203
	v_pk_mul_f32 v[186:187], v[186:187], v[200:201]
	v_and_b32_e32 v203, 0xffff0000, v203
	v_add_f32_e32 v0, 1.0, v0
	v_cvt_pk_bf16_f32 v200, v186, v187
	v_rcp_f32_e32 v186, v0
	v_mul_f32_e32 v0, 0xbfb8aa3b, v205
	v_exp_f32_e32 v0, v0
	v_ashrrev_i32_e32 v205, 31, v204
	v_add_f32_e32 v0, 1.0, v0
	v_rcp_f32_e32 v187, v0
	v_mul_f32_e32 v0, 0xbfb8aa3b, v208
	v_exp_f32_e32 v0, v0
	v_pk_mul_f32 v[186:187], v[188:189], v[186:187]
	s_nop 0
	v_cvt_pk_bf16_f32 v201, v186, v187
	v_lshlrev_b64 v[186:187], 1, v[204:205]
	v_lshl_add_u64 v[188:189], v[206:207], 0, v[186:187]
	v_add_f32_e32 v0, 1.0, v0
	global_store_dwordx2 v[188:189], v[200:201], off
	v_rcp_f32_e32 v200, v0
	v_mul_f32_e32 v0, 0xbfb8aa3b, v202
	v_exp_f32_e32 v0, v0
	s_nop 0
	v_add_f32_e32 v0, 1.0, v0
	v_rcp_f32_e32 v201, v0
	v_mul_f32_e32 v0, 0xbfb8aa3b, v209
	v_exp_f32_e32 v0, v0
	v_pk_mul_f32 v[178:179], v[178:179], v[200:201]
	s_nop 0
	v_cvt_pk_bf16_f32 v178, v178, v179
	v_add_f32_e32 v0, 1.0, v0
	v_rcp_f32_e32 v200, v0
	v_mul_f32_e32 v0, 0xbfb8aa3b, v203
	v_exp_f32_e32 v0, v0
	s_nop 0
	v_add_f32_e32 v0, 1.0, v0
	v_rcp_f32_e32 v201, v0
	s_waitcnt vmcnt(15)
; DI float sigmoidf_(float x) { return frcp(1.f + __expf(-x)); }
; template <int CT>
; DI void phase_g2(int c, int l) {
;     ...
;     for (int n = 0; n < 4; ++n) {
;       const size_t tl = tbase + wc * 64 + n * 16 + fr;
; #pragma unroll
;       for (int mp = 0; mp < 4; ++mp) {
;         float b8[8];
;         unpack8(gb16[n][mp], b8);
; #pragma unroll
;         for (int mh = 0; mh < 2; ++mh) {
;           const int m = mp * 2 + mh, f = fbase + wr * 128 + m * 16 + fq * 4;
;           uint2 o;
;           o.x = pk2(acc[m][n][0] * sigmoidf_(b8[mh * 4 + 0]), acc[m][n][1] * sigmoidf_(b8[mh * 4 + 1]));
;           o.y = pk2(acc[m][n][2] * sigmoidf_(b8[mh * 4 + 2]), acc[m][n][3] * sigmoidf_(b8[mh * 4 + 3]));
;           *(uint2*)(WSU(MRG) + tl * 1024 + f) = o;
;         }
;       }
	v_lshlrev_b32_e32 v0, 16, v182
	v_mul_f32_e32 v0, 0xbfb8aa3b, v0
	v_exp_f32_e32 v0, v0
	v_pk_mul_f32 v[180:181], v[180:181], v[200:201]
	v_add_f32_e32 v0, 1.0, v0
	v_cvt_pk_bf16_f32 v179, v180, v181
	global_store_dwordx2 v[188:189], v[178:179], off offset:32
	v_and_b32_e32 v179, 0xffff0000, v182
	v_rcp_f32_e32 v178, v0
	v_mul_f32_e32 v0, 0xbfb8aa3b, v179
	v_exp_f32_e32 v0, v0
	v_lshlrev_b32_e32 v180, 16, v183
	v_and_b32_e32 v181, 0xffff0000, v183
	v_lshlrev_b32_e32 v182, 16, v184
	v_add_f32_e32 v0, 1.0, v0
	v_rcp_f32_e32 v179, v0
	v_mul_f32_e32 v0, 0xbfb8aa3b, v180
	v_exp_f32_e32 v0, v0
	v_and_b32_e32 v183, 0xffff0000, v184
	v_pk_mul_f32 v[174:175], v[174:175], v[178:179]
	v_lshlrev_b32_e32 v184, 16, v185
	v_add_f32_e32 v0, 1.0, v0
	v_rcp_f32_e32 v178, v0
	v_mul_f32_e32 v0, 0xbfb8aa3b, v181
	v_exp_f32_e32 v0, v0
	v_cvt_pk_bf16_f32 v174, v174, v175
	v_and_b32_e32 v185, 0xffff0000, v185
	v_add_f32_e32 v0, 1.0, v0
	v_rcp_f32_e32 v179, v0
	v_mul_f32_e32 v0, 0xbfb8aa3b, v182
	v_exp_f32_e32 v0, v0
	v_pk_mul_f32 v[176:177], v[176:177], v[178:179]
	s_nop 0
	v_cvt_pk_bf16_f32 v175, v176, v177
	v_add_f32_e32 v0, 1.0, v0
	global_store_dwordx2 v[188:189], v[174:175], off offset:64
	v_rcp_f32_e32 v174, v0
	v_mul_f32_e32 v0, 0xbfb8aa3b, v183
	v_exp_f32_e32 v0, v0
	s_nop 0
	v_add_f32_e32 v0, 1.0, v0
	v_rcp_f32_e32 v175, v0
	v_mul_f32_e32 v0, 0xbfb8aa3b, v184
	v_exp_f32_e32 v0, v0
	v_pk_mul_f32 v[166:167], v[166:167], v[174:175]
	s_nop 0
	v_cvt_pk_bf16_f32 v166, v166, v167
	v_add_f32_e32 v0, 1.0, v0
	v_rcp_f32_e32 v174, v0
	v_mul_f32_e32 v0, 0xbfb8aa3b, v185
	v_exp_f32_e32 v0, v0
	s_nop 0
	v_add_f32_e32 v0, 1.0, v0
	v_rcp_f32_e32 v175, v0
	s_waitcnt vmcnt(16)
	v_lshlrev_b32_e32 v0, 16, v170
	v_mul_f32_e32 v0, 0xbfb8aa3b, v0
	v_exp_f32_e32 v0, v0
	v_pk_mul_f32 v[168:169], v[168:169], v[174:175]
	v_add_f32_e32 v0, 1.0, v0
	v_cvt_pk_bf16_f32 v167, v168, v169
	global_store_dwordx2 v[188:189], v[166:167], off offset:96
	v_and_b32_e32 v167, 0xffff0000, v170
	v_rcp_f32_e32 v166, v0
	v_mul_f32_e32 v0, 0xbfb8aa3b, v167
	v_exp_f32_e32 v0, v0
	v_lshlrev_b32_e32 v168, 16, v171
	v_and_b32_e32 v169, 0xffff0000, v171
	v_lshlrev_b32_e32 v170, 16, v172
	v_add_f32_e32 v0, 1.0, v0
	v_rcp_f32_e32 v167, v0
	v_mul_f32_e32 v0, 0xbfb8aa3b, v168
	v_exp_f32_e32 v0, v0
	v_and_b32_e32 v171, 0xffff0000, v172
	v_pk_mul_f32 v[162:163], v[162:163], v[166:167]
	v_lshlrev_b32_e32 v172, 16, v173
	v_add_f32_e32 v0, 1.0, v0
	v_rcp_f32_e32 v166, v0
	v_mul_f32_e32 v0, 0xbfb8aa3b, v169
	v_exp_f32_e32 v0, v0
	v_cvt_pk_bf16_f32 v162, v162, v163
	v_and_b32_e32 v173, 0xffff0000, v173
	v_add_f32_e32 v0, 1.0, v0
	v_rcp_f32_e32 v167, v0
	v_mul_f32_e32 v0, 0xbfb8aa3b, v170
	v_exp_f32_e32 v0, v0
	v_pk_mul_f32 v[164:165], v[164:165], v[166:167]
	s_nop 0
	v_cvt_pk_bf16_f32 v163, v164, v165
	v_add_f32_e32 v0, 1.0, v0
	global_store_dwordx2 v[188:189], v[162:163], off offset:128
	v_rcp_f32_e32 v162, v0
	v_mul_f32_e32 v0, 0xbfb8aa3b, v171
	v_exp_f32_e32 v0, v0
	s_nop 0
	v_add_f32_e32 v0, 1.0, v0
	v_rcp_f32_e32 v163, v0
	v_mul_f32_e32 v0, 0xbfb8aa3b, v172
	v_exp_f32_e32 v0, v0
	v_pk_mul_f32 v[154:155], v[154:155], v[162:163]
	s_nop 0
	v_cvt_pk_bf16_f32 v154, v154, v155
	v_add_f32_e32 v0, 1.0, v0
	v_rcp_f32_e32 v162, v0
	v_mul_f32_e32 v0, 0xbfb8aa3b, v173
	v_exp_f32_e32 v0, v0
	s_nop 0
	v_add_f32_e32 v0, 1.0, v0
	v_rcp_f32_e32 v163, v0
	s_waitcnt vmcnt(17)
	v_lshlrev_b32_e32 v0, 16, v158
	v_mul_f32_e32 v0, 0xbfb8aa3b, v0
	v_exp_f32_e32 v0, v0
	v_pk_mul_f32 v[156:157], v[156:157], v[162:163]
	v_add_f32_e32 v0, 1.0, v0
	v_cvt_pk_bf16_f32 v155, v156, v157
	global_store_dwordx2 v[188:189], v[154:155], off offset:160
	v_and_b32_e32 v155, 0xffff0000, v158
	v_rcp_f32_e32 v154, v0
	v_mul_f32_e32 v0, 0xbfb8aa3b, v155
	v_exp_f32_e32 v0, v0
	v_lshlrev_b32_e32 v156, 16, v159
	v_and_b32_e32 v157, 0xffff0000, v159
	v_lshlrev_b32_e32 v158, 16, v160
	v_add_f32_e32 v0, 1.0, v0
	v_rcp_f32_e32 v155, v0
	v_mul_f32_e32 v0, 0xbfb8aa3b, v156
	v_exp_f32_e32 v0, v0
	v_and_b32_e32 v159, 0xffff0000, v160
	v_pk_mul_f32 v[150:151], v[150:151], v[154:155]
	v_lshlrev_b32_e32 v160, 16, v161
	v_add_f32_e32 v0, 1.0, v0
	v_rcp_f32_e32 v154, v0
	v_mul_f32_e32 v0, 0xbfb8aa3b, v157
	v_exp_f32_e32 v0, v0
	v_cvt_pk_bf16_f32 v150, v150, v151
	v_and_b32_e32 v161, 0xffff0000, v161
	v_add_f32_e32 v0, 1.0, v0
	v_rcp_f32_e32 v155, v0
	v_mul_f32_e32 v0, 0xbfb8aa3b, v158
	v_exp_f32_e32 v0, v0
	v_pk_mul_f32 v[152:153], v[152:153], v[154:155]
	s_nop 0
	v_cvt_pk_bf16_f32 v151, v152, v153
	v_add_f32_e32 v0, 1.0, v0
	global_store_dwordx2 v[188:189], v[150:151], off offset:192
	v_rcp_f32_e32 v150, v0
	v_mul_f32_e32 v0, 0xbfb8aa3b, v159
	v_exp_f32_e32 v0, v0
	s_nop 0
	v_add_f32_e32 v0, 1.0, v0
	v_rcp_f32_e32 v151, v0
	v_mul_f32_e32 v0, 0xbfb8aa3b, v160
	v_exp_f32_e32 v0, v0
	v_pk_mul_f32 v[142:143], v[142:143], v[150:151]
	s_nop 0
	v_cvt_pk_bf16_f32 v142, v142, v143
	v_add_f32_e32 v0, 1.0, v0
	v_rcp_f32_e32 v150, v0
	v_mul_f32_e32 v0, 0xbfb8aa3b, v161
	v_exp_f32_e32 v0, v0
	s_nop 0
	v_add_f32_e32 v0, 1.0, v0
	v_rcp_f32_e32 v151, v0
	s_waitcnt vmcnt(18)
; DI float sigmoidf_(float x) { return frcp(1.f + __expf(-x)); }
; template <int CT>
; DI void phase_g2(int c, int l) {
;     ...
;     for (int n = 0; n < 4; ++n) {
;       const size_t tl = tbase + wc * 64 + n * 16 + fr;
; #pragma unroll
;       for (int mp = 0; mp < 4; ++mp) {
;         float b8[8];
;         unpack8(gb16[n][mp], b8);
; #pragma unroll
;         for (int mh = 0; mh < 2; ++mh) {
;           const int m = mp * 2 + mh, f = fbase + wr * 128 + m * 16 + fq * 4;
;           uint2 o;
;           o.x = pk2(acc[m][n][0] * sigmoidf_(b8[mh * 4 + 0]), acc[m][n][1] * sigmoidf_(b8[mh * 4 + 1]));
;           o.y = pk2(acc[m][n][2] * sigmoidf_(b8[mh * 4 + 2]), acc[m][n][3] * sigmoidf_(b8[mh * 4 + 3]));
;           *(uint2*)(WSU(MRG) + tl * 1024 + f) = o;
;         }
;       }
	v_lshlrev_b32_e32 v0, 16, v146
	v_mul_f32_e32 v0, 0xbfb8aa3b, v0
	v_exp_f32_e32 v0, v0
	v_pk_mul_f32 v[144:145], v[144:145], v[150:151]
	v_lshlrev_b32_e32 v150, 16, v148
	v_cvt_pk_bf16_f32 v143, v144, v145
	v_and_b32_e32 v145, 0xffff0000, v146
	v_add_f32_e32 v0, 1.0, v0
	v_rcp_f32_e32 v144, v0
	v_mul_f32_e32 v0, 0xbfb8aa3b, v145
	v_exp_f32_e32 v0, v0
	v_lshlrev_b32_e32 v146, 16, v147
	v_and_b32_e32 v147, 0xffff0000, v147
	v_and_b32_e32 v148, 0xffff0000, v148
	v_add_f32_e32 v0, 1.0, v0
	v_rcp_f32_e32 v145, v0
	v_mul_f32_e32 v0, 0xbfb8aa3b, v146
	v_exp_f32_e32 v0, v0
	v_lshlrev_b32_e32 v151, 16, v149
	v_pk_mul_f32 v[134:135], v[134:135], v[144:145]
	v_and_b32_e32 v149, 0xffff0000, v149
	v_add_f32_e32 v0, 1.0, v0
	v_cvt_pk_bf16_f32 v144, v134, v135
	v_rcp_f32_e32 v134, v0
	v_mul_f32_e32 v0, 0xbfb8aa3b, v147
	v_exp_f32_e32 v0, v0
	global_store_dwordx2 v[188:189], v[142:143], off offset:224
	v_or_b32_e32 v142, 16, v190
	v_ashrrev_i32_e32 v143, 31, v142
	v_add_f32_e32 v0, 1.0, v0
	v_rcp_f32_e32 v135, v0
	v_mul_f32_e32 v0, 0xbfb8aa3b, v150
	v_exp_f32_e32 v0, v0
	v_lshlrev_b64 v[142:143], 11, v[142:143]
	v_pk_mul_f32 v[134:135], v[136:137], v[134:135]
	v_lshl_add_u64 v[142:143], s[10:11], 0, v[142:143]
	v_add_f32_e32 v0, 1.0, v0
	v_rcp_f32_e32 v136, v0
	v_mul_f32_e32 v0, 0xbfb8aa3b, v148
	v_exp_f32_e32 v0, v0
	v_cvt_pk_bf16_f32 v145, v134, v135
	v_lshl_add_u64 v[134:135], v[142:143], 0, v[186:187]
	global_store_dwordx2 v[134:135], v[144:145], off
	v_add_f32_e32 v0, 1.0, v0
	v_rcp_f32_e32 v137, v0
	v_mul_f32_e32 v0, 0xbfb8aa3b, v151
	v_exp_f32_e32 v0, v0
	v_pk_mul_f32 v[130:131], v[130:131], v[136:137]
	s_nop 0
	v_cvt_pk_bf16_f32 v130, v130, v131
	v_add_f32_e32 v0, 1.0, v0
	v_rcp_f32_e32 v136, v0
	v_mul_f32_e32 v0, 0xbfb8aa3b, v149
	v_exp_f32_e32 v0, v0
	s_nop 0
	v_add_f32_e32 v0, 1.0, v0
	v_rcp_f32_e32 v137, v0
	s_waitcnt vmcnt(19)
	v_lshlrev_b32_e32 v0, 16, v138
	v_mul_f32_e32 v0, 0xbfb8aa3b, v0
	v_exp_f32_e32 v0, v0
	v_pk_mul_f32 v[132:133], v[132:133], v[136:137]
	v_lshlrev_b32_e32 v136, 16, v140
	v_cvt_pk_bf16_f32 v131, v132, v133
	global_store_dwordx2 v[134:135], v[130:131], off offset:32
	v_and_b32_e32 v131, 0xffff0000, v138
	v_add_f32_e32 v0, 1.0, v0
	v_rcp_f32_e32 v130, v0
	v_mul_f32_e32 v0, 0xbfb8aa3b, v131
	v_exp_f32_e32 v0, v0
	v_lshlrev_b32_e32 v132, 16, v139
	v_and_b32_e32 v133, 0xffff0000, v139
	v_and_b32_e32 v137, 0xffff0000, v140
	v_add_f32_e32 v0, 1.0, v0
	v_rcp_f32_e32 v131, v0
	v_mul_f32_e32 v0, 0xbfb8aa3b, v132
	v_exp_f32_e32 v0, v0
	v_lshlrev_b32_e32 v138, 16, v141
	v_pk_mul_f32 v[126:127], v[126:127], v[130:131]
	v_and_b32_e32 v139, 0xffff0000, v141
	v_add_f32_e32 v0, 1.0, v0
	v_rcp_f32_e32 v130, v0
	v_mul_f32_e32 v0, 0xbfb8aa3b, v133
	v_exp_f32_e32 v0, v0
	v_cvt_pk_bf16_f32 v126, v126, v127
	v_add_f32_e32 v0, 1.0, v0
	v_rcp_f32_e32 v131, v0
	v_mul_f32_e32 v0, 0xbfb8aa3b, v136
	v_exp_f32_e32 v0, v0
	v_pk_mul_f32 v[128:129], v[128:129], v[130:131]
	s_nop 0
	v_cvt_pk_bf16_f32 v127, v128, v129
	v_add_f32_e32 v0, 1.0, v0
	global_store_dwordx2 v[134:135], v[126:127], off offset:64
	v_rcp_f32_e32 v126, v0
	v_mul_f32_e32 v0, 0xbfb8aa3b, v137
	v_exp_f32_e32 v0, v0
	s_nop 0
	v_add_f32_e32 v0, 1.0, v0
	v_rcp_f32_e32 v127, v0
	v_mul_f32_e32 v0, 0xbfb8aa3b, v138
	v_exp_f32_e32 v0, v0
	v_pk_mul_f32 v[118:119], v[118:119], v[126:127]
	s_nop 0
	v_cvt_pk_bf16_f32 v118, v118, v119
	v_add_f32_e32 v0, 1.0, v0
	v_rcp_f32_e32 v126, v0
	v_mul_f32_e32 v0, 0xbfb8aa3b, v139
	v_exp_f32_e32 v0, v0
	s_nop 0
	v_add_f32_e32 v0, 1.0, v0
	v_rcp_f32_e32 v127, v0
	s_waitcnt vmcnt(20)
	v_lshlrev_b32_e32 v0, 16, v122
	v_mul_f32_e32 v0, 0xbfb8aa3b, v0
	v_exp_f32_e32 v0, v0
	v_pk_mul_f32 v[120:121], v[120:121], v[126:127]
	v_add_f32_e32 v0, 1.0, v0
	v_cvt_pk_bf16_f32 v119, v120, v121
	global_store_dwordx2 v[134:135], v[118:119], off offset:96
	v_and_b32_e32 v119, 0xffff0000, v122
	v_rcp_f32_e32 v118, v0
	v_mul_f32_e32 v0, 0xbfb8aa3b, v119
	v_exp_f32_e32 v0, v0
	v_lshlrev_b32_e32 v120, 16, v123
	v_and_b32_e32 v121, 0xffff0000, v123
	v_lshlrev_b32_e32 v122, 16, v124
	v_add_f32_e32 v0, 1.0, v0
	v_rcp_f32_e32 v119, v0
	v_mul_f32_e32 v0, 0xbfb8aa3b, v120
	v_exp_f32_e32 v0, v0
	v_and_b32_e32 v123, 0xffff0000, v124
	v_pk_mul_f32 v[114:115], v[114:115], v[118:119]
	v_lshlrev_b32_e32 v124, 16, v125
	v_add_f32_e32 v0, 1.0, v0
	v_rcp_f32_e32 v118, v0
	v_mul_f32_e32 v0, 0xbfb8aa3b, v121
	v_exp_f32_e32 v0, v0
	v_cvt_pk_bf16_f32 v114, v114, v115
	v_and_b32_e32 v125, 0xffff0000, v125
	v_add_f32_e32 v0, 1.0, v0
	v_rcp_f32_e32 v119, v0
	v_mul_f32_e32 v0, 0xbfb8aa3b, v122
	v_exp_f32_e32 v0, v0
	v_pk_mul_f32 v[116:117], v[116:117], v[118:119]
	s_nop 0
	v_cvt_pk_bf16_f32 v115, v116, v117
	v_add_f32_e32 v0, 1.0, v0
	global_store_dwordx2 v[134:135], v[114:115], off offset:128
	v_rcp_f32_e32 v114, v0
	v_mul_f32_e32 v0, 0xbfb8aa3b, v123
	v_exp_f32_e32 v0, v0
	s_nop 0
	v_add_f32_e32 v0, 1.0, v0
	v_rcp_f32_e32 v115, v0
	v_mul_f32_e32 v0, 0xbfb8aa3b, v124
	v_exp_f32_e32 v0, v0
	v_pk_mul_f32 v[106:107], v[106:107], v[114:115]
	s_nop 0
	v_cvt_pk_bf16_f32 v106, v106, v107
	v_add_f32_e32 v0, 1.0, v0
	v_rcp_f32_e32 v114, v0
	v_mul_f32_e32 v0, 0xbfb8aa3b, v125
	v_exp_f32_e32 v0, v0
	s_nop 0
	v_add_f32_e32 v0, 1.0, v0
	v_rcp_f32_e32 v115, v0
	s_waitcnt vmcnt(21)
; DI float sigmoidf_(float x) { return frcp(1.f + __expf(-x)); }
; template <int CT>
; DI void phase_g2(int c, int l) {
;     ...
;     for (int n = 0; n < 4; ++n) {
;       const size_t tl = tbase + wc * 64 + n * 16 + fr;
; #pragma unroll
;       for (int mp = 0; mp < 4; ++mp) {
;         float b8[8];
;         unpack8(gb16[n][mp], b8);
; #pragma unroll
;         for (int mh = 0; mh < 2; ++mh) {
;           const int m = mp * 2 + mh, f = fbase + wr * 128 + m * 16 + fq * 4;
;           uint2 o;
;           o.x = pk2(acc[m][n][0] * sigmoidf_(b8[mh * 4 + 0]), acc[m][n][1] * sigmoidf_(b8[mh * 4 + 1]));
;           o.y = pk2(acc[m][n][2] * sigmoidf_(b8[mh * 4 + 2]), acc[m][n][3] * sigmoidf_(b8[mh * 4 + 3]));
;           *(uint2*)(WSU(MRG) + tl * 1024 + f) = o;
;         }
;       }
	v_lshlrev_b32_e32 v0, 16, v110
	v_mul_f32_e32 v0, 0xbfb8aa3b, v0
	v_exp_f32_e32 v0, v0
	v_pk_mul_f32 v[108:109], v[108:109], v[114:115]
	v_add_f32_e32 v0, 1.0, v0
	v_cvt_pk_bf16_f32 v107, v108, v109
	global_store_dwordx2 v[134:135], v[106:107], off offset:160
	v_and_b32_e32 v107, 0xffff0000, v110
	v_rcp_f32_e32 v106, v0
	v_mul_f32_e32 v0, 0xbfb8aa3b, v107
	v_exp_f32_e32 v0, v0
	v_lshlrev_b32_e32 v108, 16, v111
	v_and_b32_e32 v109, 0xffff0000, v111
	v_lshlrev_b32_e32 v110, 16, v112
	v_add_f32_e32 v0, 1.0, v0
	v_rcp_f32_e32 v107, v0
	v_mul_f32_e32 v0, 0xbfb8aa3b, v108
	v_exp_f32_e32 v0, v0
	v_and_b32_e32 v111, 0xffff0000, v112
	v_pk_mul_f32 v[102:103], v[102:103], v[106:107]
	v_lshlrev_b32_e32 v112, 16, v113
	v_add_f32_e32 v0, 1.0, v0
	v_rcp_f32_e32 v106, v0
	v_mul_f32_e32 v0, 0xbfb8aa3b, v109
	v_exp_f32_e32 v0, v0
	v_cvt_pk_bf16_f32 v102, v102, v103
	v_and_b32_e32 v113, 0xffff0000, v113
	v_add_f32_e32 v0, 1.0, v0
	v_rcp_f32_e32 v107, v0
	v_mul_f32_e32 v0, 0xbfb8aa3b, v110
	v_exp_f32_e32 v0, v0
	v_pk_mul_f32 v[104:105], v[104:105], v[106:107]
	s_nop 0
	v_cvt_pk_bf16_f32 v103, v104, v105
	v_add_f32_e32 v0, 1.0, v0
	global_store_dwordx2 v[134:135], v[102:103], off offset:192
	v_rcp_f32_e32 v102, v0
	v_mul_f32_e32 v0, 0xbfb8aa3b, v111
	v_exp_f32_e32 v0, v0
	s_nop 0
	v_add_f32_e32 v0, 1.0, v0
	v_rcp_f32_e32 v103, v0
	v_mul_f32_e32 v0, 0xbfb8aa3b, v112
	v_exp_f32_e32 v0, v0
	v_pk_mul_f32 v[94:95], v[94:95], v[102:103]
	s_nop 0
	v_cvt_pk_bf16_f32 v94, v94, v95
	v_add_f32_e32 v0, 1.0, v0
	v_rcp_f32_e32 v102, v0
	v_mul_f32_e32 v0, 0xbfb8aa3b, v113
	v_exp_f32_e32 v0, v0
	s_nop 0
	v_add_f32_e32 v0, 1.0, v0
	v_rcp_f32_e32 v103, v0
	s_waitcnt vmcnt(22)
	v_lshlrev_b32_e32 v0, 16, v98
	v_mul_f32_e32 v0, 0xbfb8aa3b, v0
	v_exp_f32_e32 v0, v0
	v_pk_mul_f32 v[96:97], v[96:97], v[102:103]
	v_lshlrev_b32_e32 v102, 16, v100
	v_cvt_pk_bf16_f32 v95, v96, v97
	v_and_b32_e32 v97, 0xffff0000, v98
	v_add_f32_e32 v0, 1.0, v0
	v_rcp_f32_e32 v96, v0
	v_mul_f32_e32 v0, 0xbfb8aa3b, v97
	v_exp_f32_e32 v0, v0
	v_lshlrev_b32_e32 v98, 16, v99
	v_and_b32_e32 v99, 0xffff0000, v99
	v_and_b32_e32 v100, 0xffff0000, v100
	v_add_f32_e32 v0, 1.0, v0
	v_rcp_f32_e32 v97, v0
	v_mul_f32_e32 v0, 0xbfb8aa3b, v98
	v_exp_f32_e32 v0, v0
	v_lshlrev_b32_e32 v103, 16, v101
	v_pk_mul_f32 v[86:87], v[86:87], v[96:97]
	v_and_b32_e32 v101, 0xffff0000, v101
	v_add_f32_e32 v0, 1.0, v0
	v_cvt_pk_bf16_f32 v96, v86, v87
	v_rcp_f32_e32 v86, v0
	v_mul_f32_e32 v0, 0xbfb8aa3b, v99
	v_exp_f32_e32 v0, v0
	global_store_dwordx2 v[134:135], v[94:95], off offset:224
	v_or_b32_e32 v94, 32, v190
	v_ashrrev_i32_e32 v95, 31, v94
	v_add_f32_e32 v0, 1.0, v0
	v_rcp_f32_e32 v87, v0
	v_mul_f32_e32 v0, 0xbfb8aa3b, v102
	v_exp_f32_e32 v0, v0
	v_lshlrev_b64 v[94:95], 11, v[94:95]
	v_pk_mul_f32 v[86:87], v[88:89], v[86:87]
	v_lshl_add_u64 v[94:95], s[10:11], 0, v[94:95]
	v_add_f32_e32 v0, 1.0, v0
	v_rcp_f32_e32 v88, v0
	v_mul_f32_e32 v0, 0xbfb8aa3b, v100
	v_exp_f32_e32 v0, v0
	v_cvt_pk_bf16_f32 v97, v86, v87
	v_lshl_add_u64 v[86:87], v[94:95], 0, v[186:187]
	global_store_dwordx2 v[86:87], v[96:97], off
	v_add_f32_e32 v0, 1.0, v0
	v_rcp_f32_e32 v89, v0
	v_mul_f32_e32 v0, 0xbfb8aa3b, v103
	v_exp_f32_e32 v0, v0
	v_pk_mul_f32 v[82:83], v[82:83], v[88:89]
	s_nop 0
	v_cvt_pk_bf16_f32 v82, v82, v83
	v_add_f32_e32 v0, 1.0, v0
	v_rcp_f32_e32 v88, v0
	v_mul_f32_e32 v0, 0xbfb8aa3b, v101
	v_exp_f32_e32 v0, v0
	s_nop 0
	v_add_f32_e32 v0, 1.0, v0
	v_rcp_f32_e32 v89, v0
	s_waitcnt vmcnt(23)
	v_lshlrev_b32_e32 v0, 16, v90
	v_mul_f32_e32 v0, 0xbfb8aa3b, v0
	v_exp_f32_e32 v0, v0
	v_pk_mul_f32 v[84:85], v[84:85], v[88:89]
	v_lshlrev_b32_e32 v88, 16, v92
	v_cvt_pk_bf16_f32 v83, v84, v85
	global_store_dwordx2 v[86:87], v[82:83], off offset:32
	v_and_b32_e32 v83, 0xffff0000, v90
	v_add_f32_e32 v0, 1.0, v0
	v_rcp_f32_e32 v82, v0
	v_mul_f32_e32 v0, 0xbfb8aa3b, v83
	v_exp_f32_e32 v0, v0
	v_lshlrev_b32_e32 v84, 16, v91
	v_and_b32_e32 v85, 0xffff0000, v91
	v_and_b32_e32 v89, 0xffff0000, v92
	v_add_f32_e32 v0, 1.0, v0
	v_rcp_f32_e32 v83, v0
	v_mul_f32_e32 v0, 0xbfb8aa3b, v84
	v_exp_f32_e32 v0, v0
	v_lshlrev_b32_e32 v90, 16, v93
	v_pk_mul_f32 v[78:79], v[78:79], v[82:83]
	v_and_b32_e32 v91, 0xffff0000, v93
	v_add_f32_e32 v0, 1.0, v0
	v_rcp_f32_e32 v82, v0
	v_mul_f32_e32 v0, 0xbfb8aa3b, v85
	v_exp_f32_e32 v0, v0
	v_cvt_pk_bf16_f32 v78, v78, v79
	v_add_f32_e32 v0, 1.0, v0
	v_rcp_f32_e32 v83, v0
	v_mul_f32_e32 v0, 0xbfb8aa3b, v88
	v_exp_f32_e32 v0, v0
	v_pk_mul_f32 v[80:81], v[80:81], v[82:83]
	s_nop 0
	v_cvt_pk_bf16_f32 v79, v80, v81
	v_add_f32_e32 v0, 1.0, v0
	global_store_dwordx2 v[86:87], v[78:79], off offset:64
	v_rcp_f32_e32 v78, v0
	v_mul_f32_e32 v0, 0xbfb8aa3b, v89
	v_exp_f32_e32 v0, v0
	s_nop 0
	v_add_f32_e32 v0, 1.0, v0
	v_rcp_f32_e32 v79, v0
	v_mul_f32_e32 v0, 0xbfb8aa3b, v90
	v_exp_f32_e32 v0, v0
	v_pk_mul_f32 v[70:71], v[70:71], v[78:79]
	s_nop 0
	v_cvt_pk_bf16_f32 v70, v70, v71
	v_add_f32_e32 v0, 1.0, v0
	v_rcp_f32_e32 v78, v0
	v_mul_f32_e32 v0, 0xbfb8aa3b, v91
	v_exp_f32_e32 v0, v0
	s_nop 0
	v_add_f32_e32 v0, 1.0, v0
	v_rcp_f32_e32 v79, v0
	s_waitcnt vmcnt(24)
; DI float sigmoidf_(float x) { return frcp(1.f + __expf(-x)); }
; template <int CT>
; DI void phase_g2(int c, int l) {
;     ...
;     for (int n = 0; n < 4; ++n) {
;       const size_t tl = tbase + wc * 64 + n * 16 + fr;
; #pragma unroll
;       for (int mp = 0; mp < 4; ++mp) {
;         float b8[8];
;         unpack8(gb16[n][mp], b8);
; #pragma unroll
;         for (int mh = 0; mh < 2; ++mh) {
;           const int m = mp * 2 + mh, f = fbase + wr * 128 + m * 16 + fq * 4;
;           uint2 o;
;           o.x = pk2(acc[m][n][0] * sigmoidf_(b8[mh * 4 + 0]), acc[m][n][1] * sigmoidf_(b8[mh * 4 + 1]));
;           o.y = pk2(acc[m][n][2] * sigmoidf_(b8[mh * 4 + 2]), acc[m][n][3] * sigmoidf_(b8[mh * 4 + 3]));
;           *(uint2*)(WSU(MRG) + tl * 1024 + f) = o;
;         }
;       }
	v_lshlrev_b32_e32 v0, 16, v74
	v_mul_f32_e32 v0, 0xbfb8aa3b, v0
	v_exp_f32_e32 v0, v0
	v_pk_mul_f32 v[72:73], v[72:73], v[78:79]
	v_add_f32_e32 v0, 1.0, v0
	v_cvt_pk_bf16_f32 v71, v72, v73
	global_store_dwordx2 v[86:87], v[70:71], off offset:96
	v_and_b32_e32 v71, 0xffff0000, v74
	v_rcp_f32_e32 v70, v0
	v_mul_f32_e32 v0, 0xbfb8aa3b, v71
	v_exp_f32_e32 v0, v0
	v_lshlrev_b32_e32 v72, 16, v75
	v_and_b32_e32 v73, 0xffff0000, v75
	v_lshlrev_b32_e32 v74, 16, v76
	v_add_f32_e32 v0, 1.0, v0
	v_rcp_f32_e32 v71, v0
	v_mul_f32_e32 v0, 0xbfb8aa3b, v72
	v_exp_f32_e32 v0, v0
	v_and_b32_e32 v75, 0xffff0000, v76
	v_pk_mul_f32 v[66:67], v[66:67], v[70:71]
	v_lshlrev_b32_e32 v76, 16, v77
	v_add_f32_e32 v0, 1.0, v0
	v_rcp_f32_e32 v70, v0
	v_mul_f32_e32 v0, 0xbfb8aa3b, v73
	v_exp_f32_e32 v0, v0
	v_cvt_pk_bf16_f32 v66, v66, v67
	v_and_b32_e32 v77, 0xffff0000, v77
	v_add_f32_e32 v0, 1.0, v0
	v_rcp_f32_e32 v71, v0
	v_mul_f32_e32 v0, 0xbfb8aa3b, v74
	v_exp_f32_e32 v0, v0
	v_pk_mul_f32 v[68:69], v[68:69], v[70:71]
	s_nop 0
	v_cvt_pk_bf16_f32 v67, v68, v69
	v_add_f32_e32 v0, 1.0, v0
	global_store_dwordx2 v[86:87], v[66:67], off offset:128
	v_rcp_f32_e32 v66, v0
	v_mul_f32_e32 v0, 0xbfb8aa3b, v75
	v_exp_f32_e32 v0, v0
	s_nop 0
	v_add_f32_e32 v0, 1.0, v0
	v_rcp_f32_e32 v67, v0
	v_mul_f32_e32 v0, 0xbfb8aa3b, v76
	v_exp_f32_e32 v0, v0
	v_pk_mul_f32 v[58:59], v[58:59], v[66:67]
	s_nop 0
	v_cvt_pk_bf16_f32 v58, v58, v59
	v_add_f32_e32 v0, 1.0, v0
	v_rcp_f32_e32 v66, v0
	v_mul_f32_e32 v0, 0xbfb8aa3b, v77
	v_exp_f32_e32 v0, v0
	s_nop 0
	v_add_f32_e32 v0, 1.0, v0
	v_rcp_f32_e32 v67, v0
	s_waitcnt vmcnt(25)
	v_lshlrev_b32_e32 v0, 16, v62
	v_mul_f32_e32 v0, 0xbfb8aa3b, v0
	v_exp_f32_e32 v0, v0
	v_pk_mul_f32 v[60:61], v[60:61], v[66:67]
	v_add_f32_e32 v0, 1.0, v0
	v_cvt_pk_bf16_f32 v59, v60, v61
	global_store_dwordx2 v[86:87], v[58:59], off offset:160
	v_and_b32_e32 v59, 0xffff0000, v62
	v_rcp_f32_e32 v58, v0
	v_mul_f32_e32 v0, 0xbfb8aa3b, v59
	v_exp_f32_e32 v0, v0
	v_lshlrev_b32_e32 v60, 16, v63
	v_and_b32_e32 v61, 0xffff0000, v63
	v_lshlrev_b32_e32 v62, 16, v64
	v_add_f32_e32 v0, 1.0, v0
	v_rcp_f32_e32 v59, v0
	v_mul_f32_e32 v0, 0xbfb8aa3b, v60
	v_exp_f32_e32 v0, v0
	v_and_b32_e32 v63, 0xffff0000, v64
	v_pk_mul_f32 v[54:55], v[54:55], v[58:59]
	v_lshlrev_b32_e32 v64, 16, v65
	v_add_f32_e32 v0, 1.0, v0
	v_rcp_f32_e32 v58, v0
	v_mul_f32_e32 v0, 0xbfb8aa3b, v61
	v_exp_f32_e32 v0, v0
	v_cvt_pk_bf16_f32 v54, v54, v55
	v_and_b32_e32 v65, 0xffff0000, v65
	v_add_f32_e32 v0, 1.0, v0
	v_rcp_f32_e32 v59, v0
	v_mul_f32_e32 v0, 0xbfb8aa3b, v62
	v_exp_f32_e32 v0, v0
	v_pk_mul_f32 v[56:57], v[56:57], v[58:59]
	s_nop 0
	v_cvt_pk_bf16_f32 v55, v56, v57
	v_add_f32_e32 v0, 1.0, v0
	global_store_dwordx2 v[86:87], v[54:55], off offset:192
	v_rcp_f32_e32 v54, v0
	v_mul_f32_e32 v0, 0xbfb8aa3b, v63
	v_exp_f32_e32 v0, v0
	s_nop 0
	v_add_f32_e32 v0, 1.0, v0
	v_rcp_f32_e32 v55, v0
	v_mul_f32_e32 v0, 0xbfb8aa3b, v64
	v_exp_f32_e32 v0, v0
	v_pk_mul_f32 v[46:47], v[46:47], v[54:55]
	s_nop 0
	v_cvt_pk_bf16_f32 v46, v46, v47
	v_add_f32_e32 v0, 1.0, v0
	v_rcp_f32_e32 v54, v0
	v_mul_f32_e32 v0, 0xbfb8aa3b, v65
	v_exp_f32_e32 v0, v0
	s_nop 0
	v_add_f32_e32 v0, 1.0, v0
	v_rcp_f32_e32 v55, v0
	s_waitcnt vmcnt(26)
	v_lshlrev_b32_e32 v0, 16, v50
	v_mul_f32_e32 v0, 0xbfb8aa3b, v0
	v_exp_f32_e32 v0, v0
	v_pk_mul_f32 v[48:49], v[48:49], v[54:55]
	v_lshlrev_b32_e32 v54, 16, v52
	v_cvt_pk_bf16_f32 v47, v48, v49
	v_and_b32_e32 v49, 0xffff0000, v50
	v_add_f32_e32 v0, 1.0, v0
	v_rcp_f32_e32 v48, v0
	v_mul_f32_e32 v0, 0xbfb8aa3b, v49
	v_exp_f32_e32 v0, v0
	v_lshlrev_b32_e32 v50, 16, v51
	v_and_b32_e32 v51, 0xffff0000, v51
	v_and_b32_e32 v52, 0xffff0000, v52
	v_add_f32_e32 v0, 1.0, v0
	v_rcp_f32_e32 v49, v0
	v_mul_f32_e32 v0, 0xbfb8aa3b, v50
	v_exp_f32_e32 v0, v0
	v_lshlrev_b32_e32 v55, 16, v53
	v_pk_mul_f32 v[38:39], v[38:39], v[48:49]
	v_and_b32_e32 v53, 0xffff0000, v53
	v_add_f32_e32 v0, 1.0, v0
	v_cvt_pk_bf16_f32 v48, v38, v39
	v_rcp_f32_e32 v38, v0
	v_mul_f32_e32 v0, 0xbfb8aa3b, v51
	v_exp_f32_e32 v0, v0
	global_store_dwordx2 v[86:87], v[46:47], off offset:224
	v_or_b32_e32 v46, 48, v190
	v_ashrrev_i32_e32 v47, 31, v46
	v_add_f32_e32 v0, 1.0, v0
	v_rcp_f32_e32 v39, v0
	v_mul_f32_e32 v0, 0xbfb8aa3b, v54
	v_exp_f32_e32 v0, v0
	v_lshlrev_b64 v[46:47], 11, v[46:47]
	v_pk_mul_f32 v[38:39], v[40:41], v[38:39]
	v_lshl_add_u64 v[46:47], s[10:11], 0, v[46:47]
	v_add_f32_e32 v0, 1.0, v0
	v_rcp_f32_e32 v40, v0
	v_mul_f32_e32 v0, 0xbfb8aa3b, v52
	v_exp_f32_e32 v0, v0
	v_cvt_pk_bf16_f32 v49, v38, v39
	v_lshl_add_u64 v[38:39], v[46:47], 0, v[186:187]
	global_store_dwordx2 v[38:39], v[48:49], off
	v_add_f32_e32 v0, 1.0, v0
	v_rcp_f32_e32 v41, v0
	v_mul_f32_e32 v0, 0xbfb8aa3b, v55
	v_exp_f32_e32 v0, v0
	v_pk_mul_f32 v[34:35], v[34:35], v[40:41]
	s_nop 0
	v_cvt_pk_bf16_f32 v34, v34, v35
	v_add_f32_e32 v0, 1.0, v0
	v_rcp_f32_e32 v40, v0
	v_mul_f32_e32 v0, 0xbfb8aa3b, v53
	v_exp_f32_e32 v0, v0
	s_nop 0
	v_add_f32_e32 v0, 1.0, v0
	v_rcp_f32_e32 v41, v0
	s_waitcnt vmcnt(27)
; DI float sigmoidf_(float x) { return frcp(1.f + __expf(-x)); }
; template <int CT>
; DI void phase_g2(int c, int l) {
;     ...
;     for (int n = 0; n < 4; ++n) {
;       const size_t tl = tbase + wc * 64 + n * 16 + fr;
; #pragma unroll
;       for (int mp = 0; mp < 4; ++mp) {
;         float b8[8];
;         unpack8(gb16[n][mp], b8);
; #pragma unroll
;         for (int mh = 0; mh < 2; ++mh) {
;           const int m = mp * 2 + mh, f = fbase + wr * 128 + m * 16 + fq * 4;
;           uint2 o;
;           o.x = pk2(acc[m][n][0] * sigmoidf_(b8[mh * 4 + 0]), acc[m][n][1] * sigmoidf_(b8[mh * 4 + 1]));
;           o.y = pk2(acc[m][n][2] * sigmoidf_(b8[mh * 4 + 2]), acc[m][n][3] * sigmoidf_(b8[mh * 4 + 3]));
;           *(uint2*)(WSU(MRG) + tl * 1024 + f) = o;
;         }
;       }
	v_lshlrev_b32_e32 v0, 16, v42
	v_mul_f32_e32 v0, 0xbfb8aa3b, v0
	v_exp_f32_e32 v0, v0
	v_pk_mul_f32 v[36:37], v[36:37], v[40:41]
	v_lshlrev_b32_e32 v40, 16, v44
	v_cvt_pk_bf16_f32 v35, v36, v37
	global_store_dwordx2 v[38:39], v[34:35], off offset:32
	v_and_b32_e32 v35, 0xffff0000, v42
	v_add_f32_e32 v0, 1.0, v0
	v_rcp_f32_e32 v34, v0
	v_mul_f32_e32 v0, 0xbfb8aa3b, v35
	v_exp_f32_e32 v0, v0
	v_lshlrev_b32_e32 v36, 16, v43
	v_and_b32_e32 v37, 0xffff0000, v43
	v_and_b32_e32 v41, 0xffff0000, v44
	v_add_f32_e32 v0, 1.0, v0
	v_rcp_f32_e32 v35, v0
	v_mul_f32_e32 v0, 0xbfb8aa3b, v36
	v_exp_f32_e32 v0, v0
	v_lshlrev_b32_e32 v42, 16, v45
	v_pk_mul_f32 v[26:27], v[26:27], v[34:35]
	v_and_b32_e32 v43, 0xffff0000, v45
	v_add_f32_e32 v0, 1.0, v0
	v_rcp_f32_e32 v34, v0
	v_mul_f32_e32 v0, 0xbfb8aa3b, v37
	v_exp_f32_e32 v0, v0
	v_cvt_pk_bf16_f32 v26, v26, v27
	v_add_f32_e32 v0, 1.0, v0
	v_rcp_f32_e32 v35, v0
	v_mul_f32_e32 v0, 0xbfb8aa3b, v40
	v_exp_f32_e32 v0, v0
	v_pk_mul_f32 v[28:29], v[28:29], v[34:35]
	s_nop 0
	v_cvt_pk_bf16_f32 v27, v28, v29
	v_add_f32_e32 v0, 1.0, v0
	global_store_dwordx2 v[38:39], v[26:27], off offset:64
	v_rcp_f32_e32 v26, v0
	v_mul_f32_e32 v0, 0xbfb8aa3b, v41
	v_exp_f32_e32 v0, v0
	s_waitcnt vmcnt(28)
	v_lshlrev_b32_e32 v28, 16, v33
	v_and_b32_e32 v29, 0xffff0000, v33
	v_add_f32_e32 v0, 1.0, v0
	v_rcp_f32_e32 v27, v0
	v_mul_f32_e32 v0, 0xbfb8aa3b, v42
	v_exp_f32_e32 v0, v0
	v_pk_mul_f32 v[22:23], v[22:23], v[26:27]
	s_nop 0
	v_cvt_pk_bf16_f32 v22, v22, v23
	v_add_f32_e32 v0, 1.0, v0
	v_rcp_f32_e32 v26, v0
	v_mul_f32_e32 v0, 0xbfb8aa3b, v43
	v_exp_f32_e32 v0, v0
	s_nop 0
	v_add_f32_e32 v0, 1.0, v0
	v_rcp_f32_e32 v27, v0
	v_lshlrev_b32_e32 v0, 16, v30
	v_mul_f32_e32 v0, 0xbfb8aa3b, v0
	v_exp_f32_e32 v0, v0
	v_pk_mul_f32 v[24:25], v[24:25], v[26:27]
	v_lshlrev_b32_e32 v26, 16, v32
	v_cvt_pk_bf16_f32 v23, v24, v25
	global_store_dwordx2 v[38:39], v[22:23], off offset:96
	v_and_b32_e32 v23, 0xffff0000, v30
	v_add_f32_e32 v0, 1.0, v0
	v_rcp_f32_e32 v22, v0
	v_mul_f32_e32 v0, 0xbfb8aa3b, v23
	v_exp_f32_e32 v0, v0
	v_lshlrev_b32_e32 v24, 16, v31
	v_and_b32_e32 v25, 0xffff0000, v31
	v_and_b32_e32 v27, 0xffff0000, v32
	v_add_f32_e32 v0, 1.0, v0
	v_rcp_f32_e32 v23, v0
	v_mul_f32_e32 v0, 0xbfb8aa3b, v24
	v_exp_f32_e32 v0, v0
	v_pk_mul_f32 v[18:19], v[18:19], v[22:23]
	s_nop 0
	v_cvt_pk_bf16_f32 v18, v18, v19
	v_add_f32_e32 v0, 1.0, v0
	v_rcp_f32_e32 v22, v0
	v_mul_f32_e32 v0, 0xbfb8aa3b, v25
	v_exp_f32_e32 v0, v0
	s_nop 0
	v_add_f32_e32 v0, 1.0, v0
	v_rcp_f32_e32 v23, v0
	v_mul_f32_e32 v0, 0xbfb8aa3b, v26
	v_exp_f32_e32 v0, v0
	v_pk_mul_f32 v[20:21], v[20:21], v[22:23]
	s_nop 0
	v_cvt_pk_bf16_f32 v19, v20, v21
	v_add_f32_e32 v0, 1.0, v0
	global_store_dwordx2 v[38:39], v[18:19], off offset:128
	v_rcp_f32_e32 v18, v0
	v_mul_f32_e32 v0, 0xbfb8aa3b, v27
	v_exp_f32_e32 v0, v0
	s_nop 0
	v_add_f32_e32 v0, 1.0, v0
	v_rcp_f32_e32 v19, v0
	v_mul_f32_e32 v0, 0xbfb8aa3b, v28
	v_exp_f32_e32 v0, v0
	v_pk_mul_f32 v[10:11], v[10:11], v[18:19]
	s_nop 0
	v_cvt_pk_bf16_f32 v10, v10, v11
	v_add_f32_e32 v0, 1.0, v0
	v_rcp_f32_e32 v18, v0
	v_mul_f32_e32 v0, 0xbfb8aa3b, v29
	v_exp_f32_e32 v0, v0
	s_nop 0
	v_add_f32_e32 v0, 1.0, v0
	v_rcp_f32_e32 v19, v0
	s_waitcnt vmcnt(29)
	v_lshlrev_b32_e32 v0, 16, v14
	v_mul_f32_e32 v0, 0xbfb8aa3b, v0
	v_exp_f32_e32 v0, v0
	v_pk_mul_f32 v[12:13], v[12:13], v[18:19]
	v_add_f32_e32 v0, 1.0, v0
	v_cvt_pk_bf16_f32 v11, v12, v13
	global_store_dwordx2 v[38:39], v[10:11], off offset:160
	v_and_b32_e32 v11, 0xffff0000, v14
	v_rcp_f32_e32 v10, v0
	v_mul_f32_e32 v0, 0xbfb8aa3b, v11
	v_exp_f32_e32 v0, v0
	v_lshlrev_b32_e32 v12, 16, v15
	v_and_b32_e32 v13, 0xffff0000, v15
	v_lshlrev_b32_e32 v14, 16, v16
	v_add_f32_e32 v0, 1.0, v0
	v_rcp_f32_e32 v11, v0
	v_mul_f32_e32 v0, 0xbfb8aa3b, v12
	v_exp_f32_e32 v0, v0
	v_and_b32_e32 v15, 0xffff0000, v16
	v_pk_mul_f32 v[6:7], v[6:7], v[10:11]
	v_lshlrev_b32_e32 v16, 16, v17
	v_add_f32_e32 v0, 1.0, v0
	v_rcp_f32_e32 v10, v0
	v_mul_f32_e32 v0, 0xbfb8aa3b, v13
	v_exp_f32_e32 v0, v0
	v_cvt_pk_bf16_f32 v6, v6, v7
	v_and_b32_e32 v17, 0xffff0000, v17
	v_add_f32_e32 v0, 1.0, v0
	v_rcp_f32_e32 v11, v0
	v_mul_f32_e32 v0, 0xbfb8aa3b, v14
	v_exp_f32_e32 v0, v0
	v_pk_mul_f32 v[8:9], v[8:9], v[10:11]
	s_nop 0
	v_cvt_pk_bf16_f32 v7, v8, v9
	v_add_f32_e32 v0, 1.0, v0
	global_store_dwordx2 v[38:39], v[6:7], off offset:192
	v_rcp_f32_e32 v6, v0
	v_mul_f32_e32 v0, 0xbfb8aa3b, v15
	v_exp_f32_e32 v0, v0
	s_nop 0
	v_add_f32_e32 v0, 1.0, v0
	v_rcp_f32_e32 v7, v0
	v_mul_f32_e32 v0, 0xbfb8aa3b, v16
	v_exp_f32_e32 v0, v0
	v_pk_mul_f32 v[2:3], v[2:3], v[6:7]
	s_nop 0
	v_cvt_pk_bf16_f32 v2, v2, v3
	v_add_f32_e32 v0, 1.0, v0
	v_rcp_f32_e32 v6, v0
	v_mul_f32_e32 v0, 0xbfb8aa3b, v17
	v_exp_f32_e32 v0, v0
	s_nop 0
	v_add_f32_e32 v0, 1.0, v0
	v_rcp_f32_e32 v7, v0
	s_nop 0
	v_pk_mul_f32 v[4:5], v[4:5], v[6:7]
	s_nop 0
	v_cvt_pk_bf16_f32 v3, v4, v5
	global_store_dwordx2 v[38:39], v[2:3], off offset:224

; #define LOAD_PARAMS() KParams kq_ = (KParams)__builtin_amdgcn_kernarg_segment_ptr(); asm volatile("" : "+s"(kq_)); const Params p = *kq_
; template <int CT>
; __global__ void __launch_bounds__(NTHREADS) mega_kernel(Params p) {
;     ...
; #pragma unroll 1
;   for (int ph = 0; ph < nph; ++ph) {
;     run_phase<CT>(ph);
;     if (ph + 1 < nph) {
;       LOAD_PARAMS();
;       xcd_barrier((unsigned*)(p.ws + WS<CT>::bar), x, nloc, nx, k);
;       ++k;
;     }
;   }
; }
.LBB0_726:
	s_endpgm
	s_nop 0
	s_nop 0
	s_nop 0
	s_nop 0
	s_endpgm
